# attention pair jobs: exponentials, row sums and bf16 packing of each key block streamed into the P V steps one block ahead of their use
# speedup vs baseline: 1.0022x; 1.0017x over previous
.Latt_noedge_1:
	s_nop 1
	v_max3_f32 v184, v0, v1, v2
	v_max3_f32 v184, v184, v3, v4
	v_max3_f32 v184, v184, v5, v6
	v_max3_f32 v184, v184, v7, v8
	v_max3_f32 v184, v184, v9, v10
	v_max3_f32 v184, v184, v11, v12
	v_max3_f32 v184, v184, v13, v14
	v_max3_f32 v184, v184, v15, v16
	v_max3_f32 v184, v184, v17, v18
	v_max3_f32 v184, v184, v19, v20
	v_max3_f32 v184, v184, v21, v22
	v_max3_f32 v184, v184, v23, v24
	v_max3_f32 v184, v184, v25, v26
	v_max3_f32 v184, v184, v27, v28
	v_max3_f32 v184, v184, v29, v30
	v_max3_f32 v184, v184, v31, v32
	v_max3_f32 v184, v184, v33, v34
	v_max_f32_e32 v184, v184, v35
	v_mov_b32_e32 v146, v184
	s_nop 1
	v_permlane16_swap_b32_e32 v184, v146
	v_max_f32_e32 v184, v184, v146
	v_mov_b32_e32 v146, v184
	s_nop 1
	v_permlane32_swap_b32_e32 v184, v146
	v_max_f32_e32 v184, v184, v146
	v_pk_add_f32 v[0:1], v[0:1], v[184:185] op_sel_hi:[1,0] neg_lo:[0,1] neg_hi:[0,1]
	v_pk_add_f32 v[2:3], v[2:3], v[184:185] op_sel_hi:[1,0] neg_lo:[0,1] neg_hi:[0,1]
	v_exp_f32_e32 v0, v0
	v_exp_f32_e32 v1, v1
	v_exp_f32_e32 v2, v2
	v_exp_f32_e32 v3, v3
	s_nop 0
	v_pk_add_f32 v[72:73], v[0:1], v[2:3]
	v_cvt_pk_bf16_f32 v0, v0, v1
	v_cvt_pk_bf16_f32 v1, v2, v3
	v_cndmask_b32_e64 v36, v36, v230, s[52:53]
	v_cndmask_b32_e64 v68, v68, v230, s[62:63]
	v_cndmask_b32_e64 v37, v37, v230, s[56:57]
	v_cndmask_b32_e64 v69, v69, v230, s[64:65]
	v_cndmask_b32_e64 v38, v38, v230, s[58:59]
	v_cndmask_b32_e64 v70, v70, v230, s[70:71]
	v_cndmask_b32_e64 v39, v39, v230, s[60:61]
	v_cndmask_b32_e64 v71, v71, v230, s[72:73]
	s_cmp_eq_u32 s96, 0
	s_cbranch_scc1 .Latt_noedge_2
	v_sub_u32_e32 v200, s77, v229
	v_add_u32_e32 v200, -16, v200
	s_sub_i32 s91, s78, s77
	v_sub_u32_e32 v150, 0, v200
	v_sub_u32_e32 v151, 1, v200
	v_sub_u32_e32 v152, 2, v200
	v_sub_u32_e32 v153, 3, v200
	v_cmp_lt_u32_e64 s[94:95], s91, v150
	v_cmp_lt_u32_e64 s[86:87], s91, v151
	v_cmp_lt_u32_e64 s[0:1], s91, v152
	v_cmp_lt_u32_e64 s[2:3], s91, v153
	v_cndmask_b32_e64 v36, v36, v230, s[94:95]
	v_cndmask_b32_e64 v37, v37, v230, s[86:87]
	v_cndmask_b32_e64 v38, v38, v230, s[0:1]
	v_cndmask_b32_e64 v39, v39, v230, s[2:3]
	v_sub_u32_e32 v150, 16, v200
	v_sub_u32_e32 v151, 17, v200
	v_sub_u32_e32 v152, 18, v200
	v_sub_u32_e32 v153, 19, v200
	v_cmp_lt_u32_e64 s[94:95], s91, v150
	v_cmp_lt_u32_e64 s[86:87], s91, v151
	v_cmp_lt_u32_e64 s[0:1], s91, v152
	v_cmp_lt_u32_e64 s[2:3], s91, v153
	v_cndmask_b32_e64 v40, v40, v230, s[94:95]
	v_cndmask_b32_e64 v41, v41, v230, s[86:87]
	v_cndmask_b32_e64 v42, v42, v230, s[0:1]
	v_cndmask_b32_e64 v43, v43, v230, s[2:3]
	v_sub_u32_e32 v150, 32, v200
	v_sub_u32_e32 v151, 33, v200
	v_sub_u32_e32 v152, 34, v200
	v_sub_u32_e32 v153, 35, v200
	v_cmp_lt_u32_e64 s[94:95], s91, v150
	v_cmp_lt_u32_e64 s[86:87], s91, v151
	v_cmp_lt_u32_e64 s[0:1], s91, v152
	v_cmp_lt_u32_e64 s[2:3], s91, v153
	v_cndmask_b32_e64 v44, v44, v230, s[94:95]
	v_cndmask_b32_e64 v45, v45, v230, s[86:87]
	v_cndmask_b32_e64 v46, v46, v230, s[0:1]
	v_cndmask_b32_e64 v47, v47, v230, s[2:3]
	v_sub_u32_e32 v150, 48, v200
	v_sub_u32_e32 v151, 49, v200
	v_sub_u32_e32 v152, 50, v200
	v_sub_u32_e32 v153, 51, v200
	v_cmp_lt_u32_e64 s[94:95], s91, v150
	v_cmp_lt_u32_e64 s[86:87], s91, v151
	v_cmp_lt_u32_e64 s[0:1], s91, v152
	v_cmp_lt_u32_e64 s[2:3], s91, v153
	v_cndmask_b32_e64 v48, v48, v230, s[94:95]
	v_cndmask_b32_e64 v49, v49, v230, s[86:87]
	v_cndmask_b32_e64 v50, v50, v230, s[0:1]
	v_cndmask_b32_e64 v51, v51, v230, s[2:3]
	v_sub_u32_e32 v150, 64, v200
	v_sub_u32_e32 v151, 0x41, v200
	v_sub_u32_e32 v152, 0x42, v200
	v_sub_u32_e32 v153, 0x43, v200
	v_cmp_lt_u32_e64 s[94:95], s91, v150
	v_cmp_lt_u32_e64 s[86:87], s91, v151
	v_cmp_lt_u32_e64 s[0:1], s91, v152
	v_cmp_lt_u32_e64 s[2:3], s91, v153
	v_cndmask_b32_e64 v52, v52, v230, s[94:95]
	v_cndmask_b32_e64 v53, v53, v230, s[86:87]
	v_cndmask_b32_e64 v54, v54, v230, s[0:1]
	v_cndmask_b32_e64 v55, v55, v230, s[2:3]
	v_sub_u32_e32 v150, 0x50, v200
	v_sub_u32_e32 v151, 0x51, v200
	v_sub_u32_e32 v152, 0x52, v200
	v_sub_u32_e32 v153, 0x53, v200
	v_cmp_lt_u32_e64 s[94:95], s91, v150
	v_cmp_lt_u32_e64 s[86:87], s91, v151
	v_cmp_lt_u32_e64 s[0:1], s91, v152
	v_cmp_lt_u32_e64 s[2:3], s91, v153
	v_cndmask_b32_e64 v56, v56, v230, s[94:95]
	v_cndmask_b32_e64 v57, v57, v230, s[86:87]
	v_cndmask_b32_e64 v58, v58, v230, s[0:1]
	v_cndmask_b32_e64 v59, v59, v230, s[2:3]
	v_sub_u32_e32 v150, 0x60, v200
	v_sub_u32_e32 v151, 0x61, v200
	v_sub_u32_e32 v152, 0x62, v200
	v_sub_u32_e32 v153, 0x63, v200
	v_cmp_lt_u32_e64 s[94:95], s91, v150
	v_cmp_lt_u32_e64 s[86:87], s91, v151
	v_cmp_lt_u32_e64 s[0:1], s91, v152
	v_cmp_lt_u32_e64 s[2:3], s91, v153
	v_cndmask_b32_e64 v60, v60, v230, s[94:95]
	v_cndmask_b32_e64 v61, v61, v230, s[86:87]
	v_cndmask_b32_e64 v62, v62, v230, s[0:1]
	v_cndmask_b32_e64 v63, v63, v230, s[2:3]
	v_sub_u32_e32 v150, 0x70, v200
	v_sub_u32_e32 v151, 0x71, v200
	v_sub_u32_e32 v152, 0x72, v200
	v_sub_u32_e32 v153, 0x73, v200
	v_cmp_lt_u32_e64 s[94:95], s91, v150
	v_cmp_lt_u32_e64 s[86:87], s91, v151
	v_cmp_lt_u32_e64 s[0:1], s91, v152
	v_cmp_lt_u32_e64 s[2:3], s91, v153
	v_cndmask_b32_e64 v64, v64, v230, s[94:95]
	v_cndmask_b32_e64 v65, v65, v230, s[86:87]
	v_cndmask_b32_e64 v66, v66, v230, s[0:1]
	v_cndmask_b32_e64 v67, v67, v230, s[2:3]
	v_sub_u32_e32 v150, 0x80, v200
	v_sub_u32_e32 v151, 0x81, v200
	v_sub_u32_e32 v152, 0x82, v200
	v_sub_u32_e32 v153, 0x83, v200
	v_cmp_lt_u32_e64 s[94:95], s91, v150
	v_cmp_lt_u32_e64 s[86:87], s91, v151
	v_cmp_lt_u32_e64 s[0:1], s91, v152
	v_cmp_lt_u32_e64 s[2:3], s91, v153
	v_cndmask_b32_e64 v68, v68, v230, s[94:95]
	v_cndmask_b32_e64 v69, v69, v230, s[86:87]
	v_cndmask_b32_e64 v70, v70, v230, s[0:1]
	v_cndmask_b32_e64 v71, v71, v230, s[2:3]
.Latt_noedge_2:
	s_nop 1
	v_max3_f32 v186, v36, v37, v38
	v_max3_f32 v186, v186, v39, v40
	v_max3_f32 v186, v186, v41, v42
	v_max3_f32 v186, v186, v43, v44
	v_max3_f32 v186, v186, v45, v46
	v_max3_f32 v186, v186, v47, v48
	v_max3_f32 v186, v186, v49, v50
	v_max3_f32 v186, v186, v51, v52
	v_max3_f32 v186, v186, v53, v54
	v_max3_f32 v186, v186, v55, v56
	v_max3_f32 v186, v186, v57, v58
	v_max3_f32 v186, v186, v59, v60
	v_max3_f32 v186, v186, v61, v62
	v_max3_f32 v186, v186, v63, v64
	v_max3_f32 v186, v186, v65, v66
	v_max3_f32 v186, v186, v67, v68
	v_max3_f32 v186, v186, v69, v70
	v_max_f32_e32 v186, v186, v71
	v_mov_b32_e32 v146, v186
	s_nop 1
	v_permlane16_swap_b32_e32 v186, v146
	v_max_f32_e32 v186, v186, v146
	v_mov_b32_e32 v146, v186
	s_nop 1
	v_permlane32_swap_b32_e32 v186, v146
	v_max_f32_e32 v186, v186, v146
	s_waitcnt lgkmcnt(0)
	s_add_i32 s93, s76, 16
	s_mov_b32 m0, s14
	v_add_u32_e32 v164, s93, v231
	v_med3_i32 v164, v164, 0, s40
	v_lshl_or_b32 v164, v164, 7, v222
	global_load_lds_dwordx4 v164, s[24:25]
	s_add_i32 m0, s14, 0x400
	v_add_u32_e32 v165, s93, v232
	v_med3_i32 v165, v165, 0, s40
	v_lshl_or_b32 v165, v165, 7, v222
	global_load_lds_dwordx4 v165, s[24:25]
	s_waitcnt vmcnt(8)
	v_add_u32_e32 v154, s15, v225
	v_add_u32_e32 v155, s15, v226
	v_add_u32_e32 v156, s15, v227
	v_add_u32_e32 v157, s15, v228
	ds_read_b64_tr_b16 v[202:203], v154
	ds_read_b64_tr_b16 v[204:205], v155
	ds_read_b64_tr_b16 v[206:207], v156
	ds_read_b64_tr_b16 v[208:209], v157
	v_mfma_f32_16x16x16_bf16 v[96:99], v[88:89], v[0:1], 0
	v_mfma_f32_16x16x16_bf16 v[100:103], v[90:91], v[0:1], 0
	v_mfma_f32_16x16x16_bf16 v[104:107], v[92:93], v[0:1], 0
	v_mfma_f32_16x16x16_bf16 v[108:111], v[94:95], v[0:1], 0
	v_pk_add_f32 v[4:5], v[4:5], v[184:185] op_sel_hi:[1,0] neg_lo:[0,1] neg_hi:[0,1]
	v_pk_add_f32 v[6:7], v[6:7], v[184:185] op_sel_hi:[1,0] neg_lo:[0,1] neg_hi:[0,1]
	v_exp_f32_e32 v4, v4
	v_exp_f32_e32 v5, v5
	v_exp_f32_e32 v6, v6
	v_exp_f32_e32 v7, v7
	s_nop 0
	v_pk_add_f32 v[74:75], v[4:5], v[6:7]
	v_cvt_pk_bf16_f32 v4, v4, v5
	v_cvt_pk_bf16_f32 v5, v6, v7
	v_pk_add_f32 v[36:37], v[36:37], v[186:187] op_sel_hi:[1,0] neg_lo:[0,1] neg_hi:[0,1]
	v_pk_add_f32 v[38:39], v[38:39], v[186:187] op_sel_hi:[1,0] neg_lo:[0,1] neg_hi:[0,1]
	v_exp_f32_e32 v36, v36
	v_exp_f32_e32 v37, v37
	v_exp_f32_e32 v38, v38
	v_exp_f32_e32 v39, v39
	s_nop 0
	v_pk_add_f32 v[76:77], v[36:37], v[38:39]
	v_cvt_pk_bf16_f32 v36, v36, v37
	v_cvt_pk_bf16_f32 v37, v38, v39
	s_waitcnt lgkmcnt(0)
	s_add_i32 s93, s76, 32
	s_mov_b32 m0, s15
	v_add_u32_e32 v164, s93, v231
	v_med3_i32 v164, v164, 0, s40
	v_lshl_or_b32 v164, v164, 7, v222
	global_load_lds_dwordx4 v164, s[24:25]
	s_add_i32 m0, s15, 0x400
	v_add_u32_e32 v165, s93, v232
	v_med3_i32 v165, v165, 0, s40
	v_lshl_or_b32 v165, v165, 7, v222
	global_load_lds_dwordx4 v165, s[24:25]
	s_waitcnt vmcnt(8)
	v_add_u32_e32 v154, s16, v225
	v_add_u32_e32 v155, s16, v226
	v_add_u32_e32 v156, s16, v227
	v_add_u32_e32 v157, s16, v228
	ds_read_b64_tr_b16 v[88:89], v154
	ds_read_b64_tr_b16 v[90:91], v155
	ds_read_b64_tr_b16 v[92:93], v156
	ds_read_b64_tr_b16 v[94:95], v157
	v_mfma_f32_16x16x16_bf16 v[96:99], v[202:203], v[4:5], v[96:99]
	v_mfma_f32_16x16x16_bf16 v[112:115], v[202:203], v[36:37], 0
	v_mfma_f32_16x16x16_bf16 v[100:103], v[204:205], v[4:5], v[100:103]
	v_mfma_f32_16x16x16_bf16 v[116:119], v[204:205], v[36:37], 0
	v_mfma_f32_16x16x16_bf16 v[104:107], v[206:207], v[4:5], v[104:107]
	v_mfma_f32_16x16x16_bf16 v[120:123], v[206:207], v[36:37], 0
	v_mfma_f32_16x16x16_bf16 v[108:111], v[208:209], v[4:5], v[108:111]
	v_mfma_f32_16x16x16_bf16 v[124:127], v[208:209], v[36:37], 0
	v_pk_add_f32 v[8:9], v[8:9], v[184:185] op_sel_hi:[1,0] neg_lo:[0,1] neg_hi:[0,1]
	v_pk_add_f32 v[10:11], v[10:11], v[184:185] op_sel_hi:[1,0] neg_lo:[0,1] neg_hi:[0,1]
	v_exp_f32_e32 v8, v8
	v_exp_f32_e32 v9, v9
	v_exp_f32_e32 v10, v10
	v_exp_f32_e32 v11, v11
	s_nop 0
	v_pk_add_f32 v[72:73], v[72:73], v[8:9]
	v_pk_add_f32 v[74:75], v[74:75], v[10:11]
	v_cvt_pk_bf16_f32 v8, v8, v9
	v_cvt_pk_bf16_f32 v9, v10, v11
	v_pk_add_f32 v[40:41], v[40:41], v[186:187] op_sel_hi:[1,0] neg_lo:[0,1] neg_hi:[0,1]
	v_pk_add_f32 v[42:43], v[42:43], v[186:187] op_sel_hi:[1,0] neg_lo:[0,1] neg_hi:[0,1]
	v_exp_f32_e32 v40, v40
	v_exp_f32_e32 v41, v41
	v_exp_f32_e32 v42, v42
	v_exp_f32_e32 v43, v43
	s_nop 0
	v_pk_add_f32 v[78:79], v[40:41], v[42:43]
	v_cvt_pk_bf16_f32 v40, v40, v41
	v_cvt_pk_bf16_f32 v41, v42, v43
	s_waitcnt lgkmcnt(0)
	s_add_i32 s93, s76, 48
	s_mov_b32 m0, s16
	v_add_u32_e32 v164, s93, v231
	v_med3_i32 v164, v164, 0, s40
	v_lshl_or_b32 v164, v164, 7, v222
	global_load_lds_dwordx4 v164, s[24:25]
	s_add_i32 m0, s16, 0x400
	v_add_u32_e32 v165, s93, v232
	v_med3_i32 v165, v165, 0, s40
	v_lshl_or_b32 v165, v165, 7, v222
	global_load_lds_dwordx4 v165, s[24:25]
	s_waitcnt vmcnt(8)
	v_add_u32_e32 v154, s12, v225
	v_add_u32_e32 v155, s12, v226
	v_add_u32_e32 v156, s12, v227
	v_add_u32_e32 v157, s12, v228
	ds_read_b64_tr_b16 v[202:203], v154
	ds_read_b64_tr_b16 v[204:205], v155
	ds_read_b64_tr_b16 v[206:207], v156
	ds_read_b64_tr_b16 v[208:209], v157
	v_mfma_f32_16x16x16_bf16 v[96:99], v[88:89], v[8:9], v[96:99]
	v_mfma_f32_16x16x16_bf16 v[112:115], v[88:89], v[40:41], v[112:115]
	v_mfma_f32_16x16x16_bf16 v[100:103], v[90:91], v[8:9], v[100:103]
	v_mfma_f32_16x16x16_bf16 v[116:119], v[90:91], v[40:41], v[116:119]
	v_mfma_f32_16x16x16_bf16 v[104:107], v[92:93], v[8:9], v[104:107]
	v_mfma_f32_16x16x16_bf16 v[120:123], v[92:93], v[40:41], v[120:123]
	v_mfma_f32_16x16x16_bf16 v[108:111], v[94:95], v[8:9], v[108:111]
	v_mfma_f32_16x16x16_bf16 v[124:127], v[94:95], v[40:41], v[124:127]
	v_pk_add_f32 v[12:13], v[12:13], v[184:185] op_sel_hi:[1,0] neg_lo:[0,1] neg_hi:[0,1]
	v_pk_add_f32 v[14:15], v[14:15], v[184:185] op_sel_hi:[1,0] neg_lo:[0,1] neg_hi:[0,1]
	v_exp_f32_e32 v12, v12
	v_exp_f32_e32 v13, v13
	v_exp_f32_e32 v14, v14
	v_exp_f32_e32 v15, v15
	s_nop 0
	v_pk_add_f32 v[72:73], v[72:73], v[12:13]
	v_pk_add_f32 v[74:75], v[74:75], v[14:15]
	v_cvt_pk_bf16_f32 v12, v12, v13
	v_cvt_pk_bf16_f32 v13, v14, v15
	v_pk_add_f32 v[44:45], v[44:45], v[186:187] op_sel_hi:[1,0] neg_lo:[0,1] neg_hi:[0,1]
	v_pk_add_f32 v[46:47], v[46:47], v[186:187] op_sel_hi:[1,0] neg_lo:[0,1] neg_hi:[0,1]
	v_exp_f32_e32 v44, v44
	v_exp_f32_e32 v45, v45
	v_exp_f32_e32 v46, v46
	v_exp_f32_e32 v47, v47
	s_nop 0
	v_pk_add_f32 v[76:77], v[76:77], v[44:45]
	v_pk_add_f32 v[78:79], v[78:79], v[46:47]
	v_cvt_pk_bf16_f32 v44, v44, v45
	v_cvt_pk_bf16_f32 v45, v46, v47
	s_waitcnt lgkmcnt(0)
	s_add_i32 s93, s76, 64
	s_mov_b32 m0, s12
	v_add_u32_e32 v164, s93, v231
	v_med3_i32 v164, v164, 0, s40
	v_lshl_or_b32 v164, v164, 7, v222
	global_load_lds_dwordx4 v164, s[24:25]
	s_add_i32 m0, s12, 0x400
	v_add_u32_e32 v165, s93, v232
	v_med3_i32 v165, v165, 0, s40
	v_lshl_or_b32 v165, v165, 7, v222
	global_load_lds_dwordx4 v165, s[24:25]
	s_waitcnt vmcnt(8)
	v_add_u32_e32 v154, s13, v225
	v_add_u32_e32 v155, s13, v226
	v_add_u32_e32 v156, s13, v227
	v_add_u32_e32 v157, s13, v228
	ds_read_b64_tr_b16 v[88:89], v154
	ds_read_b64_tr_b16 v[90:91], v155
	ds_read_b64_tr_b16 v[92:93], v156
	ds_read_b64_tr_b16 v[94:95], v157
	v_mfma_f32_16x16x16_bf16 v[96:99], v[202:203], v[12:13], v[96:99]
	v_mfma_f32_16x16x16_bf16 v[112:115], v[202:203], v[44:45], v[112:115]
	v_mfma_f32_16x16x16_bf16 v[100:103], v[204:205], v[12:13], v[100:103]
	v_mfma_f32_16x16x16_bf16 v[116:119], v[204:205], v[44:45], v[116:119]
	v_mfma_f32_16x16x16_bf16 v[104:107], v[206:207], v[12:13], v[104:107]
	v_mfma_f32_16x16x16_bf16 v[120:123], v[206:207], v[44:45], v[120:123]
	v_mfma_f32_16x16x16_bf16 v[108:111], v[208:209], v[12:13], v[108:111]
	v_mfma_f32_16x16x16_bf16 v[124:127], v[208:209], v[44:45], v[124:127]
	v_pk_add_f32 v[16:17], v[16:17], v[184:185] op_sel_hi:[1,0] neg_lo:[0,1] neg_hi:[0,1]
	v_pk_add_f32 v[18:19], v[18:19], v[184:185] op_sel_hi:[1,0] neg_lo:[0,1] neg_hi:[0,1]
	v_exp_f32_e32 v16, v16
	v_exp_f32_e32 v17, v17
	v_exp_f32_e32 v18, v18
	v_exp_f32_e32 v19, v19
	s_nop 0
	v_pk_add_f32 v[72:73], v[72:73], v[16:17]
	v_pk_add_f32 v[74:75], v[74:75], v[18:19]
	v_cvt_pk_bf16_f32 v16, v16, v17
	v_cvt_pk_bf16_f32 v17, v18, v19
	v_pk_add_f32 v[48:49], v[48:49], v[186:187] op_sel_hi:[1,0] neg_lo:[0,1] neg_hi:[0,1]
	v_pk_add_f32 v[50:51], v[50:51], v[186:187] op_sel_hi:[1,0] neg_lo:[0,1] neg_hi:[0,1]
	v_exp_f32_e32 v48, v48
	v_exp_f32_e32 v49, v49
	v_exp_f32_e32 v50, v50
	v_exp_f32_e32 v51, v51
	s_nop 0
	v_pk_add_f32 v[76:77], v[76:77], v[48:49]
	v_pk_add_f32 v[78:79], v[78:79], v[50:51]
	v_cvt_pk_bf16_f32 v48, v48, v49
	v_cvt_pk_bf16_f32 v49, v50, v51
	s_waitcnt lgkmcnt(0)
	s_add_i32 s93, s76, 0x50
	s_mov_b32 m0, s13
	v_add_u32_e32 v164, s93, v231
	v_med3_i32 v164, v164, 0, s40
	v_lshl_or_b32 v164, v164, 7, v222
	global_load_lds_dwordx4 v164, s[24:25]
	s_add_i32 m0, s13, 0x400
	v_add_u32_e32 v165, s93, v232
	v_med3_i32 v165, v165, 0, s40
	v_lshl_or_b32 v165, v165, 7, v222
	global_load_lds_dwordx4 v165, s[24:25]
	s_waitcnt vmcnt(8)
	v_add_u32_e32 v154, s14, v225
	v_add_u32_e32 v155, s14, v226
	v_add_u32_e32 v156, s14, v227
	v_add_u32_e32 v157, s14, v228
	ds_read_b64_tr_b16 v[202:203], v154
	ds_read_b64_tr_b16 v[204:205], v155
	ds_read_b64_tr_b16 v[206:207], v156
	ds_read_b64_tr_b16 v[208:209], v157
	v_mfma_f32_16x16x16_bf16 v[96:99], v[88:89], v[16:17], v[96:99]
	v_mfma_f32_16x16x16_bf16 v[112:115], v[88:89], v[48:49], v[112:115]
	v_mfma_f32_16x16x16_bf16 v[100:103], v[90:91], v[16:17], v[100:103]
	v_mfma_f32_16x16x16_bf16 v[116:119], v[90:91], v[48:49], v[116:119]
	v_mfma_f32_16x16x16_bf16 v[104:107], v[92:93], v[16:17], v[104:107]
	v_mfma_f32_16x16x16_bf16 v[120:123], v[92:93], v[48:49], v[120:123]
	v_mfma_f32_16x16x16_bf16 v[108:111], v[94:95], v[16:17], v[108:111]
	v_mfma_f32_16x16x16_bf16 v[124:127], v[94:95], v[48:49], v[124:127]
	v_pk_add_f32 v[20:21], v[20:21], v[184:185] op_sel_hi:[1,0] neg_lo:[0,1] neg_hi:[0,1]
	v_pk_add_f32 v[22:23], v[22:23], v[184:185] op_sel_hi:[1,0] neg_lo:[0,1] neg_hi:[0,1]
	v_exp_f32_e32 v20, v20
	v_exp_f32_e32 v21, v21
	v_exp_f32_e32 v22, v22
	v_exp_f32_e32 v23, v23
	s_nop 0
	v_pk_add_f32 v[72:73], v[72:73], v[20:21]
	v_pk_add_f32 v[74:75], v[74:75], v[22:23]
	v_cvt_pk_bf16_f32 v20, v20, v21
	v_cvt_pk_bf16_f32 v21, v22, v23
	v_pk_add_f32 v[52:53], v[52:53], v[186:187] op_sel_hi:[1,0] neg_lo:[0,1] neg_hi:[0,1]
	v_pk_add_f32 v[54:55], v[54:55], v[186:187] op_sel_hi:[1,0] neg_lo:[0,1] neg_hi:[0,1]
	v_exp_f32_e32 v52, v52
	v_exp_f32_e32 v53, v53
	v_exp_f32_e32 v54, v54
	v_exp_f32_e32 v55, v55
	s_nop 0
	v_pk_add_f32 v[76:77], v[76:77], v[52:53]
	v_pk_add_f32 v[78:79], v[78:79], v[54:55]
	v_cvt_pk_bf16_f32 v52, v52, v53
	v_cvt_pk_bf16_f32 v53, v54, v55
	s_waitcnt lgkmcnt(0)
	s_add_i32 s93, s79, 0
	s_mov_b32 m0, s14
	v_add_u32_e32 v164, s93, v162
	v_lshl_or_b32 v164, v164, 7, v220
	global_load_lds_dwordx4 v164, s[18:19]
	s_add_i32 m0, s14, 0x400
	v_add_u32_e32 v165, s93, v163
	v_lshl_or_b32 v165, v165, 7, v221
	global_load_lds_dwordx4 v165, s[18:19]
	s_waitcnt vmcnt(8)
	v_add_u32_e32 v154, s15, v225
	v_add_u32_e32 v155, s15, v226
	v_add_u32_e32 v156, s15, v227
	v_add_u32_e32 v157, s15, v228
	ds_read_b64_tr_b16 v[88:89], v154
	ds_read_b64_tr_b16 v[90:91], v155
	ds_read_b64_tr_b16 v[92:93], v156
	ds_read_b64_tr_b16 v[94:95], v157
	v_mfma_f32_16x16x16_bf16 v[96:99], v[202:203], v[20:21], v[96:99]
	v_mfma_f32_16x16x16_bf16 v[112:115], v[202:203], v[52:53], v[112:115]
	v_mfma_f32_16x16x16_bf16 v[100:103], v[204:205], v[20:21], v[100:103]
	v_mfma_f32_16x16x16_bf16 v[116:119], v[204:205], v[52:53], v[116:119]
	v_mfma_f32_16x16x16_bf16 v[104:107], v[206:207], v[20:21], v[104:107]
	v_mfma_f32_16x16x16_bf16 v[120:123], v[206:207], v[52:53], v[120:123]
	v_mfma_f32_16x16x16_bf16 v[108:111], v[208:209], v[20:21], v[108:111]
	v_mfma_f32_16x16x16_bf16 v[124:127], v[208:209], v[52:53], v[124:127]
	v_pk_add_f32 v[24:25], v[24:25], v[184:185] op_sel_hi:[1,0] neg_lo:[0,1] neg_hi:[0,1]
	v_pk_add_f32 v[26:27], v[26:27], v[184:185] op_sel_hi:[1,0] neg_lo:[0,1] neg_hi:[0,1]
	v_exp_f32_e32 v24, v24
	v_exp_f32_e32 v25, v25
	v_exp_f32_e32 v26, v26
	v_exp_f32_e32 v27, v27
	s_nop 0
	v_pk_add_f32 v[72:73], v[72:73], v[24:25]
	v_pk_add_f32 v[74:75], v[74:75], v[26:27]
	v_cvt_pk_bf16_f32 v24, v24, v25
	v_cvt_pk_bf16_f32 v25, v26, v27
	v_pk_add_f32 v[56:57], v[56:57], v[186:187] op_sel_hi:[1,0] neg_lo:[0,1] neg_hi:[0,1]
	v_pk_add_f32 v[58:59], v[58:59], v[186:187] op_sel_hi:[1,0] neg_lo:[0,1] neg_hi:[0,1]
	v_exp_f32_e32 v56, v56
	v_exp_f32_e32 v57, v57
	v_exp_f32_e32 v58, v58
	v_exp_f32_e32 v59, v59
	s_nop 0
	v_pk_add_f32 v[76:77], v[76:77], v[56:57]
	v_pk_add_f32 v[78:79], v[78:79], v[58:59]
	v_cvt_pk_bf16_f32 v56, v56, v57
	v_cvt_pk_bf16_f32 v57, v58, v59
	s_waitcnt lgkmcnt(0)
	s_add_i32 s93, s79, 64
	s_mov_b32 m0, s15
	v_add_u32_e32 v164, s93, v162
	v_lshl_or_b32 v164, v164, 7, v220
	global_load_lds_dwordx4 v164, s[18:19]
	s_add_i32 m0, s15, 0x400
	v_add_u32_e32 v165, s93, v163
	v_lshl_or_b32 v165, v165, 7, v221
	global_load_lds_dwordx4 v165, s[18:19]
	s_waitcnt vmcnt(8)
	v_add_u32_e32 v154, s16, v225
	v_add_u32_e32 v155, s16, v226
	v_add_u32_e32 v156, s16, v227
	v_add_u32_e32 v157, s16, v228
	ds_read_b64_tr_b16 v[202:203], v154
	ds_read_b64_tr_b16 v[204:205], v155
	ds_read_b64_tr_b16 v[206:207], v156
	ds_read_b64_tr_b16 v[208:209], v157
	v_mfma_f32_16x16x16_bf16 v[96:99], v[88:89], v[24:25], v[96:99]
	v_mfma_f32_16x16x16_bf16 v[112:115], v[88:89], v[56:57], v[112:115]
	v_mfma_f32_16x16x16_bf16 v[100:103], v[90:91], v[24:25], v[100:103]
	v_mfma_f32_16x16x16_bf16 v[116:119], v[90:91], v[56:57], v[116:119]
	v_mfma_f32_16x16x16_bf16 v[104:107], v[92:93], v[24:25], v[104:107]
	v_mfma_f32_16x16x16_bf16 v[120:123], v[92:93], v[56:57], v[120:123]
	v_mfma_f32_16x16x16_bf16 v[108:111], v[94:95], v[24:25], v[108:111]
	v_mfma_f32_16x16x16_bf16 v[124:127], v[94:95], v[56:57], v[124:127]
	v_pk_add_f32 v[28:29], v[28:29], v[184:185] op_sel_hi:[1,0] neg_lo:[0,1] neg_hi:[0,1]
	v_pk_add_f32 v[30:31], v[30:31], v[184:185] op_sel_hi:[1,0] neg_lo:[0,1] neg_hi:[0,1]
	v_exp_f32_e32 v28, v28
	v_exp_f32_e32 v29, v29
	v_exp_f32_e32 v30, v30
	v_exp_f32_e32 v31, v31
	s_nop 0
	v_pk_add_f32 v[72:73], v[72:73], v[28:29]
	v_pk_add_f32 v[74:75], v[74:75], v[30:31]
	v_cvt_pk_bf16_f32 v28, v28, v29
	v_cvt_pk_bf16_f32 v29, v30, v31
	v_pk_add_f32 v[60:61], v[60:61], v[186:187] op_sel_hi:[1,0] neg_lo:[0,1] neg_hi:[0,1]
	v_pk_add_f32 v[62:63], v[62:63], v[186:187] op_sel_hi:[1,0] neg_lo:[0,1] neg_hi:[0,1]
	v_exp_f32_e32 v60, v60
	v_exp_f32_e32 v61, v61
	v_exp_f32_e32 v62, v62
	v_exp_f32_e32 v63, v63
	s_nop 0
	v_pk_add_f32 v[76:77], v[76:77], v[60:61]
	v_pk_add_f32 v[78:79], v[78:79], v[62:63]
	v_cvt_pk_bf16_f32 v60, v60, v61
	v_cvt_pk_bf16_f32 v61, v62, v63
	s_waitcnt lgkmcnt(0)
	s_add_i32 s93, s79, 0xffffff00
	s_mov_b32 m0, s16
	v_add_u32_e32 v164, s93, v162
	v_med3_i32 v164, v164, 0, s40
	v_lshl_or_b32 v164, v164, 7, v220
	global_load_lds_dwordx4 v164, s[20:21]
	s_add_i32 m0, s16, 0x400
	v_add_u32_e32 v165, s93, v163
	v_med3_i32 v165, v165, 0, s40
	v_lshl_or_b32 v165, v165, 7, v221
	global_load_lds_dwordx4 v165, s[20:21]
	s_waitcnt vmcnt(8)
	v_add_u32_e32 v154, s12, v225
	v_add_u32_e32 v155, s12, v226
	v_add_u32_e32 v156, s12, v227
	v_add_u32_e32 v157, s12, v228
	ds_read_b64_tr_b16 v[88:89], v154
	ds_read_b64_tr_b16 v[90:91], v155
	ds_read_b64_tr_b16 v[92:93], v156
	ds_read_b64_tr_b16 v[94:95], v157
	v_mfma_f32_16x16x16_bf16 v[96:99], v[202:203], v[28:29], v[96:99]
	v_mfma_f32_16x16x16_bf16 v[112:115], v[202:203], v[60:61], v[112:115]
	v_mfma_f32_16x16x16_bf16 v[100:103], v[204:205], v[28:29], v[100:103]
	v_mfma_f32_16x16x16_bf16 v[116:119], v[204:205], v[60:61], v[116:119]
	v_mfma_f32_16x16x16_bf16 v[104:107], v[206:207], v[28:29], v[104:107]
	v_mfma_f32_16x16x16_bf16 v[120:123], v[206:207], v[60:61], v[120:123]
	v_mfma_f32_16x16x16_bf16 v[108:111], v[208:209], v[28:29], v[108:111]
	v_mfma_f32_16x16x16_bf16 v[124:127], v[208:209], v[60:61], v[124:127]
	v_pk_add_f32 v[32:33], v[32:33], v[184:185] op_sel_hi:[1,0] neg_lo:[0,1] neg_hi:[0,1]
	v_pk_add_f32 v[34:35], v[34:35], v[184:185] op_sel_hi:[1,0] neg_lo:[0,1] neg_hi:[0,1]
	v_exp_f32_e32 v32, v32
	v_exp_f32_e32 v33, v33
	v_exp_f32_e32 v34, v34
	v_exp_f32_e32 v35, v35
	s_nop 0
	v_pk_add_f32 v[72:73], v[72:73], v[32:33]
	v_pk_add_f32 v[74:75], v[74:75], v[34:35]
	v_cvt_pk_bf16_f32 v32, v32, v33
	v_cvt_pk_bf16_f32 v33, v34, v35
	v_pk_add_f32 v[64:65], v[64:65], v[186:187] op_sel_hi:[1,0] neg_lo:[0,1] neg_hi:[0,1]
	v_pk_add_f32 v[66:67], v[66:67], v[186:187] op_sel_hi:[1,0] neg_lo:[0,1] neg_hi:[0,1]
	v_exp_f32_e32 v64, v64
	v_exp_f32_e32 v65, v65
	v_exp_f32_e32 v66, v66
	v_exp_f32_e32 v67, v67
	s_nop 0
	v_pk_add_f32 v[76:77], v[76:77], v[64:65]
	v_pk_add_f32 v[78:79], v[78:79], v[66:67]
	v_cvt_pk_bf16_f32 v64, v64, v65
	v_cvt_pk_bf16_f32 v65, v66, v67
	s_waitcnt lgkmcnt(0)
	s_add_i32 s93, s79, 0xffffff40
	s_mov_b32 m0, s12
	v_add_u32_e32 v164, s93, v162
	v_med3_i32 v164, v164, 0, s40
	v_lshl_or_b32 v164, v164, 7, v220
	global_load_lds_dwordx4 v164, s[20:21]
	s_add_i32 m0, s12, 0x400
	v_add_u32_e32 v165, s93, v163
	v_med3_i32 v165, v165, 0, s40
	v_lshl_or_b32 v165, v165, 7, v221
	global_load_lds_dwordx4 v165, s[20:21]
	s_waitcnt vmcnt(8)
	v_add_u32_e32 v154, s13, v225
	v_add_u32_e32 v155, s13, v226
	v_add_u32_e32 v156, s13, v227
	v_add_u32_e32 v157, s13, v228
	ds_read_b64_tr_b16 v[202:203], v154
	ds_read_b64_tr_b16 v[204:205], v155
	ds_read_b64_tr_b16 v[206:207], v156
	ds_read_b64_tr_b16 v[208:209], v157
	v_mfma_f32_16x16x16_bf16 v[96:99], v[88:89], v[32:33], v[96:99]
	v_mfma_f32_16x16x16_bf16 v[112:115], v[88:89], v[64:65], v[112:115]
	v_mfma_f32_16x16x16_bf16 v[100:103], v[90:91], v[32:33], v[100:103]
	v_mfma_f32_16x16x16_bf16 v[116:119], v[90:91], v[64:65], v[116:119]
	v_mfma_f32_16x16x16_bf16 v[104:107], v[92:93], v[32:33], v[104:107]
	v_mfma_f32_16x16x16_bf16 v[120:123], v[92:93], v[64:65], v[120:123]
	v_mfma_f32_16x16x16_bf16 v[108:111], v[94:95], v[32:33], v[108:111]
	v_mfma_f32_16x16x16_bf16 v[124:127], v[94:95], v[64:65], v[124:127]
	v_pk_add_f32 v[68:69], v[68:69], v[186:187] op_sel_hi:[1,0] neg_lo:[0,1] neg_hi:[0,1]
	v_pk_add_f32 v[70:71], v[70:71], v[186:187] op_sel_hi:[1,0] neg_lo:[0,1] neg_hi:[0,1]
	v_exp_f32_e32 v68, v68
	v_exp_f32_e32 v69, v69
	v_exp_f32_e32 v70, v70
	v_exp_f32_e32 v71, v71
	s_nop 0
	v_pk_add_f32 v[76:77], v[76:77], v[68:69]
	v_pk_add_f32 v[78:79], v[78:79], v[70:71]
	v_cvt_pk_bf16_f32 v68, v68, v69
	v_cvt_pk_bf16_f32 v69, v70, v71
	s_nop 0
	v_pk_add_f32 v[72:73], v[72:73], v[74:75]
	s_nop 0
	v_add_f32_e32 v185, v72, v73
	v_mov_b32_e32 v146, v185
	s_nop 1
	v_permlane16_swap_b32_e32 v185, v146
	v_add_f32_e32 v185, v185, v146
	v_mov_b32_e32 v146, v185
	s_nop 1
	v_permlane32_swap_b32_e32 v185, v146
	v_add_f32_e32 v185, v185, v146
	s_waitcnt lgkmcnt(0)
	s_add_i32 s93, s79, 0xffffff80
	s_mov_b32 m0, s13
	v_add_u32_e32 v164, s93, v162
	v_med3_i32 v164, v164, 0, s40
	v_lshl_or_b32 v164, v164, 7, v220
	global_load_lds_dwordx4 v164, s[20:21]
	s_add_i32 m0, s13, 0x400
	v_add_u32_e32 v165, s93, v163
	v_med3_i32 v165, v165, 0, s40
	v_lshl_or_b32 v165, v165, 7, v221
	global_load_lds_dwordx4 v165, s[20:21]
	v_mfma_f32_16x16x16_bf16 v[112:115], v[202:203], v[68:69], v[112:115]
	v_mfma_f32_16x16x16_bf16 v[116:119], v[204:205], v[68:69], v[116:119]
	v_mfma_f32_16x16x16_bf16 v[120:123], v[206:207], v[68:69], v[120:123]
	v_mfma_f32_16x16x16_bf16 v[124:127], v[208:209], v[68:69], v[124:127]
	s_nop 0
	v_pk_add_f32 v[76:77], v[76:77], v[78:79]
	s_nop 0
	v_add_f32_e32 v187, v76, v77
	v_mov_b32_e32 v146, v187
	s_nop 1
	v_permlane16_swap_b32_e32 v187, v146
	v_add_f32_e32 v187, v187, v146
	v_mov_b32_e32 v146, v187
	s_nop 1
	v_permlane32_swap_b32_e32 v187, v146
	v_add_f32_e32 v187, v187, v146
	s_and_saveexec_b64 s[80:81], s[74:75]
	ds_write_b64 v194, v[184:185]
	s_mov_b64 exec, s[80:81]
	ds_write_b128 v190, v[96:99]
	ds_write_b128 v191, v[100:103]
	ds_write_b128 v192, v[104:107]
	ds_write_b128 v193, v[108:111]
	s_and_saveexec_b64 s[80:81], s[74:75]
	ds_write_b64 v199, v[186:187]
	s_mov_b64 exec, s[80:81]
	ds_write_b128 v195, v[112:115]
	ds_write_b128 v196, v[116:119]
	ds_write_b128 v197, v[120:123]
	ds_write_b128 v198, v[124:127]
	s_waitcnt lgkmcnt(0)
	s_barrier
	s_add_i32 s76, s38, s83
	s_add_i32 s79, s38, s84
	v_lshlrev_b32_e32 v231, 2, v218
	v_add_u32_e32 v232, 8, v218
	v_lshlrev_b32_e32 v232, 2, v232
	v_lshlrev_b32_e32 v162, 4, v218
	v_add_u32_e32 v163, 8, v218
	v_lshlrev_b32_e32 v163, 4, v163
	s_waitcnt vmcnt(8)
	v_add_u32_e32 v154, s14, v223
	v_add_u32_e32 v155, s14, v224
	ds_read_b128 v[72:75], v154
	ds_read_b128 v[76:79], v155
	s_waitcnt lgkmcnt(0)
	s_add_i32 s93, s76, 0xffffffc0
	s_mov_b32 m0, s14
	v_add_u32_e32 v164, s93, v231
	v_med3_i32 v164, v164, 0, s40
	v_lshl_or_b32 v164, v164, 7, v220
	global_load_lds_dwordx4 v164, s[20:21]
	s_add_i32 m0, s14, 0x400
	v_add_u32_e32 v165, s93, v232
	v_med3_i32 v165, v165, 0, s40
	v_lshl_or_b32 v165, v165, 7, v221
	global_load_lds_dwordx4 v165, s[20:21]
	s_waitcnt vmcnt(8)
	v_add_u32_e32 v154, s15, v223
	v_add_u32_e32 v155, s15, v224
	ds_read_b128 v[80:83], v154
	ds_read_b128 v[84:87], v155
	s_waitcnt lgkmcnt(0)
	s_add_i32 s93, s76, 0
	s_mov_b32 m0, s15
	v_add_u32_e32 v164, s93, v231
	v_med3_i32 v164, v164, 0, s40
	v_lshl_or_b32 v164, v164, 7, v220
	global_load_lds_dwordx4 v164, s[20:21]
	s_add_i32 m0, s15, 0x400
	v_add_u32_e32 v165, s93, v232
	v_med3_i32 v165, v165, 0, s40
	v_lshl_or_b32 v165, v165, 7, v221
	global_load_lds_dwordx4 v165, s[20:21]
	s_waitcnt vmcnt(8)
	v_add_u32_e32 v154, s16, v223
	v_add_u32_e32 v155, s16, v224
	ds_read_b128 v[88:91], v154
	ds_read_b128 v[92:95], v155
	s_waitcnt lgkmcnt(0)
	s_add_i32 s93, s76, 64
	s_mov_b32 m0, s16
	v_add_u32_e32 v164, s93, v231
	v_med3_i32 v164, v164, 0, s40
	v_lshl_or_b32 v164, v164, 7, v220
	global_load_lds_dwordx4 v164, s[20:21]
	s_add_i32 m0, s16, 0x400
	v_add_u32_e32 v165, s93, v232
	v_med3_i32 v165, v165, 0, s40
	v_lshl_or_b32 v165, v165, 7, v221
	global_load_lds_dwordx4 v165, s[20:21]
	s_waitcnt vmcnt(8)
	v_add_u32_e32 v154, s12, v223
	v_add_u32_e32 v155, s12, v224
	ds_read_b128 v[202:205], v154
	ds_read_b128 v[206:209], v155
	v_mfma_f32_16x16x32_bf16 v[0:3], v[88:91], v[72:75], 0
	v_mfma_f32_16x16x32_bf16 v[0:3], v[92:95], v[76:79], v[0:3]
	s_waitcnt lgkmcnt(0)
	s_add_i32 s93, s76, 0x80
	s_mov_b32 m0, s12
	v_add_u32_e32 v164, s93, v231
	v_med3_i32 v164, v164, 0, s40
	v_lshl_or_b32 v164, v164, 7, v220
	global_load_lds_dwordx4 v164, s[20:21]
	s_add_i32 m0, s12, 0x400
	v_add_u32_e32 v165, s93, v232
	v_med3_i32 v165, v165, 0, s40
	v_lshl_or_b32 v165, v165, 7, v221
	global_load_lds_dwordx4 v165, s[20:21]
	s_waitcnt vmcnt(8)
	v_add_u32_e32 v154, s13, v223
	v_add_u32_e32 v155, s13, v224
	ds_read_b128 v[88:91], v154
	ds_read_b128 v[92:95], v155
	v_mfma_f32_16x16x32_bf16 v[4:7], v[202:205], v[72:75], 0
	v_mfma_f32_16x16x32_bf16 v[36:39], v[202:205], v[80:83], 0
	v_mfma_f32_16x16x32_bf16 v[4:7], v[206:209], v[76:79], v[4:7]
	v_mfma_f32_16x16x32_bf16 v[36:39], v[206:209], v[84:87], v[36:39]
	s_waitcnt lgkmcnt(0)
	s_add_i32 s93, s76, 0xc0
	s_mov_b32 m0, s13
	v_add_u32_e32 v164, s93, v231
	v_med3_i32 v164, v164, 0, s40
	v_lshl_or_b32 v164, v164, 7, v220
	global_load_lds_dwordx4 v164, s[20:21]
	s_add_i32 m0, s13, 0x400
	v_add_u32_e32 v165, s93, v232
	v_med3_i32 v165, v165, 0, s40
	v_lshl_or_b32 v165, v165, 7, v221
	global_load_lds_dwordx4 v165, s[20:21]
	s_waitcnt vmcnt(8)
	v_add_u32_e32 v154, s14, v223
	v_add_u32_e32 v155, s14, v224
	ds_read_b128 v[202:205], v154
	ds_read_b128 v[206:209], v155
	v_mfma_f32_16x16x32_bf16 v[8:11], v[88:91], v[72:75], 0
	v_mfma_f32_16x16x32_bf16 v[40:43], v[88:91], v[80:83], 0
	v_mfma_f32_16x16x32_bf16 v[8:11], v[92:95], v[76:79], v[8:11]
	v_mfma_f32_16x16x32_bf16 v[40:43], v[92:95], v[84:87], v[40:43]
	v_mov_b32_e32 v188, s83
	v_lshl_add_u32 v188, v216, 2, v188
	v_lshrrev_b32_e32 v146, 4, v188
	v_xor_b32_e32 v146, v146, v188
	v_and_b32_e32 v146, 15, v146
	v_lshlrev_b32_e32 v147, 8, v188
	v_or_b32_e32 v148, 0, v217
	s_waitcnt lgkmcnt(0)
	s_add_i32 s93, s76, 0x100
	s_mov_b32 m0, s14
	v_add_u32_e32 v164, s93, v231
	v_med3_i32 v164, v164, 0, s40
	v_lshl_or_b32 v164, v164, 7, v220
	global_load_lds_dwordx4 v164, s[20:21]
	s_add_i32 m0, s14, 0x400
	v_add_u32_e32 v165, s93, v232
	v_med3_i32 v165, v165, 0, s40
	v_lshl_or_b32 v165, v165, 7, v221
	global_load_lds_dwordx4 v165, s[20:21]
	s_waitcnt vmcnt(8)
	v_add_u32_e32 v154, s15, v223
	v_add_u32_e32 v155, s15, v224
	ds_read_b128 v[88:91], v154
	ds_read_b128 v[92:95], v155
	v_mfma_f32_16x16x32_bf16 v[12:15], v[202:205], v[72:75], 0
	v_mfma_f32_16x16x32_bf16 v[44:47], v[202:205], v[80:83], 0
	v_mfma_f32_16x16x32_bf16 v[12:15], v[206:209], v[76:79], v[12:15]
	v_mfma_f32_16x16x32_bf16 v[44:47], v[206:209], v[84:87], v[44:47]
	v_xor_b32_e32 v148, v148, v146
	v_lshl_add_u32 v190, v148, 4, v147
	v_or_b32_e32 v148, 4, v217
	v_xor_b32_e32 v148, v148, v146
	v_lshl_add_u32 v191, v148, 4, v147
	v_or_b32_e32 v148, 8, v217
	v_xor_b32_e32 v148, v148, v146
	s_waitcnt lgkmcnt(0)
	s_add_i32 s93, s76, 0x140
	s_mov_b32 m0, s15
	v_add_u32_e32 v164, s93, v231
	v_med3_i32 v164, v164, 0, s40
	v_lshl_or_b32 v164, v164, 7, v220
	global_load_lds_dwordx4 v164, s[20:21]
	s_add_i32 m0, s15, 0x400
	v_add_u32_e32 v165, s93, v232
	v_med3_i32 v165, v165, 0, s40
	v_lshl_or_b32 v165, v165, 7, v221
	global_load_lds_dwordx4 v165, s[20:21]
	s_waitcnt vmcnt(8)
	v_add_u32_e32 v154, s16, v223
	v_add_u32_e32 v155, s16, v224
	ds_read_b128 v[202:205], v154
	ds_read_b128 v[206:209], v155
	v_mfma_f32_16x16x32_bf16 v[16:19], v[88:91], v[72:75], 0
	v_mfma_f32_16x16x32_bf16 v[48:51], v[88:91], v[80:83], 0
	v_mfma_f32_16x16x32_bf16 v[16:19], v[92:95], v[76:79], v[16:19]
	v_mfma_f32_16x16x32_bf16 v[48:51], v[92:95], v[84:87], v[48:51]
	v_lshl_add_u32 v192, v148, 4, v147
	v_or_b32_e32 v148, 12, v217
	v_xor_b32_e32 v148, v148, v146
	v_lshl_add_u32 v193, v148, 4, v147
	v_lshlrev_b32_e32 v194, 3, v188
	v_add_u32_e32 v194, 0x10000, v194
	ds_read_b64 v[144:145], v194
	s_waitcnt lgkmcnt(0)
	s_add_i32 s93, s76, 0xffffff00
	s_mov_b32 m0, s16
	v_add_u32_e32 v164, s93, v231
	v_med3_i32 v164, v164, 0, s40
	v_lshl_or_b32 v164, v164, 7, v222
	global_load_lds_dwordx4 v164, s[24:25]
	s_add_i32 m0, s16, 0x400
	v_add_u32_e32 v165, s93, v232
	v_med3_i32 v165, v165, 0, s40
	v_lshl_or_b32 v165, v165, 7, v222
	global_load_lds_dwordx4 v165, s[24:25]
	s_waitcnt vmcnt(8)
	v_add_u32_e32 v154, s12, v223
	v_add_u32_e32 v155, s12, v224
	ds_read_b128 v[88:91], v154
	ds_read_b128 v[92:95], v155
	v_mfma_f32_16x16x32_bf16 v[20:23], v[202:205], v[72:75], 0
	v_mfma_f32_16x16x32_bf16 v[52:55], v[202:205], v[80:83], 0
	v_mfma_f32_16x16x32_bf16 v[20:23], v[206:209], v[76:79], v[20:23]
	v_mfma_f32_16x16x32_bf16 v[52:55], v[206:209], v[84:87], v[52:55]
	ds_read_b128 v[128:131], v190
	ds_read_b128 v[132:135], v191
	ds_read_b128 v[136:139], v192
	ds_read_b128 v[140:143], v193
	v_mov_b32_e32 v189, s83
	v_lshl_add_u32 v189, v216, 2, v189
	v_add_u32_e32 v189, 64, v189
	s_waitcnt lgkmcnt(0)
	s_add_i32 s93, s76, 0xffffff40
	s_mov_b32 m0, s12
	v_add_u32_e32 v164, s93, v231
	v_med3_i32 v164, v164, 0, s40
	v_lshl_or_b32 v164, v164, 7, v222
	global_load_lds_dwordx4 v164, s[24:25]
	s_add_i32 m0, s12, 0x400
	v_add_u32_e32 v165, s93, v232
	v_med3_i32 v165, v165, 0, s40
	v_lshl_or_b32 v165, v165, 7, v222
	global_load_lds_dwordx4 v165, s[24:25]
	s_waitcnt vmcnt(8)
	v_add_u32_e32 v154, s13, v223
	v_add_u32_e32 v155, s13, v224
	ds_read_b128 v[202:205], v154
	ds_read_b128 v[206:209], v155
	v_mfma_f32_16x16x32_bf16 v[24:27], v[88:91], v[72:75], 0
	v_mfma_f32_16x16x32_bf16 v[56:59], v[88:91], v[80:83], 0
	v_mfma_f32_16x16x32_bf16 v[24:27], v[92:95], v[76:79], v[24:27]
	v_mfma_f32_16x16x32_bf16 v[56:59], v[92:95], v[84:87], v[56:59]
	v_lshrrev_b32_e32 v146, 4, v189
	v_xor_b32_e32 v146, v146, v189
	v_and_b32_e32 v146, 15, v146
	v_lshlrev_b32_e32 v147, 8, v189
	v_or_b32_e32 v148, 0, v217
	v_xor_b32_e32 v148, v148, v146
	v_lshl_add_u32 v195, v148, 4, v147
	s_waitcnt lgkmcnt(0)
	s_add_i32 s93, s76, 0xffffff80
	s_mov_b32 m0, s13
	v_add_u32_e32 v164, s93, v231
	v_med3_i32 v164, v164, 0, s40
	v_lshl_or_b32 v164, v164, 7, v222
	global_load_lds_dwordx4 v164, s[24:25]
	s_add_i32 m0, s13, 0x400
	v_add_u32_e32 v165, s93, v232
	v_med3_i32 v165, v165, 0, s40
	v_lshl_or_b32 v165, v165, 7, v222
	global_load_lds_dwordx4 v165, s[24:25]
	s_waitcnt vmcnt(8)
	v_add_u32_e32 v154, s14, v223
	v_add_u32_e32 v155, s14, v224
	ds_read_b128 v[88:91], v154
	ds_read_b128 v[92:95], v155
	v_mfma_f32_16x16x32_bf16 v[28:31], v[202:205], v[72:75], 0
	v_mfma_f32_16x16x32_bf16 v[60:63], v[202:205], v[80:83], 0
	v_mfma_f32_16x16x32_bf16 v[28:31], v[206:209], v[76:79], v[28:31]
	v_mfma_f32_16x16x32_bf16 v[60:63], v[206:209], v[84:87], v[60:63]
	v_or_b32_e32 v148, 4, v217
	v_xor_b32_e32 v148, v148, v146
	v_lshl_add_u32 v196, v148, 4, v147
	v_or_b32_e32 v148, 8, v217
	v_xor_b32_e32 v148, v148, v146
	v_lshl_add_u32 v197, v148, 4, v147
	v_or_b32_e32 v148, 12, v217
	s_waitcnt lgkmcnt(0)
	s_add_i32 s93, s76, 0xffffffc0
	s_mov_b32 m0, s14
	v_add_u32_e32 v164, s93, v231
	v_med3_i32 v164, v164, 0, s40
	v_lshl_or_b32 v164, v164, 7, v222
	global_load_lds_dwordx4 v164, s[24:25]
	s_add_i32 m0, s14, 0x400
	v_add_u32_e32 v165, s93, v232
	v_med3_i32 v165, v165, 0, s40
	v_lshl_or_b32 v165, v165, 7, v222
	global_load_lds_dwordx4 v165, s[24:25]
	s_waitcnt vmcnt(8)
	v_add_u32_e32 v154, s15, v223
	v_add_u32_e32 v155, s15, v224
	ds_read_b128 v[202:205], v154
	ds_read_b128 v[206:209], v155
	v_mfma_f32_16x16x32_bf16 v[32:35], v[88:91], v[72:75], 0
	v_mfma_f32_16x16x32_bf16 v[64:67], v[88:91], v[80:83], 0
	v_mfma_f32_16x16x32_bf16 v[32:35], v[92:95], v[76:79], v[32:35]
	v_mfma_f32_16x16x32_bf16 v[64:67], v[92:95], v[84:87], v[64:67]
	v_xor_b32_e32 v148, v148, v146
	v_lshl_add_u32 v198, v148, 4, v147
	v_lshlrev_b32_e32 v199, 3, v189
	v_add_u32_e32 v199, 0x10000, v199
	ds_read_b64 v[182:183], v199
	ds_read_b128 v[166:169], v195
	ds_read_b128 v[170:173], v196
	s_waitcnt lgkmcnt(0)
	s_add_i32 s93, s76, 0
	s_mov_b32 m0, s15
	v_add_u32_e32 v164, s93, v231
	v_med3_i32 v164, v164, 0, s40
	v_lshl_or_b32 v164, v164, 7, v222
	global_load_lds_dwordx4 v164, s[24:25]
	s_add_i32 m0, s15, 0x400
	v_add_u32_e32 v165, s93, v232
	v_med3_i32 v165, v165, 0, s40
	v_lshl_or_b32 v165, v165, 7, v222
	global_load_lds_dwordx4 v165, s[24:25]
	s_waitcnt vmcnt(8)
	v_add_u32_e32 v154, s16, v225
	v_add_u32_e32 v155, s16, v226
	v_add_u32_e32 v156, s16, v227
	v_add_u32_e32 v157, s16, v228
	ds_read_b64_tr_b16 v[88:89], v154
	ds_read_b64_tr_b16 v[90:91], v155
	ds_read_b64_tr_b16 v[92:93], v156
	ds_read_b64_tr_b16 v[94:95], v157
	v_mfma_f32_16x16x32_bf16 v[68:71], v[202:205], v[80:83], 0
	v_mfma_f32_16x16x32_bf16 v[68:71], v[206:209], v[84:87], v[68:71]
	ds_read_b128 v[174:177], v197
	ds_read_b128 v[178:181], v198
	s_add_i32 s90, s76, 0x17c
	s_cmp_gt_i32 s90, s40
	s_cselect_b32 s96, 1, 0
	s_cmp_lt_i32 s76, 0x100
	s_cselect_b32 s96, 1, s96
	s_ashr_i32 s77, s76, 2
	s_sub_i32 s77, 64, s77
	s_sub_i32 s78, s40, s76
	s_ashr_i32 s78, s78, 2
	s_add_i32 s78, s78, 64
	v_cndmask_b32_e64 v0, v0, v230, s[52:53]
	v_cndmask_b32_e64 v32, v32, v230, s[62:63]
	v_cndmask_b32_e64 v1, v1, v230, s[56:57]
	v_cndmask_b32_e64 v33, v33, v230, s[64:65]
	v_cndmask_b32_e64 v2, v2, v230, s[58:59]
	v_cndmask_b32_e64 v34, v34, v230, s[70:71]
	v_cndmask_b32_e64 v3, v3, v230, s[60:61]
	v_cndmask_b32_e64 v35, v35, v230, s[72:73]
	s_cmp_eq_u32 s96, 0
	s_cbranch_scc1 .Latt_noedge_3
	v_sub_u32_e32 v200, s77, v229
	s_sub_i32 s91, s78, s77
	v_sub_u32_e32 v150, 0, v200
	v_sub_u32_e32 v151, 1, v200
	v_sub_u32_e32 v152, 2, v200
	v_sub_u32_e32 v153, 3, v200
	v_cmp_lt_u32_e64 s[94:95], s91, v150
	v_cmp_lt_u32_e64 s[86:87], s91, v151
	v_cmp_lt_u32_e64 s[0:1], s91, v152
	v_cmp_lt_u32_e64 s[2:3], s91, v153
	v_cndmask_b32_e64 v0, v0, v230, s[94:95]
	v_cndmask_b32_e64 v1, v1, v230, s[86:87]
	v_cndmask_b32_e64 v2, v2, v230, s[0:1]
	v_cndmask_b32_e64 v3, v3, v230, s[2:3]
	v_sub_u32_e32 v150, 16, v200
	v_sub_u32_e32 v151, 17, v200
	v_sub_u32_e32 v152, 18, v200
	v_sub_u32_e32 v153, 19, v200
	v_cmp_lt_u32_e64 s[94:95], s91, v150
	v_cmp_lt_u32_e64 s[86:87], s91, v151
	v_cmp_lt_u32_e64 s[0:1], s91, v152
	v_cmp_lt_u32_e64 s[2:3], s91, v153
	v_cndmask_b32_e64 v4, v4, v230, s[94:95]
	v_cndmask_b32_e64 v5, v5, v230, s[86:87]
	v_cndmask_b32_e64 v6, v6, v230, s[0:1]
	v_cndmask_b32_e64 v7, v7, v230, s[2:3]
	v_sub_u32_e32 v150, 32, v200
	v_sub_u32_e32 v151, 33, v200
	v_sub_u32_e32 v152, 34, v200
	v_sub_u32_e32 v153, 35, v200
	v_cmp_lt_u32_e64 s[94:95], s91, v150
	v_cmp_lt_u32_e64 s[86:87], s91, v151
	v_cmp_lt_u32_e64 s[0:1], s91, v152
	v_cmp_lt_u32_e64 s[2:3], s91, v153
	v_cndmask_b32_e64 v8, v8, v230, s[94:95]
	v_cndmask_b32_e64 v9, v9, v230, s[86:87]
	v_cndmask_b32_e64 v10, v10, v230, s[0:1]
	v_cndmask_b32_e64 v11, v11, v230, s[2:3]
	v_sub_u32_e32 v150, 48, v200
	v_sub_u32_e32 v151, 49, v200
	v_sub_u32_e32 v152, 50, v200
	v_sub_u32_e32 v153, 51, v200
	v_cmp_lt_u32_e64 s[94:95], s91, v150
	v_cmp_lt_u32_e64 s[86:87], s91, v151
	v_cmp_lt_u32_e64 s[0:1], s91, v152
	v_cmp_lt_u32_e64 s[2:3], s91, v153
	v_cndmask_b32_e64 v12, v12, v230, s[94:95]
	v_cndmask_b32_e64 v13, v13, v230, s[86:87]
	v_cndmask_b32_e64 v14, v14, v230, s[0:1]
	v_cndmask_b32_e64 v15, v15, v230, s[2:3]
	v_sub_u32_e32 v150, 64, v200
	v_sub_u32_e32 v151, 0x41, v200
	v_sub_u32_e32 v152, 0x42, v200
	v_sub_u32_e32 v153, 0x43, v200
	v_cmp_lt_u32_e64 s[94:95], s91, v150
	v_cmp_lt_u32_e64 s[86:87], s91, v151
	v_cmp_lt_u32_e64 s[0:1], s91, v152
	v_cmp_lt_u32_e64 s[2:3], s91, v153
	v_cndmask_b32_e64 v16, v16, v230, s[94:95]
	v_cndmask_b32_e64 v17, v17, v230, s[86:87]
	v_cndmask_b32_e64 v18, v18, v230, s[0:1]
	v_cndmask_b32_e64 v19, v19, v230, s[2:3]
	v_sub_u32_e32 v150, 0x50, v200
	v_sub_u32_e32 v151, 0x51, v200
	v_sub_u32_e32 v152, 0x52, v200
	v_sub_u32_e32 v153, 0x53, v200
	v_cmp_lt_u32_e64 s[94:95], s91, v150
	v_cmp_lt_u32_e64 s[86:87], s91, v151
	v_cmp_lt_u32_e64 s[0:1], s91, v152
	v_cmp_lt_u32_e64 s[2:3], s91, v153
	v_cndmask_b32_e64 v20, v20, v230, s[94:95]
	v_cndmask_b32_e64 v21, v21, v230, s[86:87]
	v_cndmask_b32_e64 v22, v22, v230, s[0:1]
	v_cndmask_b32_e64 v23, v23, v230, s[2:3]
	v_sub_u32_e32 v150, 0x60, v200
	v_sub_u32_e32 v151, 0x61, v200
	v_sub_u32_e32 v152, 0x62, v200
	v_sub_u32_e32 v153, 0x63, v200
	v_cmp_lt_u32_e64 s[94:95], s91, v150
	v_cmp_lt_u32_e64 s[86:87], s91, v151
	v_cmp_lt_u32_e64 s[0:1], s91, v152
	v_cmp_lt_u32_e64 s[2:3], s91, v153
	v_cndmask_b32_e64 v24, v24, v230, s[94:95]
	v_cndmask_b32_e64 v25, v25, v230, s[86:87]
	v_cndmask_b32_e64 v26, v26, v230, s[0:1]
	v_cndmask_b32_e64 v27, v27, v230, s[2:3]
	v_sub_u32_e32 v150, 0x70, v200
	v_sub_u32_e32 v151, 0x71, v200
	v_sub_u32_e32 v152, 0x72, v200
	v_sub_u32_e32 v153, 0x73, v200
	v_cmp_lt_u32_e64 s[94:95], s91, v150
	v_cmp_lt_u32_e64 s[86:87], s91, v151
	v_cmp_lt_u32_e64 s[0:1], s91, v152
	v_cmp_lt_u32_e64 s[2:3], s91, v153
	v_cndmask_b32_e64 v28, v28, v230, s[94:95]
	v_cndmask_b32_e64 v29, v29, v230, s[86:87]
	v_cndmask_b32_e64 v30, v30, v230, s[0:1]
	v_cndmask_b32_e64 v31, v31, v230, s[2:3]
	v_sub_u32_e32 v150, 0x80, v200
	v_sub_u32_e32 v151, 0x81, v200
	v_sub_u32_e32 v152, 0x82, v200
	v_sub_u32_e32 v153, 0x83, v200
	v_cmp_lt_u32_e64 s[94:95], s91, v150
	v_cmp_lt_u32_e64 s[86:87], s91, v151
	v_cmp_lt_u32_e64 s[0:1], s91, v152
	v_cmp_lt_u32_e64 s[2:3], s91, v153
	v_cndmask_b32_e64 v32, v32, v230, s[94:95]
	v_cndmask_b32_e64 v33, v33, v230, s[86:87]
	v_cndmask_b32_e64 v34, v34, v230, s[0:1]
	v_cndmask_b32_e64 v35, v35, v230, s[2:3]

.Latt_noedge_4:
	s_nop 1
	v_max3_f32 v186, v36, v37, v38
	v_max3_f32 v186, v186, v39, v40
	v_max3_f32 v186, v186, v41, v42
	v_max3_f32 v186, v186, v43, v44
	v_max3_f32 v186, v186, v45, v46
	v_max3_f32 v186, v186, v47, v48
	v_max3_f32 v186, v186, v49, v50
	v_max3_f32 v186, v186, v51, v52
	v_max3_f32 v186, v186, v53, v54
	v_max3_f32 v186, v186, v55, v56
	v_max3_f32 v186, v186, v57, v58
	v_max3_f32 v186, v186, v59, v60
	v_max3_f32 v186, v186, v61, v62
	v_max3_f32 v186, v186, v63, v64
	v_max3_f32 v186, v186, v65, v66
	v_max3_f32 v186, v186, v67, v68
	v_max3_f32 v186, v186, v69, v70
	v_max_f32_e32 v186, v186, v71
	v_mov_b32_e32 v146, v186
	s_nop 1
	v_permlane16_swap_b32_e32 v186, v146
	v_max_f32_e32 v186, v186, v146
	v_mov_b32_e32 v146, v186
	s_nop 1
	v_permlane32_swap_b32_e32 v186, v146
	v_max_f32_e32 v186, v186, v146
	s_waitcnt lgkmcnt(0)
	s_add_i32 s93, s76, 64
	s_mov_b32 m0, s16
	v_add_u32_e32 v164, s93, v231
	v_med3_i32 v164, v164, 0, s40
	v_lshl_or_b32 v164, v164, 7, v222
	global_load_lds_dwordx4 v164, s[24:25]
	s_add_i32 m0, s16, 0x400
	v_add_u32_e32 v165, s93, v232
	v_med3_i32 v165, v165, 0, s40
	v_lshl_or_b32 v165, v165, 7, v222
	global_load_lds_dwordx4 v165, s[24:25]
	s_waitcnt vmcnt(8)
	v_add_u32_e32 v154, s12, v225
	v_add_u32_e32 v155, s12, v226
	v_add_u32_e32 v156, s12, v227
	v_add_u32_e32 v157, s12, v228
	ds_read_b64_tr_b16 v[202:203], v154
	ds_read_b64_tr_b16 v[204:205], v155
	ds_read_b64_tr_b16 v[206:207], v156
	ds_read_b64_tr_b16 v[208:209], v157
	v_mfma_f32_16x16x16_bf16 v[96:99], v[88:89], v[0:1], 0
	v_mfma_f32_16x16x16_bf16 v[100:103], v[90:91], v[0:1], 0
	v_mfma_f32_16x16x16_bf16 v[104:107], v[92:93], v[0:1], 0
	v_mfma_f32_16x16x16_bf16 v[108:111], v[94:95], v[0:1], 0
	v_pk_add_f32 v[4:5], v[4:5], v[184:185] op_sel_hi:[1,0] neg_lo:[0,1] neg_hi:[0,1]
	v_pk_add_f32 v[6:7], v[6:7], v[184:185] op_sel_hi:[1,0] neg_lo:[0,1] neg_hi:[0,1]
	v_exp_f32_e32 v4, v4
	v_exp_f32_e32 v5, v5
	v_exp_f32_e32 v6, v6
	v_exp_f32_e32 v7, v7
	s_nop 0
	v_pk_add_f32 v[74:75], v[4:5], v[6:7]
	v_cvt_pk_bf16_f32 v4, v4, v5
	v_cvt_pk_bf16_f32 v5, v6, v7
	v_pk_add_f32 v[36:37], v[36:37], v[186:187] op_sel_hi:[1,0] neg_lo:[0,1] neg_hi:[0,1]
	v_pk_add_f32 v[38:39], v[38:39], v[186:187] op_sel_hi:[1,0] neg_lo:[0,1] neg_hi:[0,1]
	v_exp_f32_e32 v36, v36
	v_exp_f32_e32 v37, v37
	v_exp_f32_e32 v38, v38
	v_exp_f32_e32 v39, v39
	s_nop 0
	v_pk_add_f32 v[76:77], v[36:37], v[38:39]
	v_cvt_pk_bf16_f32 v36, v36, v37
	v_cvt_pk_bf16_f32 v37, v38, v39
	s_waitcnt lgkmcnt(0)
	s_add_i32 s93, s76, 0x80
	s_mov_b32 m0, s12
	v_add_u32_e32 v164, s93, v231
	v_med3_i32 v164, v164, 0, s40
	v_lshl_or_b32 v164, v164, 7, v222
	global_load_lds_dwordx4 v164, s[24:25]
	s_add_i32 m0, s12, 0x400
	v_add_u32_e32 v165, s93, v232
	v_med3_i32 v165, v165, 0, s40
	v_lshl_or_b32 v165, v165, 7, v222
	global_load_lds_dwordx4 v165, s[24:25]
	s_waitcnt vmcnt(8)
	v_add_u32_e32 v154, s13, v225
	v_add_u32_e32 v155, s13, v226
	v_add_u32_e32 v156, s13, v227
	v_add_u32_e32 v157, s13, v228
	ds_read_b64_tr_b16 v[88:89], v154
	ds_read_b64_tr_b16 v[90:91], v155
	ds_read_b64_tr_b16 v[92:93], v156
	ds_read_b64_tr_b16 v[94:95], v157
	v_mfma_f32_16x16x16_bf16 v[96:99], v[202:203], v[4:5], v[96:99]
	v_mfma_f32_16x16x16_bf16 v[112:115], v[202:203], v[36:37], 0
	v_mfma_f32_16x16x16_bf16 v[100:103], v[204:205], v[4:5], v[100:103]
	v_mfma_f32_16x16x16_bf16 v[116:119], v[204:205], v[36:37], 0
	v_mfma_f32_16x16x16_bf16 v[104:107], v[206:207], v[4:5], v[104:107]
	v_mfma_f32_16x16x16_bf16 v[120:123], v[206:207], v[36:37], 0
	v_mfma_f32_16x16x16_bf16 v[108:111], v[208:209], v[4:5], v[108:111]
	v_mfma_f32_16x16x16_bf16 v[124:127], v[208:209], v[36:37], 0
	v_pk_add_f32 v[8:9], v[8:9], v[184:185] op_sel_hi:[1,0] neg_lo:[0,1] neg_hi:[0,1]
	v_pk_add_f32 v[10:11], v[10:11], v[184:185] op_sel_hi:[1,0] neg_lo:[0,1] neg_hi:[0,1]
	v_exp_f32_e32 v8, v8
	v_exp_f32_e32 v9, v9
	v_exp_f32_e32 v10, v10
	v_exp_f32_e32 v11, v11
	s_nop 0
	v_pk_add_f32 v[72:73], v[72:73], v[8:9]
	v_pk_add_f32 v[74:75], v[74:75], v[10:11]
	v_cvt_pk_bf16_f32 v8, v8, v9
	v_cvt_pk_bf16_f32 v9, v10, v11
	v_pk_add_f32 v[40:41], v[40:41], v[186:187] op_sel_hi:[1,0] neg_lo:[0,1] neg_hi:[0,1]
	v_pk_add_f32 v[42:43], v[42:43], v[186:187] op_sel_hi:[1,0] neg_lo:[0,1] neg_hi:[0,1]
	v_exp_f32_e32 v40, v40
	v_exp_f32_e32 v41, v41
	v_exp_f32_e32 v42, v42
	v_exp_f32_e32 v43, v43
	s_nop 0
	v_pk_add_f32 v[78:79], v[40:41], v[42:43]
	v_cvt_pk_bf16_f32 v40, v40, v41
	v_cvt_pk_bf16_f32 v41, v42, v43
	s_waitcnt lgkmcnt(0)
	s_add_i32 s93, s76, 0xc0
	s_mov_b32 m0, s13
	v_add_u32_e32 v164, s93, v231
	v_med3_i32 v164, v164, 0, s40
	v_lshl_or_b32 v164, v164, 7, v222
	global_load_lds_dwordx4 v164, s[24:25]
	s_add_i32 m0, s13, 0x400
	v_add_u32_e32 v165, s93, v232
	v_med3_i32 v165, v165, 0, s40
	v_lshl_or_b32 v165, v165, 7, v222
	global_load_lds_dwordx4 v165, s[24:25]
	s_waitcnt vmcnt(8)
	v_add_u32_e32 v154, s14, v225
	v_add_u32_e32 v155, s14, v226
	v_add_u32_e32 v156, s14, v227
	v_add_u32_e32 v157, s14, v228
	ds_read_b64_tr_b16 v[202:203], v154
	ds_read_b64_tr_b16 v[204:205], v155
	ds_read_b64_tr_b16 v[206:207], v156
	ds_read_b64_tr_b16 v[208:209], v157
	v_mfma_f32_16x16x16_bf16 v[96:99], v[88:89], v[8:9], v[96:99]
	v_mfma_f32_16x16x16_bf16 v[112:115], v[88:89], v[40:41], v[112:115]
	v_mfma_f32_16x16x16_bf16 v[100:103], v[90:91], v[8:9], v[100:103]
	v_mfma_f32_16x16x16_bf16 v[116:119], v[90:91], v[40:41], v[116:119]
	v_mfma_f32_16x16x16_bf16 v[104:107], v[92:93], v[8:9], v[104:107]
	v_mfma_f32_16x16x16_bf16 v[120:123], v[92:93], v[40:41], v[120:123]
	v_mfma_f32_16x16x16_bf16 v[108:111], v[94:95], v[8:9], v[108:111]
	v_mfma_f32_16x16x16_bf16 v[124:127], v[94:95], v[40:41], v[124:127]
	v_pk_add_f32 v[12:13], v[12:13], v[184:185] op_sel_hi:[1,0] neg_lo:[0,1] neg_hi:[0,1]
	v_pk_add_f32 v[14:15], v[14:15], v[184:185] op_sel_hi:[1,0] neg_lo:[0,1] neg_hi:[0,1]
	v_exp_f32_e32 v12, v12
	v_exp_f32_e32 v13, v13
	v_exp_f32_e32 v14, v14
	v_exp_f32_e32 v15, v15
	s_nop 0
	v_pk_add_f32 v[72:73], v[72:73], v[12:13]
	v_pk_add_f32 v[74:75], v[74:75], v[14:15]
	v_cvt_pk_bf16_f32 v12, v12, v13
	v_cvt_pk_bf16_f32 v13, v14, v15
	v_pk_add_f32 v[44:45], v[44:45], v[186:187] op_sel_hi:[1,0] neg_lo:[0,1] neg_hi:[0,1]
	v_pk_add_f32 v[46:47], v[46:47], v[186:187] op_sel_hi:[1,0] neg_lo:[0,1] neg_hi:[0,1]
	v_exp_f32_e32 v44, v44
	v_exp_f32_e32 v45, v45
	v_exp_f32_e32 v46, v46
	v_exp_f32_e32 v47, v47
	s_nop 0
	v_pk_add_f32 v[76:77], v[76:77], v[44:45]
	v_pk_add_f32 v[78:79], v[78:79], v[46:47]
	v_cvt_pk_bf16_f32 v44, v44, v45
	v_cvt_pk_bf16_f32 v45, v46, v47
	s_waitcnt lgkmcnt(0)
	s_add_i32 s93, s76, 0x100
	s_mov_b32 m0, s14
	v_add_u32_e32 v164, s93, v231
	v_med3_i32 v164, v164, 0, s40
	v_lshl_or_b32 v164, v164, 7, v222
	global_load_lds_dwordx4 v164, s[24:25]
	s_add_i32 m0, s14, 0x400
	v_add_u32_e32 v165, s93, v232
	v_med3_i32 v165, v165, 0, s40
	v_lshl_or_b32 v165, v165, 7, v222
	global_load_lds_dwordx4 v165, s[24:25]
	s_waitcnt vmcnt(8)
	v_add_u32_e32 v154, s15, v225
	v_add_u32_e32 v155, s15, v226
	v_add_u32_e32 v156, s15, v227
	v_add_u32_e32 v157, s15, v228
	ds_read_b64_tr_b16 v[88:89], v154
	ds_read_b64_tr_b16 v[90:91], v155
	ds_read_b64_tr_b16 v[92:93], v156
	ds_read_b64_tr_b16 v[94:95], v157
	v_mfma_f32_16x16x16_bf16 v[96:99], v[202:203], v[12:13], v[96:99]
	v_mfma_f32_16x16x16_bf16 v[112:115], v[202:203], v[44:45], v[112:115]
	v_mfma_f32_16x16x16_bf16 v[100:103], v[204:205], v[12:13], v[100:103]
	v_mfma_f32_16x16x16_bf16 v[116:119], v[204:205], v[44:45], v[116:119]
	v_mfma_f32_16x16x16_bf16 v[104:107], v[206:207], v[12:13], v[104:107]
	v_mfma_f32_16x16x16_bf16 v[120:123], v[206:207], v[44:45], v[120:123]
	v_mfma_f32_16x16x16_bf16 v[108:111], v[208:209], v[12:13], v[108:111]
	v_mfma_f32_16x16x16_bf16 v[124:127], v[208:209], v[44:45], v[124:127]
	v_pk_add_f32 v[16:17], v[16:17], v[184:185] op_sel_hi:[1,0] neg_lo:[0,1] neg_hi:[0,1]
	v_pk_add_f32 v[18:19], v[18:19], v[184:185] op_sel_hi:[1,0] neg_lo:[0,1] neg_hi:[0,1]
	v_exp_f32_e32 v16, v16
	v_exp_f32_e32 v17, v17
	v_exp_f32_e32 v18, v18
	v_exp_f32_e32 v19, v19
	s_nop 0
	v_pk_add_f32 v[72:73], v[72:73], v[16:17]
	v_pk_add_f32 v[74:75], v[74:75], v[18:19]
	v_cvt_pk_bf16_f32 v16, v16, v17
	v_cvt_pk_bf16_f32 v17, v18, v19
	v_pk_add_f32 v[48:49], v[48:49], v[186:187] op_sel_hi:[1,0] neg_lo:[0,1] neg_hi:[0,1]
	v_pk_add_f32 v[50:51], v[50:51], v[186:187] op_sel_hi:[1,0] neg_lo:[0,1] neg_hi:[0,1]
	v_exp_f32_e32 v48, v48
	v_exp_f32_e32 v49, v49
	v_exp_f32_e32 v50, v50
	v_exp_f32_e32 v51, v51
	s_nop 0
	v_pk_add_f32 v[76:77], v[76:77], v[48:49]
	v_pk_add_f32 v[78:79], v[78:79], v[50:51]
	v_cvt_pk_bf16_f32 v48, v48, v49
	v_cvt_pk_bf16_f32 v49, v50, v51
	s_waitcnt lgkmcnt(0)
	s_add_i32 s93, s76, 0x140
	s_mov_b32 m0, s15
	v_add_u32_e32 v164, s93, v231
	v_med3_i32 v164, v164, 0, s40
	v_lshl_or_b32 v164, v164, 7, v222
	global_load_lds_dwordx4 v164, s[24:25]
	s_add_i32 m0, s15, 0x400
	v_add_u32_e32 v165, s93, v232
	v_med3_i32 v165, v165, 0, s40
	v_lshl_or_b32 v165, v165, 7, v222
	global_load_lds_dwordx4 v165, s[24:25]
	s_waitcnt vmcnt(8)
	v_add_u32_e32 v154, s16, v225
	v_add_u32_e32 v155, s16, v226
	v_add_u32_e32 v156, s16, v227
	v_add_u32_e32 v157, s16, v228
	ds_read_b64_tr_b16 v[202:203], v154
	ds_read_b64_tr_b16 v[204:205], v155
	ds_read_b64_tr_b16 v[206:207], v156
	ds_read_b64_tr_b16 v[208:209], v157
	v_mfma_f32_16x16x16_bf16 v[96:99], v[88:89], v[16:17], v[96:99]
	v_mfma_f32_16x16x16_bf16 v[112:115], v[88:89], v[48:49], v[112:115]
	v_mfma_f32_16x16x16_bf16 v[100:103], v[90:91], v[16:17], v[100:103]
	v_mfma_f32_16x16x16_bf16 v[116:119], v[90:91], v[48:49], v[116:119]
	v_mfma_f32_16x16x16_bf16 v[104:107], v[92:93], v[16:17], v[104:107]
	v_mfma_f32_16x16x16_bf16 v[120:123], v[92:93], v[48:49], v[120:123]
	v_mfma_f32_16x16x16_bf16 v[108:111], v[94:95], v[16:17], v[108:111]
	v_mfma_f32_16x16x16_bf16 v[124:127], v[94:95], v[48:49], v[124:127]
	v_pk_add_f32 v[20:21], v[20:21], v[184:185] op_sel_hi:[1,0] neg_lo:[0,1] neg_hi:[0,1]
	v_pk_add_f32 v[22:23], v[22:23], v[184:185] op_sel_hi:[1,0] neg_lo:[0,1] neg_hi:[0,1]
	v_exp_f32_e32 v20, v20
	v_exp_f32_e32 v21, v21
	v_exp_f32_e32 v22, v22
	v_exp_f32_e32 v23, v23
	s_nop 0
	v_pk_add_f32 v[72:73], v[72:73], v[20:21]
	v_pk_add_f32 v[74:75], v[74:75], v[22:23]
	v_cvt_pk_bf16_f32 v20, v20, v21
	v_cvt_pk_bf16_f32 v21, v22, v23
	v_pk_add_f32 v[52:53], v[52:53], v[186:187] op_sel_hi:[1,0] neg_lo:[0,1] neg_hi:[0,1]
	v_pk_add_f32 v[54:55], v[54:55], v[186:187] op_sel_hi:[1,0] neg_lo:[0,1] neg_hi:[0,1]
	v_exp_f32_e32 v52, v52
	v_exp_f32_e32 v53, v53
	v_exp_f32_e32 v54, v54
	v_exp_f32_e32 v55, v55
	s_nop 0
	v_pk_add_f32 v[76:77], v[76:77], v[52:53]
	v_pk_add_f32 v[78:79], v[78:79], v[54:55]
	v_cvt_pk_bf16_f32 v52, v52, v53
	v_cvt_pk_bf16_f32 v53, v54, v55
	s_waitcnt lgkmcnt(0)
	s_add_i32 s93, s79, 0
	s_mov_b32 m0, s16
	v_add_u32_e32 v164, s93, v162
	v_lshl_or_b32 v164, v164, 7, v220
	global_load_lds_dwordx4 v164, s[18:19]
	s_add_i32 m0, s16, 0x400
	v_add_u32_e32 v165, s93, v163
	v_lshl_or_b32 v165, v165, 7, v221
	global_load_lds_dwordx4 v165, s[18:19]
	s_waitcnt vmcnt(8)
	v_add_u32_e32 v154, s12, v225
	v_add_u32_e32 v155, s12, v226
	v_add_u32_e32 v156, s12, v227
	v_add_u32_e32 v157, s12, v228
	ds_read_b64_tr_b16 v[88:89], v154
	ds_read_b64_tr_b16 v[90:91], v155
	ds_read_b64_tr_b16 v[92:93], v156
	ds_read_b64_tr_b16 v[94:95], v157
	v_mfma_f32_16x16x16_bf16 v[96:99], v[202:203], v[20:21], v[96:99]
	v_mfma_f32_16x16x16_bf16 v[112:115], v[202:203], v[52:53], v[112:115]
	v_mfma_f32_16x16x16_bf16 v[100:103], v[204:205], v[20:21], v[100:103]
	v_mfma_f32_16x16x16_bf16 v[116:119], v[204:205], v[52:53], v[116:119]
	v_mfma_f32_16x16x16_bf16 v[104:107], v[206:207], v[20:21], v[104:107]
	v_mfma_f32_16x16x16_bf16 v[120:123], v[206:207], v[52:53], v[120:123]
	v_mfma_f32_16x16x16_bf16 v[108:111], v[208:209], v[20:21], v[108:111]
	v_mfma_f32_16x16x16_bf16 v[124:127], v[208:209], v[52:53], v[124:127]
	v_pk_add_f32 v[24:25], v[24:25], v[184:185] op_sel_hi:[1,0] neg_lo:[0,1] neg_hi:[0,1]
	v_pk_add_f32 v[26:27], v[26:27], v[184:185] op_sel_hi:[1,0] neg_lo:[0,1] neg_hi:[0,1]
	v_exp_f32_e32 v24, v24
	v_exp_f32_e32 v25, v25
	v_exp_f32_e32 v26, v26
	v_exp_f32_e32 v27, v27
	s_nop 0
	v_pk_add_f32 v[72:73], v[72:73], v[24:25]
	v_pk_add_f32 v[74:75], v[74:75], v[26:27]
	v_cvt_pk_bf16_f32 v24, v24, v25
	v_cvt_pk_bf16_f32 v25, v26, v27
	v_pk_add_f32 v[56:57], v[56:57], v[186:187] op_sel_hi:[1,0] neg_lo:[0,1] neg_hi:[0,1]
	v_pk_add_f32 v[58:59], v[58:59], v[186:187] op_sel_hi:[1,0] neg_lo:[0,1] neg_hi:[0,1]
	v_exp_f32_e32 v56, v56
	v_exp_f32_e32 v57, v57
	v_exp_f32_e32 v58, v58
	v_exp_f32_e32 v59, v59
	s_nop 0
	v_pk_add_f32 v[76:77], v[76:77], v[56:57]
	v_pk_add_f32 v[78:79], v[78:79], v[58:59]
	v_cvt_pk_bf16_f32 v56, v56, v57
	v_cvt_pk_bf16_f32 v57, v58, v59
	s_waitcnt lgkmcnt(0)
	s_add_i32 s93, s79, 0xfffffc00
	s_mov_b32 m0, s12
	v_add_u32_e32 v164, s93, v162
	v_med3_i32 v164, v164, 0, s40
	v_lshl_or_b32 v164, v164, 7, v220
	global_load_lds_dwordx4 v164, s[20:21]
	s_add_i32 m0, s12, 0x400
	v_add_u32_e32 v165, s93, v163
	v_med3_i32 v165, v165, 0, s40
	v_lshl_or_b32 v165, v165, 7, v221
	global_load_lds_dwordx4 v165, s[20:21]
	s_waitcnt vmcnt(8)
	v_add_u32_e32 v154, s13, v225
	v_add_u32_e32 v155, s13, v226
	v_add_u32_e32 v156, s13, v227
	v_add_u32_e32 v157, s13, v228
	ds_read_b64_tr_b16 v[202:203], v154
	ds_read_b64_tr_b16 v[204:205], v155
	ds_read_b64_tr_b16 v[206:207], v156
	ds_read_b64_tr_b16 v[208:209], v157
	v_mfma_f32_16x16x16_bf16 v[96:99], v[88:89], v[24:25], v[96:99]
	v_mfma_f32_16x16x16_bf16 v[112:115], v[88:89], v[56:57], v[112:115]
	v_mfma_f32_16x16x16_bf16 v[100:103], v[90:91], v[24:25], v[100:103]
	v_mfma_f32_16x16x16_bf16 v[116:119], v[90:91], v[56:57], v[116:119]
	v_mfma_f32_16x16x16_bf16 v[104:107], v[92:93], v[24:25], v[104:107]
	v_mfma_f32_16x16x16_bf16 v[120:123], v[92:93], v[56:57], v[120:123]
	v_mfma_f32_16x16x16_bf16 v[108:111], v[94:95], v[24:25], v[108:111]
	v_mfma_f32_16x16x16_bf16 v[124:127], v[94:95], v[56:57], v[124:127]
	v_pk_add_f32 v[28:29], v[28:29], v[184:185] op_sel_hi:[1,0] neg_lo:[0,1] neg_hi:[0,1]
	v_pk_add_f32 v[30:31], v[30:31], v[184:185] op_sel_hi:[1,0] neg_lo:[0,1] neg_hi:[0,1]
	v_exp_f32_e32 v28, v28
	v_exp_f32_e32 v29, v29
	v_exp_f32_e32 v30, v30
	v_exp_f32_e32 v31, v31
	s_nop 0
	v_pk_add_f32 v[72:73], v[72:73], v[28:29]
	v_pk_add_f32 v[74:75], v[74:75], v[30:31]
	v_cvt_pk_bf16_f32 v28, v28, v29
	v_cvt_pk_bf16_f32 v29, v30, v31
	v_pk_add_f32 v[60:61], v[60:61], v[186:187] op_sel_hi:[1,0] neg_lo:[0,1] neg_hi:[0,1]
	v_pk_add_f32 v[62:63], v[62:63], v[186:187] op_sel_hi:[1,0] neg_lo:[0,1] neg_hi:[0,1]
	v_exp_f32_e32 v60, v60
	v_exp_f32_e32 v61, v61
	v_exp_f32_e32 v62, v62
	v_exp_f32_e32 v63, v63
	s_nop 0
	v_pk_add_f32 v[76:77], v[76:77], v[60:61]
	v_pk_add_f32 v[78:79], v[78:79], v[62:63]
	v_cvt_pk_bf16_f32 v60, v60, v61
	v_cvt_pk_bf16_f32 v61, v62, v63
	s_waitcnt lgkmcnt(0)
	s_add_i32 s93, s79, 0xfffffd00
	s_mov_b32 m0, s13
	v_add_u32_e32 v164, s93, v162
	v_med3_i32 v164, v164, 0, s40
	v_lshl_or_b32 v164, v164, 7, v220
	global_load_lds_dwordx4 v164, s[20:21]
	s_add_i32 m0, s13, 0x400
	v_add_u32_e32 v165, s93, v163
	v_med3_i32 v165, v165, 0, s40
	v_lshl_or_b32 v165, v165, 7, v221
	global_load_lds_dwordx4 v165, s[20:21]
	s_waitcnt vmcnt(8)
	v_add_u32_e32 v154, s14, v225
	v_add_u32_e32 v155, s14, v226
	v_add_u32_e32 v156, s14, v227
	v_add_u32_e32 v157, s14, v228
	ds_read_b64_tr_b16 v[88:89], v154
	ds_read_b64_tr_b16 v[90:91], v155
	ds_read_b64_tr_b16 v[92:93], v156
	ds_read_b64_tr_b16 v[94:95], v157
	v_mfma_f32_16x16x16_bf16 v[96:99], v[202:203], v[28:29], v[96:99]
	v_mfma_f32_16x16x16_bf16 v[112:115], v[202:203], v[60:61], v[112:115]
	v_mfma_f32_16x16x16_bf16 v[100:103], v[204:205], v[28:29], v[100:103]
	v_mfma_f32_16x16x16_bf16 v[116:119], v[204:205], v[60:61], v[116:119]
	v_mfma_f32_16x16x16_bf16 v[104:107], v[206:207], v[28:29], v[104:107]
	v_mfma_f32_16x16x16_bf16 v[120:123], v[206:207], v[60:61], v[120:123]
	v_mfma_f32_16x16x16_bf16 v[108:111], v[208:209], v[28:29], v[108:111]
	v_mfma_f32_16x16x16_bf16 v[124:127], v[208:209], v[60:61], v[124:127]
	v_pk_add_f32 v[32:33], v[32:33], v[184:185] op_sel_hi:[1,0] neg_lo:[0,1] neg_hi:[0,1]
	v_pk_add_f32 v[34:35], v[34:35], v[184:185] op_sel_hi:[1,0] neg_lo:[0,1] neg_hi:[0,1]
	v_exp_f32_e32 v32, v32
	v_exp_f32_e32 v33, v33
	v_exp_f32_e32 v34, v34
	v_exp_f32_e32 v35, v35
	s_nop 0
	v_pk_add_f32 v[72:73], v[72:73], v[32:33]
	v_pk_add_f32 v[74:75], v[74:75], v[34:35]
	v_cvt_pk_bf16_f32 v32, v32, v33
	v_cvt_pk_bf16_f32 v33, v34, v35
	v_pk_add_f32 v[64:65], v[64:65], v[186:187] op_sel_hi:[1,0] neg_lo:[0,1] neg_hi:[0,1]
	v_pk_add_f32 v[66:67], v[66:67], v[186:187] op_sel_hi:[1,0] neg_lo:[0,1] neg_hi:[0,1]
	v_exp_f32_e32 v64, v64
	v_exp_f32_e32 v65, v65
	v_exp_f32_e32 v66, v66
	v_exp_f32_e32 v67, v67
	s_nop 0
	v_pk_add_f32 v[76:77], v[76:77], v[64:65]
	v_pk_add_f32 v[78:79], v[78:79], v[66:67]
	v_cvt_pk_bf16_f32 v64, v64, v65
	v_cvt_pk_bf16_f32 v65, v66, v67
	s_waitcnt lgkmcnt(0)
	s_add_i32 s93, s79, 0xfffffe00
	s_mov_b32 m0, s14
	v_add_u32_e32 v164, s93, v162
	v_med3_i32 v164, v164, 0, s40
	v_lshl_or_b32 v164, v164, 7, v220
	global_load_lds_dwordx4 v164, s[20:21]
	s_add_i32 m0, s14, 0x400
	v_add_u32_e32 v165, s93, v163
	v_med3_i32 v165, v165, 0, s40
	v_lshl_or_b32 v165, v165, 7, v221
	global_load_lds_dwordx4 v165, s[20:21]
	s_waitcnt vmcnt(8)
	v_add_u32_e32 v154, s15, v225
	v_add_u32_e32 v155, s15, v226
	v_add_u32_e32 v156, s15, v227
	v_add_u32_e32 v157, s15, v228
	ds_read_b64_tr_b16 v[202:203], v154
	ds_read_b64_tr_b16 v[204:205], v155
	ds_read_b64_tr_b16 v[206:207], v156
	ds_read_b64_tr_b16 v[208:209], v157
	v_mfma_f32_16x16x16_bf16 v[96:99], v[88:89], v[32:33], v[96:99]
	v_mfma_f32_16x16x16_bf16 v[112:115], v[88:89], v[64:65], v[112:115]
	v_mfma_f32_16x16x16_bf16 v[100:103], v[90:91], v[32:33], v[100:103]
	v_mfma_f32_16x16x16_bf16 v[116:119], v[90:91], v[64:65], v[116:119]
	v_mfma_f32_16x16x16_bf16 v[104:107], v[92:93], v[32:33], v[104:107]
	v_mfma_f32_16x16x16_bf16 v[120:123], v[92:93], v[64:65], v[120:123]
	v_mfma_f32_16x16x16_bf16 v[108:111], v[94:95], v[32:33], v[108:111]
	v_mfma_f32_16x16x16_bf16 v[124:127], v[94:95], v[64:65], v[124:127]
	v_pk_add_f32 v[68:69], v[68:69], v[186:187] op_sel_hi:[1,0] neg_lo:[0,1] neg_hi:[0,1]
	v_pk_add_f32 v[70:71], v[70:71], v[186:187] op_sel_hi:[1,0] neg_lo:[0,1] neg_hi:[0,1]
	v_exp_f32_e32 v68, v68
	v_exp_f32_e32 v69, v69
	v_exp_f32_e32 v70, v70
	v_exp_f32_e32 v71, v71
	s_nop 0
	v_pk_add_f32 v[76:77], v[76:77], v[68:69]
	v_pk_add_f32 v[78:79], v[78:79], v[70:71]
	v_cvt_pk_bf16_f32 v68, v68, v69
	v_cvt_pk_bf16_f32 v69, v70, v71
	s_nop 0
	v_pk_add_f32 v[72:73], v[72:73], v[74:75]
	s_nop 0
	v_add_f32_e32 v185, v72, v73
	v_mov_b32_e32 v146, v185
	s_nop 1
	v_permlane16_swap_b32_e32 v185, v146
	v_add_f32_e32 v185, v185, v146
	v_mov_b32_e32 v146, v185
	s_nop 1
	v_permlane32_swap_b32_e32 v185, v146
	v_add_f32_e32 v185, v185, v146
	s_waitcnt lgkmcnt(0)
	s_add_i32 s93, s79, 0xffffff00
	s_mov_b32 m0, s15
	v_add_u32_e32 v164, s93, v162
	v_med3_i32 v164, v164, 0, s40
	v_lshl_or_b32 v164, v164, 7, v220
	global_load_lds_dwordx4 v164, s[20:21]
	s_add_i32 m0, s15, 0x400
	v_add_u32_e32 v165, s93, v163
	v_med3_i32 v165, v165, 0, s40
	v_lshl_or_b32 v165, v165, 7, v221
	global_load_lds_dwordx4 v165, s[20:21]
	v_mfma_f32_16x16x16_bf16 v[112:115], v[202:203], v[68:69], v[112:115]
	v_mfma_f32_16x16x16_bf16 v[116:119], v[204:205], v[68:69], v[116:119]
	v_mfma_f32_16x16x16_bf16 v[120:123], v[206:207], v[68:69], v[120:123]
	v_mfma_f32_16x16x16_bf16 v[124:127], v[208:209], v[68:69], v[124:127]
	s_nop 0
	v_pk_add_f32 v[76:77], v[76:77], v[78:79]
	s_nop 0
	v_add_f32_e32 v187, v76, v77
	v_mov_b32_e32 v146, v187
	s_nop 1
	v_permlane16_swap_b32_e32 v187, v146
	v_add_f32_e32 v187, v187, v146
	v_mov_b32_e32 v146, v187
	s_nop 1
	v_permlane32_swap_b32_e32 v187, v146
	v_add_f32_e32 v187, v187, v146
	s_waitcnt lgkmcnt(0)
	v_max_f32_e32 v146, v144, v184
	v_sub_f32_e32 v148, v144, v146
	v_sub_f32_e32 v150, v184, v146
	v_exp_f32_e32 v148, v148
	v_exp_f32_e32 v150, v150
	v_mov_b32_e32 v184, v146
	v_mul_f32_e32 v185, v185, v150
	v_fmac_f32_e32 v185, v145, v148
	v_pk_mul_f32 v[96:97], v[150:151], v[96:97] op_sel_hi:[0,1]
	v_pk_mul_f32 v[98:99], v[150:151], v[98:99] op_sel_hi:[0,1]
	v_pk_mul_f32 v[100:101], v[150:151], v[100:101] op_sel_hi:[0,1]
	v_pk_mul_f32 v[102:103], v[150:151], v[102:103] op_sel_hi:[0,1]
	v_pk_mul_f32 v[104:105], v[150:151], v[104:105] op_sel_hi:[0,1]
	v_pk_mul_f32 v[106:107], v[150:151], v[106:107] op_sel_hi:[0,1]
	v_pk_mul_f32 v[108:109], v[150:151], v[108:109] op_sel_hi:[0,1]
	v_pk_mul_f32 v[110:111], v[150:151], v[110:111] op_sel_hi:[0,1]
	v_pk_fma_f32 v[96:97], v[148:149], v[128:129], v[96:97] op_sel_hi:[0,1,1]
	v_pk_fma_f32 v[98:99], v[148:149], v[130:131], v[98:99] op_sel_hi:[0,1,1]
	v_pk_fma_f32 v[100:101], v[148:149], v[132:133], v[100:101] op_sel_hi:[0,1,1]
	v_pk_fma_f32 v[102:103], v[148:149], v[134:135], v[102:103] op_sel_hi:[0,1,1]
	v_pk_fma_f32 v[104:105], v[148:149], v[136:137], v[104:105] op_sel_hi:[0,1,1]
	v_pk_fma_f32 v[106:107], v[148:149], v[138:139], v[106:107] op_sel_hi:[0,1,1]
	v_pk_fma_f32 v[108:109], v[148:149], v[140:141], v[108:109] op_sel_hi:[0,1,1]
	v_pk_fma_f32 v[110:111], v[148:149], v[142:143], v[110:111] op_sel_hi:[0,1,1]
	s_and_saveexec_b64 s[80:81], s[74:75]
	ds_write_b64 v194, v[184:185]
	s_mov_b64 exec, s[80:81]
	ds_write_b128 v190, v[96:99]
	ds_write_b128 v191, v[100:103]
	ds_write_b128 v192, v[104:107]
	ds_write_b128 v193, v[108:111]
	s_waitcnt lgkmcnt(0)
	v_max_f32_e32 v146, v182, v186
	v_sub_f32_e32 v148, v182, v146
	v_sub_f32_e32 v150, v186, v146
	v_exp_f32_e32 v148, v148
	v_exp_f32_e32 v150, v150
	v_mov_b32_e32 v186, v146
	v_mul_f32_e32 v187, v187, v150
	v_fmac_f32_e32 v187, v183, v148
	v_pk_mul_f32 v[112:113], v[150:151], v[112:113] op_sel_hi:[0,1]
	v_pk_mul_f32 v[114:115], v[150:151], v[114:115] op_sel_hi:[0,1]
	v_pk_mul_f32 v[116:117], v[150:151], v[116:117] op_sel_hi:[0,1]
	v_pk_mul_f32 v[118:119], v[150:151], v[118:119] op_sel_hi:[0,1]
	v_pk_mul_f32 v[120:121], v[150:151], v[120:121] op_sel_hi:[0,1]
	v_pk_mul_f32 v[122:123], v[150:151], v[122:123] op_sel_hi:[0,1]
	v_pk_mul_f32 v[124:125], v[150:151], v[124:125] op_sel_hi:[0,1]
	v_pk_mul_f32 v[126:127], v[150:151], v[126:127] op_sel_hi:[0,1]
	v_pk_fma_f32 v[112:113], v[148:149], v[166:167], v[112:113] op_sel_hi:[0,1,1]
	v_pk_fma_f32 v[114:115], v[148:149], v[168:169], v[114:115] op_sel_hi:[0,1,1]
	v_pk_fma_f32 v[116:117], v[148:149], v[170:171], v[116:117] op_sel_hi:[0,1,1]
	v_pk_fma_f32 v[118:119], v[148:149], v[172:173], v[118:119] op_sel_hi:[0,1,1]
	v_pk_fma_f32 v[120:121], v[148:149], v[174:175], v[120:121] op_sel_hi:[0,1,1]
	v_pk_fma_f32 v[122:123], v[148:149], v[176:177], v[122:123] op_sel_hi:[0,1,1]
	v_pk_fma_f32 v[124:125], v[148:149], v[178:179], v[124:125] op_sel_hi:[0,1,1]
	v_pk_fma_f32 v[126:127], v[148:149], v[180:181], v[126:127] op_sel_hi:[0,1,1]
	s_and_saveexec_b64 s[80:81], s[74:75]
	ds_write_b64 v199, v[186:187]
	s_mov_b64 exec, s[80:81]
	ds_write_b128 v195, v[112:115]
	ds_write_b128 v196, v[116:119]
	ds_write_b128 v197, v[120:123]
	ds_write_b128 v198, v[124:127]
	s_waitcnt lgkmcnt(0)
	s_barrier
	s_add_i32 s76, s38, s84
	s_add_i32 s79, s39, s82
	v_lshlrev_b32_e32 v231, 4, v218
	v_add_u32_e32 v232, 8, v218
	v_lshlrev_b32_e32 v232, 4, v232
	v_lshlrev_b32_e32 v162, 0, v218
	v_add_u32_e32 v163, 8, v218
	v_lshlrev_b32_e32 v163, 0, v163
	s_add_i32 s8, s38, s85
	s_waitcnt vmcnt(8)
	v_add_u32_e32 v154, s16, v223
	v_add_u32_e32 v155, s16, v224
	ds_read_b128 v[72:75], v154
	ds_read_b128 v[76:79], v155
	s_waitcnt lgkmcnt(0)
	s_add_i32 s93, s76, 0
	s_mov_b32 m0, s16
	v_add_u32_e32 v164, s93, v231
	v_med3_i32 v164, v164, 0, s40
	v_lshl_or_b32 v164, v164, 7, v220
	global_load_lds_dwordx4 v164, s[20:21]
	s_add_i32 m0, s16, 0x400
	v_add_u32_e32 v165, s93, v232
	v_med3_i32 v165, v165, 0, s40
	v_lshl_or_b32 v165, v165, 7, v221
	global_load_lds_dwordx4 v165, s[20:21]
	s_waitcnt vmcnt(8)
	v_add_u32_e32 v154, s12, v223
	v_add_u32_e32 v155, s12, v224
	ds_read_b128 v[202:205], v154
	ds_read_b128 v[206:209], v155
	s_waitcnt lgkmcnt(0)
	s_add_i32 s93, s76, 0x100
	s_mov_b32 m0, s12
	v_add_u32_e32 v164, s93, v231
	v_med3_i32 v164, v164, 0, s40
	v_lshl_or_b32 v164, v164, 7, v220
	global_load_lds_dwordx4 v164, s[20:21]
	s_add_i32 m0, s12, 0x400
	v_add_u32_e32 v165, s93, v232
	v_med3_i32 v165, v165, 0, s40
	v_lshl_or_b32 v165, v165, 7, v221
	global_load_lds_dwordx4 v165, s[20:21]
	s_waitcnt vmcnt(8)
	v_add_u32_e32 v154, s13, v223
	v_add_u32_e32 v155, s13, v224
	ds_read_b128 v[88:91], v154
	ds_read_b128 v[92:95], v155
	v_mfma_f32_16x16x32_bf16 v[0:3], v[202:205], v[72:75], 0
	v_mfma_f32_16x16x32_bf16 v[0:3], v[206:209], v[76:79], v[0:3]
	s_waitcnt lgkmcnt(0)
	s_add_i32 s93, s76, 0x200
	s_mov_b32 m0, s13
	v_add_u32_e32 v164, s93, v231
	v_med3_i32 v164, v164, 0, s40
	v_lshl_or_b32 v164, v164, 7, v220
	global_load_lds_dwordx4 v164, s[20:21]
	s_add_i32 m0, s13, 0x400
	v_add_u32_e32 v165, s93, v232
	v_med3_i32 v165, v165, 0, s40
	v_lshl_or_b32 v165, v165, 7, v221
	global_load_lds_dwordx4 v165, s[20:21]
	s_waitcnt vmcnt(8)
	v_add_u32_e32 v154, s14, v223
	v_add_u32_e32 v155, s14, v224
	ds_read_b128 v[202:205], v154
	ds_read_b128 v[206:209], v155
	v_mfma_f32_16x16x32_bf16 v[4:7], v[88:91], v[72:75], 0
	v_mfma_f32_16x16x32_bf16 v[4:7], v[92:95], v[76:79], v[4:7]
	s_waitcnt lgkmcnt(0)
	s_add_i32 s93, s76, 0x300
	s_mov_b32 m0, s14
	v_add_u32_e32 v164, s93, v231
	v_med3_i32 v164, v164, 0, s40
	v_lshl_or_b32 v164, v164, 7, v220
	global_load_lds_dwordx4 v164, s[20:21]
	s_add_i32 m0, s14, 0x400
	v_add_u32_e32 v165, s93, v232
	v_med3_i32 v165, v165, 0, s40
	v_lshl_or_b32 v165, v165, 7, v221
	global_load_lds_dwordx4 v165, s[20:21]
	s_waitcnt vmcnt(8)
	v_add_u32_e32 v154, s15, v223
	v_add_u32_e32 v155, s15, v224
	ds_read_b128 v[88:91], v154
	ds_read_b128 v[92:95], v155
	v_mfma_f32_16x16x32_bf16 v[8:11], v[202:205], v[72:75], 0
	v_mfma_f32_16x16x32_bf16 v[8:11], v[206:209], v[76:79], v[8:11]
	s_waitcnt lgkmcnt(0)
	s_add_i32 s93, s76, 0x400
	s_mov_b32 m0, s15
	v_add_u32_e32 v164, s93, v231
	v_med3_i32 v164, v164, 0, s40
	v_lshl_or_b32 v164, v164, 7, v220
	global_load_lds_dwordx4 v164, s[20:21]
	s_add_i32 m0, s15, 0x400
	v_add_u32_e32 v165, s93, v232
	v_med3_i32 v165, v165, 0, s40
	v_lshl_or_b32 v165, v165, 7, v221
	global_load_lds_dwordx4 v165, s[20:21]
	s_waitcnt vmcnt(8)
	v_add_u32_e32 v154, s16, v223
	v_add_u32_e32 v155, s16, v224
	ds_read_b128 v[202:205], v154
	ds_read_b128 v[206:209], v155
	v_mfma_f32_16x16x32_bf16 v[12:15], v[88:91], v[72:75], 0
	v_mfma_f32_16x16x32_bf16 v[12:15], v[92:95], v[76:79], v[12:15]
	s_waitcnt lgkmcnt(0)
	s_add_i32 s93, s8, 0
	s_mov_b32 m0, s16
	v_add_u32_e32 v164, s93, v231
	v_lshl_or_b32 v164, v164, 7, v220
	global_load_lds_dwordx4 v164, s[18:19]
	s_add_i32 m0, s16, 0x400
	v_add_u32_e32 v165, s93, v232
	v_lshl_or_b32 v165, v165, 7, v221
	global_load_lds_dwordx4 v165, s[18:19]
	s_waitcnt vmcnt(8)
	v_add_u32_e32 v154, s12, v223
	v_add_u32_e32 v155, s12, v224
	ds_read_b128 v[88:91], v154
	ds_read_b128 v[92:95], v155
	v_mfma_f32_16x16x32_bf16 v[16:19], v[202:205], v[72:75], 0
	v_mfma_f32_16x16x32_bf16 v[16:19], v[206:209], v[76:79], v[16:19]
	s_waitcnt lgkmcnt(0)
	s_add_i32 s93, s8, 0xfffffc00
	s_mov_b32 m0, s12
	v_add_u32_e32 v164, s93, v231
	v_med3_i32 v164, v164, 0, s40
	v_lshl_or_b32 v164, v164, 7, v220
	global_load_lds_dwordx4 v164, s[20:21]
	s_add_i32 m0, s12, 0x400
	v_add_u32_e32 v165, s93, v232
	v_med3_i32 v165, v165, 0, s40
	v_lshl_or_b32 v165, v165, 7, v221
	global_load_lds_dwordx4 v165, s[20:21]
	s_waitcnt vmcnt(8)
	v_add_u32_e32 v154, s13, v223
	v_add_u32_e32 v155, s13, v224
	ds_read_b128 v[202:205], v154
	ds_read_b128 v[206:209], v155
	v_mfma_f32_16x16x32_bf16 v[20:23], v[88:91], v[72:75], 0
	v_mfma_f32_16x16x32_bf16 v[20:23], v[92:95], v[76:79], v[20:23]
	s_waitcnt lgkmcnt(0)
	s_add_i32 s93, s8, 0xfffffd00
	s_mov_b32 m0, s13
	v_add_u32_e32 v164, s93, v231
	v_med3_i32 v164, v164, 0, s40
	v_lshl_or_b32 v164, v164, 7, v220
	global_load_lds_dwordx4 v164, s[20:21]
	s_add_i32 m0, s13, 0x400
	v_add_u32_e32 v165, s93, v232
	v_med3_i32 v165, v165, 0, s40
	v_lshl_or_b32 v165, v165, 7, v221
	global_load_lds_dwordx4 v165, s[20:21]
	s_waitcnt vmcnt(8)
	v_add_u32_e32 v154, s14, v223
	v_add_u32_e32 v155, s14, v224
	ds_read_b128 v[88:91], v154
	ds_read_b128 v[92:95], v155
	v_mfma_f32_16x16x32_bf16 v[24:27], v[202:205], v[72:75], 0
	v_mfma_f32_16x16x32_bf16 v[24:27], v[206:209], v[76:79], v[24:27]
	s_waitcnt lgkmcnt(0)
	s_add_i32 s93, s8, 0xfffffe00
	s_mov_b32 m0, s14
	v_add_u32_e32 v164, s93, v231
	v_med3_i32 v164, v164, 0, s40
	v_lshl_or_b32 v164, v164, 7, v220
	global_load_lds_dwordx4 v164, s[20:21]
	s_add_i32 m0, s14, 0x400
	v_add_u32_e32 v165, s93, v232
	v_med3_i32 v165, v165, 0, s40
	v_lshl_or_b32 v165, v165, 7, v221
	global_load_lds_dwordx4 v165, s[20:21]
	s_waitcnt vmcnt(8)
	v_add_u32_e32 v154, s15, v223
	v_add_u32_e32 v155, s15, v224
	ds_read_b128 v[202:205], v154
	ds_read_b128 v[206:209], v155
	v_mfma_f32_16x16x32_bf16 v[28:31], v[88:91], v[72:75], 0
	v_mfma_f32_16x16x32_bf16 v[28:31], v[92:95], v[76:79], v[28:31]
	s_waitcnt lgkmcnt(0)
	s_add_i32 s93, s8, 0xffffff00
	s_mov_b32 m0, s15
	v_add_u32_e32 v164, s93, v231
	v_med3_i32 v164, v164, 0, s40
	v_lshl_or_b32 v164, v164, 7, v220
	global_load_lds_dwordx4 v164, s[20:21]
	s_add_i32 m0, s15, 0x400
	v_add_u32_e32 v165, s93, v232
	v_med3_i32 v165, v165, 0, s40
	v_lshl_or_b32 v165, v165, 7, v221
	global_load_lds_dwordx4 v165, s[20:21]
	s_waitcnt vmcnt(8)
	v_add_u32_e32 v154, s16, v223
	v_add_u32_e32 v155, s16, v224
	ds_read_b128 v[80:83], v154
	ds_read_b128 v[84:87], v155
	v_mfma_f32_16x16x32_bf16 v[32:35], v[202:205], v[72:75], 0
	v_mfma_f32_16x16x32_bf16 v[32:35], v[206:209], v[76:79], v[32:35]
	s_waitcnt lgkmcnt(0)
	s_add_i32 s93, s8, 0
	s_mov_b32 m0, s16
	v_add_u32_e32 v164, s93, v231
	v_med3_i32 v164, v164, 0, s40
	v_lshl_or_b32 v164, v164, 7, v220
	global_load_lds_dwordx4 v164, s[20:21]
	s_add_i32 m0, s16, 0x400
	v_add_u32_e32 v165, s93, v232
	v_med3_i32 v165, v165, 0, s40
	v_lshl_or_b32 v165, v165, 7, v221
	global_load_lds_dwordx4 v165, s[20:21]
	s_waitcnt vmcnt(8)
	v_add_u32_e32 v154, s12, v223
	v_add_u32_e32 v155, s12, v224
	ds_read_b128 v[202:205], v154
	ds_read_b128 v[206:209], v155
	v_mov_b32_e32 v188, s84
	v_lshl_add_u32 v188, v216, 4, v188
	v_lshrrev_b32_e32 v146, 4, v188
	v_xor_b32_e32 v146, v146, v188
	v_and_b32_e32 v146, 15, v146
	v_lshlrev_b32_e32 v147, 8, v188
	v_or_b32_e32 v148, 0, v217
	v_xor_b32_e32 v148, v148, v146
	v_lshl_add_u32 v190, v148, 4, v147
	v_or_b32_e32 v148, 4, v217
	v_xor_b32_e32 v148, v148, v146
	v_lshl_add_u32 v191, v148, 4, v147
	v_or_b32_e32 v148, 8, v217
	v_xor_b32_e32 v148, v148, v146
	v_lshl_add_u32 v192, v148, 4, v147
	v_or_b32_e32 v148, 12, v217
	v_xor_b32_e32 v148, v148, v146
	v_lshl_add_u32 v193, v148, 4, v147
	v_lshlrev_b32_e32 v194, 3, v188
	v_add_u32_e32 v194, 0x10000, v194
	ds_read_b64 v[144:145], v194
	ds_read_b128 v[128:131], v190
	ds_read_b128 v[132:135], v191
	ds_read_b128 v[136:139], v192
	ds_read_b128 v[140:143], v193
	s_ashr_i32 s77, s76, 4
	s_sub_i32 s77, 64, s77
	s_sub_i32 s78, s40, s76
	s_waitcnt lgkmcnt(0)
	s_add_i32 s93, s8, 0x100
	s_mov_b32 m0, s12
	v_add_u32_e32 v164, s93, v231
	v_med3_i32 v164, v164, 0, s40
	v_lshl_or_b32 v164, v164, 7, v220
	global_load_lds_dwordx4 v164, s[20:21]
	s_add_i32 m0, s12, 0x400
	v_add_u32_e32 v165, s93, v232
	v_med3_i32 v165, v165, 0, s40
	v_lshl_or_b32 v165, v165, 7, v221
	global_load_lds_dwordx4 v165, s[20:21]
	s_waitcnt vmcnt(8)
	v_add_u32_e32 v154, s13, v223
	v_add_u32_e32 v155, s13, v224
	ds_read_b128 v[88:91], v154
	ds_read_b128 v[92:95], v155
	v_mfma_f32_16x16x32_bf16 v[36:39], v[202:205], v[80:83], 0
	v_mfma_f32_16x16x32_bf16 v[36:39], v[206:209], v[84:87], v[36:39]
	s_ashr_i32 s78, s78, 4
	s_add_i32 s78, s78, 64
	v_cndmask_b32_e64 v0, v0, v230, s[52:53]
	v_cndmask_b32_e64 v32, v32, v230, s[62:63]
	v_cndmask_b32_e64 v1, v1, v230, s[56:57]
	v_cndmask_b32_e64 v33, v33, v230, s[64:65]
	v_cndmask_b32_e64 v2, v2, v230, s[58:59]
	v_cndmask_b32_e64 v34, v34, v230, s[70:71]
	v_cndmask_b32_e64 v3, v3, v230, s[60:61]
	v_cndmask_b32_e64 v35, v35, v230, s[72:73]
	v_sub_u32_e32 v200, s77, v229
	s_sub_i32 s91, s78, s77
	v_sub_u32_e32 v150, 0, v200
	v_sub_u32_e32 v151, 1, v200
	v_sub_u32_e32 v152, 2, v200
	v_sub_u32_e32 v153, 3, v200
	v_cmp_lt_u32_e64 s[94:95], s91, v150
	v_cmp_lt_u32_e64 s[86:87], s91, v151
	v_cmp_lt_u32_e64 s[0:1], s91, v152
	v_cmp_lt_u32_e64 s[2:3], s91, v153
	v_cndmask_b32_e64 v0, v0, v230, s[94:95]
	v_cndmask_b32_e64 v1, v1, v230, s[86:87]
	v_cndmask_b32_e64 v2, v2, v230, s[0:1]
	v_cndmask_b32_e64 v3, v3, v230, s[2:3]
	v_sub_u32_e32 v150, 16, v200
	v_sub_u32_e32 v151, 17, v200
	v_sub_u32_e32 v152, 18, v200
	v_sub_u32_e32 v153, 19, v200
	s_waitcnt lgkmcnt(0)
	s_add_i32 s93, s8, 0x200
	s_mov_b32 m0, s13
	v_add_u32_e32 v164, s93, v231
	v_med3_i32 v164, v164, 0, s40
	v_lshl_or_b32 v164, v164, 7, v220
	global_load_lds_dwordx4 v164, s[20:21]
	s_add_i32 m0, s13, 0x400
	v_add_u32_e32 v165, s93, v232
	v_med3_i32 v165, v165, 0, s40
	v_lshl_or_b32 v165, v165, 7, v221
	global_load_lds_dwordx4 v165, s[20:21]
	s_waitcnt vmcnt(8)
	v_add_u32_e32 v154, s14, v223
	v_add_u32_e32 v155, s14, v224
	ds_read_b128 v[202:205], v154
	ds_read_b128 v[206:209], v155
	v_mfma_f32_16x16x32_bf16 v[40:43], v[88:91], v[80:83], 0
	v_mfma_f32_16x16x32_bf16 v[40:43], v[92:95], v[84:87], v[40:43]
	v_cmp_lt_u32_e64 s[94:95], s91, v150
	v_cmp_lt_u32_e64 s[86:87], s91, v151
	v_cmp_lt_u32_e64 s[0:1], s91, v152
	v_cmp_lt_u32_e64 s[2:3], s91, v153
	v_cndmask_b32_e64 v4, v4, v230, s[94:95]
	v_cndmask_b32_e64 v5, v5, v230, s[86:87]
	v_cndmask_b32_e64 v6, v6, v230, s[0:1]
	v_cndmask_b32_e64 v7, v7, v230, s[2:3]
	v_sub_u32_e32 v150, 32, v200
	v_sub_u32_e32 v151, 33, v200
	v_sub_u32_e32 v152, 34, v200
	v_sub_u32_e32 v153, 35, v200
	v_cmp_lt_u32_e64 s[94:95], s91, v150
	v_cmp_lt_u32_e64 s[86:87], s91, v151
	v_cmp_lt_u32_e64 s[0:1], s91, v152
	v_cmp_lt_u32_e64 s[2:3], s91, v153
	v_cndmask_b32_e64 v8, v8, v230, s[94:95]
	v_cndmask_b32_e64 v9, v9, v230, s[86:87]
	v_cndmask_b32_e64 v10, v10, v230, s[0:1]
	v_cndmask_b32_e64 v11, v11, v230, s[2:3]
	v_sub_u32_e32 v150, 48, v200
	v_sub_u32_e32 v151, 49, v200
	v_sub_u32_e32 v152, 50, v200
	v_sub_u32_e32 v153, 51, v200
	v_cmp_lt_u32_e64 s[94:95], s91, v150
	v_cmp_lt_u32_e64 s[86:87], s91, v151
	v_cmp_lt_u32_e64 s[0:1], s91, v152
	v_cmp_lt_u32_e64 s[2:3], s91, v153
	s_waitcnt lgkmcnt(0)
	s_add_i32 s93, s8, 0x300
	s_mov_b32 m0, s14
	v_add_u32_e32 v164, s93, v231
	v_med3_i32 v164, v164, 0, s40
	v_lshl_or_b32 v164, v164, 7, v220
	global_load_lds_dwordx4 v164, s[20:21]
	s_add_i32 m0, s14, 0x400
	v_add_u32_e32 v165, s93, v232
	v_med3_i32 v165, v165, 0, s40
	v_lshl_or_b32 v165, v165, 7, v221
	global_load_lds_dwordx4 v165, s[20:21]
	s_waitcnt vmcnt(8)
	v_add_u32_e32 v154, s15, v223
	v_add_u32_e32 v155, s15, v224
	ds_read_b128 v[88:91], v154
	ds_read_b128 v[92:95], v155
	v_mfma_f32_16x16x32_bf16 v[44:47], v[202:205], v[80:83], 0
	v_mfma_f32_16x16x32_bf16 v[44:47], v[206:209], v[84:87], v[44:47]
	v_cndmask_b32_e64 v12, v12, v230, s[94:95]
	v_cndmask_b32_e64 v13, v13, v230, s[86:87]
	v_cndmask_b32_e64 v14, v14, v230, s[0:1]
	v_cndmask_b32_e64 v15, v15, v230, s[2:3]
	v_sub_u32_e32 v150, 64, v200
	v_sub_u32_e32 v151, 0x41, v200
	v_sub_u32_e32 v152, 0x42, v200
	v_sub_u32_e32 v153, 0x43, v200
	v_cmp_lt_u32_e64 s[94:95], s91, v150
	v_cmp_lt_u32_e64 s[86:87], s91, v151
	v_cmp_lt_u32_e64 s[0:1], s91, v152
	v_cmp_lt_u32_e64 s[2:3], s91, v153
	v_cndmask_b32_e64 v16, v16, v230, s[94:95]
	v_cndmask_b32_e64 v17, v17, v230, s[86:87]
	v_cndmask_b32_e64 v18, v18, v230, s[0:1]
	v_cndmask_b32_e64 v19, v19, v230, s[2:3]
	v_sub_u32_e32 v150, 0x50, v200
	v_sub_u32_e32 v151, 0x51, v200
	v_sub_u32_e32 v152, 0x52, v200
	v_sub_u32_e32 v153, 0x53, v200
	v_cmp_lt_u32_e64 s[94:95], s91, v150
	v_cmp_lt_u32_e64 s[86:87], s91, v151
	v_cmp_lt_u32_e64 s[0:1], s91, v152
	v_cmp_lt_u32_e64 s[2:3], s91, v153
	v_cndmask_b32_e64 v20, v20, v230, s[94:95]
	v_cndmask_b32_e64 v21, v21, v230, s[86:87]
	v_cndmask_b32_e64 v22, v22, v230, s[0:1]
	v_cndmask_b32_e64 v23, v23, v230, s[2:3]
	s_waitcnt lgkmcnt(0)
	s_add_i32 s93, s8, 0x400
	s_mov_b32 m0, s15
	v_add_u32_e32 v164, s93, v231
	v_med3_i32 v164, v164, 0, s40
	v_lshl_or_b32 v164, v164, 7, v220
	global_load_lds_dwordx4 v164, s[20:21]
	s_add_i32 m0, s15, 0x400
	v_add_u32_e32 v165, s93, v232
	v_med3_i32 v165, v165, 0, s40
	v_lshl_or_b32 v165, v165, 7, v221
	global_load_lds_dwordx4 v165, s[20:21]
	s_waitcnt vmcnt(8)
	v_add_u32_e32 v154, s16, v223
	v_add_u32_e32 v155, s16, v224
	ds_read_b128 v[202:205], v154
	ds_read_b128 v[206:209], v155
	v_mfma_f32_16x16x32_bf16 v[48:51], v[88:91], v[80:83], 0
	v_mfma_f32_16x16x32_bf16 v[48:51], v[92:95], v[84:87], v[48:51]
	v_sub_u32_e32 v150, 0x60, v200
	v_sub_u32_e32 v151, 0x61, v200
	v_sub_u32_e32 v152, 0x62, v200
	v_sub_u32_e32 v153, 0x63, v200
	v_cmp_lt_u32_e64 s[94:95], s91, v150
	v_cmp_lt_u32_e64 s[86:87], s91, v151
	v_cmp_lt_u32_e64 s[0:1], s91, v152
	v_cmp_lt_u32_e64 s[2:3], s91, v153
	v_cndmask_b32_e64 v24, v24, v230, s[94:95]
	v_cndmask_b32_e64 v25, v25, v230, s[86:87]
	v_cndmask_b32_e64 v26, v26, v230, s[0:1]
	v_cndmask_b32_e64 v27, v27, v230, s[2:3]
	v_sub_u32_e32 v150, 0x70, v200
	v_sub_u32_e32 v151, 0x71, v200
	v_sub_u32_e32 v152, 0x72, v200
	v_sub_u32_e32 v153, 0x73, v200
	v_cmp_lt_u32_e64 s[94:95], s91, v150
	v_cmp_lt_u32_e64 s[86:87], s91, v151
	v_cmp_lt_u32_e64 s[0:1], s91, v152
	v_cmp_lt_u32_e64 s[2:3], s91, v153
	v_cndmask_b32_e64 v28, v28, v230, s[94:95]
	v_cndmask_b32_e64 v29, v29, v230, s[86:87]
	v_cndmask_b32_e64 v30, v30, v230, s[0:1]
	v_cndmask_b32_e64 v31, v31, v230, s[2:3]
	v_sub_u32_e32 v150, 0x80, v200
	v_sub_u32_e32 v151, 0x81, v200
	v_sub_u32_e32 v152, 0x82, v200
	v_sub_u32_e32 v153, 0x83, v200
	s_waitcnt lgkmcnt(0)
	s_add_i32 s93, s76, 0xfffffc00
	s_mov_b32 m0, s16
	v_add_u32_e32 v164, s93, v231
	v_med3_i32 v164, v164, 0, s40
	v_lshl_or_b32 v164, v164, 7, v222
	global_load_lds_dwordx4 v164, s[24:25]
	s_add_i32 m0, s16, 0x400
	v_add_u32_e32 v165, s93, v232
	v_med3_i32 v165, v165, 0, s40
	v_lshl_or_b32 v165, v165, 7, v222
	global_load_lds_dwordx4 v165, s[24:25]
	s_waitcnt vmcnt(8)
	v_add_u32_e32 v154, s12, v223
	v_add_u32_e32 v155, s12, v224
	ds_read_b128 v[88:91], v154
	ds_read_b128 v[92:95], v155
	v_mfma_f32_16x16x32_bf16 v[52:55], v[202:205], v[80:83], 0
	v_mfma_f32_16x16x32_bf16 v[52:55], v[206:209], v[84:87], v[52:55]
	v_cmp_lt_u32_e64 s[94:95], s91, v150
	v_cmp_lt_u32_e64 s[86:87], s91, v151
	v_cmp_lt_u32_e64 s[0:1], s91, v152
	v_cmp_lt_u32_e64 s[2:3], s91, v153
	v_cndmask_b32_e64 v32, v32, v230, s[94:95]
	v_cndmask_b32_e64 v33, v33, v230, s[86:87]
	v_cndmask_b32_e64 v34, v34, v230, s[0:1]
	v_cndmask_b32_e64 v35, v35, v230, s[2:3]
	v_max3_f32 v184, v0, v1, v2
	v_max3_f32 v184, v184, v3, v4
	v_max3_f32 v184, v184, v5, v6
	v_max3_f32 v184, v184, v7, v8
	v_max3_f32 v184, v184, v9, v10
	v_max3_f32 v184, v184, v11, v12
	v_max3_f32 v184, v184, v13, v14
	v_max3_f32 v184, v184, v15, v16
	v_max3_f32 v184, v184, v17, v18
	v_max3_f32 v184, v184, v19, v20
	v_max3_f32 v184, v184, v21, v22
	v_max3_f32 v184, v184, v23, v24
	v_max3_f32 v184, v184, v25, v26
	v_max3_f32 v184, v184, v27, v28
	v_max3_f32 v184, v184, v29, v30
	v_max3_f32 v184, v184, v31, v32
	v_max3_f32 v184, v184, v33, v34
	v_max_f32_e32 v184, v184, v35
	v_mov_b32_e32 v146, v184
	s_nop 1
	v_permlane16_swap_b32_e32 v184, v146
	s_waitcnt lgkmcnt(0)
	s_add_i32 s93, s76, 0xfffffd00
	s_mov_b32 m0, s12
	v_add_u32_e32 v164, s93, v231
	v_med3_i32 v164, v164, 0, s40
	v_lshl_or_b32 v164, v164, 7, v222
	global_load_lds_dwordx4 v164, s[24:25]
	s_add_i32 m0, s12, 0x400
	v_add_u32_e32 v165, s93, v232
	v_med3_i32 v165, v165, 0, s40
	v_lshl_or_b32 v165, v165, 7, v222
	global_load_lds_dwordx4 v165, s[24:25]
	s_waitcnt vmcnt(8)
	v_add_u32_e32 v154, s13, v223
	v_add_u32_e32 v155, s13, v224
	ds_read_b128 v[202:205], v154
	ds_read_b128 v[206:209], v155
	v_mfma_f32_16x16x32_bf16 v[56:59], v[88:91], v[80:83], 0
	v_mfma_f32_16x16x32_bf16 v[56:59], v[92:95], v[84:87], v[56:59]
	v_max_f32_e32 v184, v184, v146
	v_mov_b32_e32 v146, v184
	s_nop 1
	v_permlane32_swap_b32_e32 v184, v146
	v_max_f32_e32 v184, v184, v146
	v_pk_add_f32 v[0:1], v[0:1], v[184:185] op_sel_hi:[1,0] neg_lo:[0,1] neg_hi:[0,1]
	v_pk_add_f32 v[2:3], v[2:3], v[184:185] op_sel_hi:[1,0] neg_lo:[0,1] neg_hi:[0,1]
	v_pk_add_f32 v[4:5], v[4:5], v[184:185] op_sel_hi:[1,0] neg_lo:[0,1] neg_hi:[0,1]
	v_pk_add_f32 v[6:7], v[6:7], v[184:185] op_sel_hi:[1,0] neg_lo:[0,1] neg_hi:[0,1]
	v_exp_f32_e32 v0, v0
	v_exp_f32_e32 v1, v1
	v_exp_f32_e32 v2, v2
	v_exp_f32_e32 v3, v3
	v_pk_add_f32 v[8:9], v[8:9], v[184:185] op_sel_hi:[1,0] neg_lo:[0,1] neg_hi:[0,1]
	v_pk_add_f32 v[10:11], v[10:11], v[184:185] op_sel_hi:[1,0] neg_lo:[0,1] neg_hi:[0,1]
	v_exp_f32_e32 v4, v4
	v_exp_f32_e32 v5, v5
	v_exp_f32_e32 v6, v6
	v_exp_f32_e32 v7, v7
	v_pk_add_f32 v[12:13], v[12:13], v[184:185] op_sel_hi:[1,0] neg_lo:[0,1] neg_hi:[0,1]
	v_pk_add_f32 v[14:15], v[14:15], v[184:185] op_sel_hi:[1,0] neg_lo:[0,1] neg_hi:[0,1]
	v_exp_f32_e32 v8, v8
	v_exp_f32_e32 v9, v9
	v_exp_f32_e32 v10, v10
	v_exp_f32_e32 v11, v11
	v_pk_add_f32 v[16:17], v[16:17], v[184:185] op_sel_hi:[1,0] neg_lo:[0,1] neg_hi:[0,1]
	v_pk_add_f32 v[18:19], v[18:19], v[184:185] op_sel_hi:[1,0] neg_lo:[0,1] neg_hi:[0,1]
	v_exp_f32_e32 v12, v12
	v_exp_f32_e32 v13, v13
	s_waitcnt lgkmcnt(0)
	s_add_i32 s93, s76, 0xfffffe00
	s_mov_b32 m0, s13
	v_add_u32_e32 v164, s93, v231
	v_med3_i32 v164, v164, 0, s40
	v_lshl_or_b32 v164, v164, 7, v222
	global_load_lds_dwordx4 v164, s[24:25]
	s_add_i32 m0, s13, 0x400
	v_add_u32_e32 v165, s93, v232
	v_med3_i32 v165, v165, 0, s40
	v_lshl_or_b32 v165, v165, 7, v222
	global_load_lds_dwordx4 v165, s[24:25]
	s_waitcnt vmcnt(8)
	v_add_u32_e32 v154, s14, v223
	v_add_u32_e32 v155, s14, v224
	ds_read_b128 v[88:91], v154
	ds_read_b128 v[92:95], v155
	v_mfma_f32_16x16x32_bf16 v[60:63], v[202:205], v[80:83], 0
	v_mfma_f32_16x16x32_bf16 v[60:63], v[206:209], v[84:87], v[60:63]
	v_exp_f32_e32 v14, v14
	v_exp_f32_e32 v15, v15
	v_pk_add_f32 v[20:21], v[20:21], v[184:185] op_sel_hi:[1,0] neg_lo:[0,1] neg_hi:[0,1]
	v_pk_add_f32 v[22:23], v[22:23], v[184:185] op_sel_hi:[1,0] neg_lo:[0,1] neg_hi:[0,1]
	v_exp_f32_e32 v16, v16
	v_exp_f32_e32 v17, v17
	v_exp_f32_e32 v18, v18
	v_exp_f32_e32 v19, v19
	v_pk_add_f32 v[24:25], v[24:25], v[184:185] op_sel_hi:[1,0] neg_lo:[0,1] neg_hi:[0,1]
	v_pk_add_f32 v[26:27], v[26:27], v[184:185] op_sel_hi:[1,0] neg_lo:[0,1] neg_hi:[0,1]
	v_exp_f32_e32 v20, v20
	v_exp_f32_e32 v21, v21
	v_exp_f32_e32 v22, v22
	v_exp_f32_e32 v23, v23
	v_pk_add_f32 v[28:29], v[28:29], v[184:185] op_sel_hi:[1,0] neg_lo:[0,1] neg_hi:[0,1]
	v_pk_add_f32 v[30:31], v[30:31], v[184:185] op_sel_hi:[1,0] neg_lo:[0,1] neg_hi:[0,1]
	v_exp_f32_e32 v24, v24
	v_exp_f32_e32 v25, v25
	v_exp_f32_e32 v26, v26
	v_exp_f32_e32 v27, v27
	v_pk_add_f32 v[32:33], v[32:33], v[184:185] op_sel_hi:[1,0] neg_lo:[0,1] neg_hi:[0,1]
	v_pk_add_f32 v[34:35], v[34:35], v[184:185] op_sel_hi:[1,0] neg_lo:[0,1] neg_hi:[0,1]
	v_exp_f32_e32 v28, v28
	v_exp_f32_e32 v29, v29
	v_exp_f32_e32 v30, v30
	v_exp_f32_e32 v31, v31
	v_exp_f32_e32 v32, v32
	v_exp_f32_e32 v33, v33
	s_waitcnt lgkmcnt(0)
	s_add_i32 s93, s76, 0xffffff00
	s_mov_b32 m0, s14
	v_add_u32_e32 v164, s93, v231
	v_med3_i32 v164, v164, 0, s40
	v_lshl_or_b32 v164, v164, 7, v222
	global_load_lds_dwordx4 v164, s[24:25]
	s_add_i32 m0, s14, 0x400
	v_add_u32_e32 v165, s93, v232
	v_med3_i32 v165, v165, 0, s40
	v_lshl_or_b32 v165, v165, 7, v222
	global_load_lds_dwordx4 v165, s[24:25]
	s_waitcnt vmcnt(8)
	v_add_u32_e32 v154, s15, v223
	v_add_u32_e32 v155, s15, v224
	ds_read_b128 v[202:205], v154
	ds_read_b128 v[206:209], v155
	v_mfma_f32_16x16x32_bf16 v[64:67], v[88:91], v[80:83], 0
	v_mfma_f32_16x16x32_bf16 v[64:67], v[92:95], v[84:87], v[64:67]
	v_exp_f32_e32 v34, v34
	v_exp_f32_e32 v35, v35
	s_nop 0
	v_pk_add_f32 v[146:147], v[0:1], v[2:3]
	v_pk_add_f32 v[148:149], v[4:5], v[6:7]
	v_pk_add_f32 v[146:147], v[146:147], v[8:9]
	v_pk_add_f32 v[148:149], v[148:149], v[10:11]
	v_pk_add_f32 v[146:147], v[146:147], v[12:13]
	v_pk_add_f32 v[148:149], v[148:149], v[14:15]
	v_pk_add_f32 v[146:147], v[146:147], v[16:17]
	v_pk_add_f32 v[148:149], v[148:149], v[18:19]
	v_pk_add_f32 v[146:147], v[146:147], v[20:21]
	v_pk_add_f32 v[148:149], v[148:149], v[22:23]
	v_pk_add_f32 v[146:147], v[146:147], v[24:25]
	v_pk_add_f32 v[148:149], v[148:149], v[26:27]
	v_pk_add_f32 v[146:147], v[146:147], v[28:29]
	v_pk_add_f32 v[148:149], v[148:149], v[30:31]
	v_pk_add_f32 v[146:147], v[146:147], v[32:33]
	v_pk_add_f32 v[148:149], v[148:149], v[34:35]
	s_nop 0
	v_pk_add_f32 v[146:147], v[146:147], v[148:149]
	s_nop 0
	v_add_f32_e32 v185, v146, v147
	v_cvt_pk_bf16_f32 v0, v0, v1
	v_cvt_pk_bf16_f32 v1, v2, v3
	v_cvt_pk_bf16_f32 v4, v4, v5
	v_cvt_pk_bf16_f32 v5, v6, v7
	v_cvt_pk_bf16_f32 v8, v8, v9
	s_waitcnt lgkmcnt(0)
	s_add_i32 s93, s76, 0
	s_mov_b32 m0, s15
	v_add_u32_e32 v164, s93, v231
	v_med3_i32 v164, v164, 0, s40
	v_lshl_or_b32 v164, v164, 7, v222
	global_load_lds_dwordx4 v164, s[24:25]
	s_add_i32 m0, s15, 0x400
	v_add_u32_e32 v165, s93, v232
	v_med3_i32 v165, v165, 0, s40
	v_lshl_or_b32 v165, v165, 7, v222
	global_load_lds_dwordx4 v165, s[24:25]
	s_waitcnt vmcnt(8)
	v_add_u32_e32 v154, s16, v225
	v_add_u32_e32 v155, s16, v226
	v_add_u32_e32 v156, s16, v227
	v_add_u32_e32 v157, s16, v228
	ds_read_b64_tr_b16 v[88:89], v154
	ds_read_b64_tr_b16 v[90:91], v155
	ds_read_b64_tr_b16 v[92:93], v156
	ds_read_b64_tr_b16 v[94:95], v157
	v_mfma_f32_16x16x32_bf16 v[68:71], v[202:205], v[80:83], 0
	v_mfma_f32_16x16x32_bf16 v[68:71], v[206:209], v[84:87], v[68:71]
	v_cvt_pk_bf16_f32 v9, v10, v11
	v_cvt_pk_bf16_f32 v12, v12, v13
	v_cvt_pk_bf16_f32 v13, v14, v15
	v_cvt_pk_bf16_f32 v16, v16, v17
	v_cvt_pk_bf16_f32 v17, v18, v19
	v_cvt_pk_bf16_f32 v20, v20, v21
	v_cvt_pk_bf16_f32 v21, v22, v23
	v_cvt_pk_bf16_f32 v24, v24, v25
	v_cvt_pk_bf16_f32 v25, v26, v27
	v_cvt_pk_bf16_f32 v28, v28, v29
	v_cvt_pk_bf16_f32 v29, v30, v31
	v_cvt_pk_bf16_f32 v32, v32, v33
	v_cvt_pk_bf16_f32 v33, v34, v35
	v_mov_b32_e32 v146, v185
	s_nop 1
	v_permlane16_swap_b32_e32 v185, v146
	v_add_f32_e32 v185, v185, v146
	v_mov_b32_e32 v146, v185
	s_nop 1
	v_permlane32_swap_b32_e32 v185, v146
	v_add_f32_e32 v185, v185, v146
	s_waitcnt lgkmcnt(0)
	s_add_i32 s93, s76, 0x100
	s_mov_b32 m0, s16
	v_add_u32_e32 v164, s93, v231
	v_med3_i32 v164, v164, 0, s40
	v_lshl_or_b32 v164, v164, 7, v222
	global_load_lds_dwordx4 v164, s[24:25]
	s_add_i32 m0, s16, 0x400
	v_add_u32_e32 v165, s93, v232
	v_med3_i32 v165, v165, 0, s40
	v_lshl_or_b32 v165, v165, 7, v222
	global_load_lds_dwordx4 v165, s[24:25]
	s_waitcnt vmcnt(8)
	v_add_u32_e32 v154, s12, v225
	v_add_u32_e32 v155, s12, v226
	v_add_u32_e32 v156, s12, v227
	v_add_u32_e32 v157, s12, v228
	ds_read_b64_tr_b16 v[202:203], v154
	ds_read_b64_tr_b16 v[204:205], v155
	ds_read_b64_tr_b16 v[206:207], v156
	ds_read_b64_tr_b16 v[208:209], v157
	v_mfma_f32_16x16x16_bf16 v[96:99], v[88:89], v[0:1], 0
	v_mfma_f32_16x16x16_bf16 v[100:103], v[90:91], v[0:1], 0
	v_mfma_f32_16x16x16_bf16 v[104:107], v[92:93], v[0:1], 0
	v_mfma_f32_16x16x16_bf16 v[108:111], v[94:95], v[0:1], 0
	v_mov_b32_e32 v189, s85
	v_lshl_add_u32 v189, v216, 4, v189
	v_lshrrev_b32_e32 v146, 4, v189
	v_xor_b32_e32 v146, v146, v189
	v_and_b32_e32 v146, 15, v146
	v_lshlrev_b32_e32 v147, 8, v189
	v_or_b32_e32 v148, 0, v217
	v_xor_b32_e32 v148, v148, v146
	v_lshl_add_u32 v195, v148, 4, v147
	v_or_b32_e32 v148, 4, v217
	v_xor_b32_e32 v148, v148, v146
	v_lshl_add_u32 v196, v148, 4, v147
	v_or_b32_e32 v148, 8, v217
	v_xor_b32_e32 v148, v148, v146
	v_lshl_add_u32 v197, v148, 4, v147
	v_or_b32_e32 v148, 12, v217
	v_xor_b32_e32 v148, v148, v146
	v_lshl_add_u32 v198, v148, 4, v147
	v_lshlrev_b32_e32 v199, 3, v189
	v_add_u32_e32 v199, 0x10000, v199
	ds_read_b64 v[182:183], v199
	ds_read_b128 v[166:169], v195
	ds_read_b128 v[170:173], v196
	ds_read_b128 v[174:177], v197
	ds_read_b128 v[178:181], v198
	s_ashr_i32 s77, s8, 4
	s_sub_i32 s77, 64, s77
	s_sub_i32 s78, s40, s8
	s_ashr_i32 s78, s78, 4
	s_add_i32 s78, s78, 64
	v_cndmask_b32_e64 v36, v36, v230, s[52:53]
	s_waitcnt lgkmcnt(0)
	s_add_i32 s93, s76, 0x200
	s_mov_b32 m0, s12
	v_add_u32_e32 v164, s93, v231
	v_med3_i32 v164, v164, 0, s40
	v_lshl_or_b32 v164, v164, 7, v222
	global_load_lds_dwordx4 v164, s[24:25]
	s_add_i32 m0, s12, 0x400
	v_add_u32_e32 v165, s93, v232
	v_med3_i32 v165, v165, 0, s40
	v_lshl_or_b32 v165, v165, 7, v222
	global_load_lds_dwordx4 v165, s[24:25]
	s_waitcnt vmcnt(8)
	v_add_u32_e32 v154, s13, v225
	v_add_u32_e32 v155, s13, v226
	v_add_u32_e32 v156, s13, v227
	v_add_u32_e32 v157, s13, v228
	ds_read_b64_tr_b16 v[88:89], v154
	ds_read_b64_tr_b16 v[90:91], v155
	ds_read_b64_tr_b16 v[92:93], v156
	ds_read_b64_tr_b16 v[94:95], v157
	v_mfma_f32_16x16x16_bf16 v[96:99], v[202:203], v[4:5], v[96:99]
	v_mfma_f32_16x16x16_bf16 v[100:103], v[204:205], v[4:5], v[100:103]
	v_mfma_f32_16x16x16_bf16 v[104:107], v[206:207], v[4:5], v[104:107]
	v_mfma_f32_16x16x16_bf16 v[108:111], v[208:209], v[4:5], v[108:111]
	v_cndmask_b32_e64 v68, v68, v230, s[62:63]
	v_cndmask_b32_e64 v37, v37, v230, s[56:57]
	v_cndmask_b32_e64 v69, v69, v230, s[64:65]
	v_cndmask_b32_e64 v38, v38, v230, s[58:59]
	v_cndmask_b32_e64 v70, v70, v230, s[70:71]
	v_cndmask_b32_e64 v39, v39, v230, s[60:61]
	v_cndmask_b32_e64 v71, v71, v230, s[72:73]
	v_sub_u32_e32 v200, s77, v229
	s_sub_i32 s91, s78, s77
	v_sub_u32_e32 v150, 0, v200
	v_sub_u32_e32 v151, 1, v200
	v_sub_u32_e32 v152, 2, v200
	v_sub_u32_e32 v153, 3, v200
	v_cmp_lt_u32_e64 s[94:95], s91, v150
	v_cmp_lt_u32_e64 s[86:87], s91, v151
	v_cmp_lt_u32_e64 s[0:1], s91, v152
	v_cmp_lt_u32_e64 s[2:3], s91, v153
	v_cndmask_b32_e64 v36, v36, v230, s[94:95]
	v_cndmask_b32_e64 v37, v37, v230, s[86:87]
	v_cndmask_b32_e64 v38, v38, v230, s[0:1]
	v_cndmask_b32_e64 v39, v39, v230, s[2:3]
	v_sub_u32_e32 v150, 16, v200
	v_sub_u32_e32 v151, 17, v200
	v_sub_u32_e32 v152, 18, v200
	v_sub_u32_e32 v153, 19, v200
	v_cmp_lt_u32_e64 s[94:95], s91, v150
	v_cmp_lt_u32_e64 s[86:87], s91, v151
	v_cmp_lt_u32_e64 s[0:1], s91, v152
	v_cmp_lt_u32_e64 s[2:3], s91, v153
	v_cndmask_b32_e64 v40, v40, v230, s[94:95]
	v_cndmask_b32_e64 v41, v41, v230, s[86:87]
	s_waitcnt lgkmcnt(0)
	s_add_i32 s93, s76, 0x300
	s_mov_b32 m0, s13
	v_add_u32_e32 v164, s93, v231
	v_med3_i32 v164, v164, 0, s40
	v_lshl_or_b32 v164, v164, 7, v222
	global_load_lds_dwordx4 v164, s[24:25]
	s_add_i32 m0, s13, 0x400
	v_add_u32_e32 v165, s93, v232
	v_med3_i32 v165, v165, 0, s40
	v_lshl_or_b32 v165, v165, 7, v222
	global_load_lds_dwordx4 v165, s[24:25]
	s_waitcnt vmcnt(8)
	v_add_u32_e32 v154, s14, v225
	v_add_u32_e32 v155, s14, v226
	v_add_u32_e32 v156, s14, v227
	v_add_u32_e32 v157, s14, v228
	ds_read_b64_tr_b16 v[202:203], v154
	ds_read_b64_tr_b16 v[204:205], v155
	ds_read_b64_tr_b16 v[206:207], v156
	ds_read_b64_tr_b16 v[208:209], v157
	v_mfma_f32_16x16x16_bf16 v[96:99], v[88:89], v[8:9], v[96:99]
	v_mfma_f32_16x16x16_bf16 v[100:103], v[90:91], v[8:9], v[100:103]
	v_mfma_f32_16x16x16_bf16 v[104:107], v[92:93], v[8:9], v[104:107]
	v_mfma_f32_16x16x16_bf16 v[108:111], v[94:95], v[8:9], v[108:111]
	v_cndmask_b32_e64 v42, v42, v230, s[0:1]
	v_cndmask_b32_e64 v43, v43, v230, s[2:3]
	v_sub_u32_e32 v150, 32, v200
	v_sub_u32_e32 v151, 33, v200
	v_sub_u32_e32 v152, 34, v200
	v_sub_u32_e32 v153, 35, v200
	v_cmp_lt_u32_e64 s[94:95], s91, v150
	v_cmp_lt_u32_e64 s[86:87], s91, v151
	v_cmp_lt_u32_e64 s[0:1], s91, v152
	v_cmp_lt_u32_e64 s[2:3], s91, v153
	v_cndmask_b32_e64 v44, v44, v230, s[94:95]
	v_cndmask_b32_e64 v45, v45, v230, s[86:87]
	v_cndmask_b32_e64 v46, v46, v230, s[0:1]
	v_cndmask_b32_e64 v47, v47, v230, s[2:3]
	v_sub_u32_e32 v150, 48, v200
	v_sub_u32_e32 v151, 49, v200
	v_sub_u32_e32 v152, 50, v200
	v_sub_u32_e32 v153, 51, v200
	v_cmp_lt_u32_e64 s[94:95], s91, v150
	v_cmp_lt_u32_e64 s[86:87], s91, v151
	v_cmp_lt_u32_e64 s[0:1], s91, v152
	v_cmp_lt_u32_e64 s[2:3], s91, v153
	v_cndmask_b32_e64 v48, v48, v230, s[94:95]
	v_cndmask_b32_e64 v49, v49, v230, s[86:87]
	v_cndmask_b32_e64 v50, v50, v230, s[0:1]
	v_cndmask_b32_e64 v51, v51, v230, s[2:3]
	v_sub_u32_e32 v150, 64, v200
	v_sub_u32_e32 v151, 0x41, v200
	v_sub_u32_e32 v152, 0x42, v200
	v_sub_u32_e32 v153, 0x43, v200
	v_cmp_lt_u32_e64 s[94:95], s91, v150
	s_waitcnt lgkmcnt(0)
	s_add_i32 s93, s76, 0x400
	s_mov_b32 m0, s14
	v_add_u32_e32 v164, s93, v231
	v_med3_i32 v164, v164, 0, s40
	v_lshl_or_b32 v164, v164, 7, v222
	global_load_lds_dwordx4 v164, s[24:25]
	s_add_i32 m0, s14, 0x400
	v_add_u32_e32 v165, s93, v232
	v_med3_i32 v165, v165, 0, s40
	v_lshl_or_b32 v165, v165, 7, v222
	global_load_lds_dwordx4 v165, s[24:25]
	s_waitcnt vmcnt(8)
	v_add_u32_e32 v154, s15, v225
	v_add_u32_e32 v155, s15, v226
	v_add_u32_e32 v156, s15, v227
	v_add_u32_e32 v157, s15, v228
	ds_read_b64_tr_b16 v[88:89], v154
	ds_read_b64_tr_b16 v[90:91], v155
	ds_read_b64_tr_b16 v[92:93], v156
	ds_read_b64_tr_b16 v[94:95], v157
	v_mfma_f32_16x16x16_bf16 v[96:99], v[202:203], v[12:13], v[96:99]
	v_mfma_f32_16x16x16_bf16 v[100:103], v[204:205], v[12:13], v[100:103]
	v_mfma_f32_16x16x16_bf16 v[104:107], v[206:207], v[12:13], v[104:107]
	v_mfma_f32_16x16x16_bf16 v[108:111], v[208:209], v[12:13], v[108:111]
	v_cmp_lt_u32_e64 s[86:87], s91, v151
	v_cmp_lt_u32_e64 s[0:1], s91, v152
	v_cmp_lt_u32_e64 s[2:3], s91, v153
	v_cndmask_b32_e64 v52, v52, v230, s[94:95]
	v_cndmask_b32_e64 v53, v53, v230, s[86:87]
	v_cndmask_b32_e64 v54, v54, v230, s[0:1]
	v_cndmask_b32_e64 v55, v55, v230, s[2:3]
	v_sub_u32_e32 v150, 0x50, v200
	v_sub_u32_e32 v151, 0x51, v200
	v_sub_u32_e32 v152, 0x52, v200
	v_sub_u32_e32 v153, 0x53, v200
	v_cmp_lt_u32_e64 s[94:95], s91, v150
	v_cmp_lt_u32_e64 s[86:87], s91, v151
	v_cmp_lt_u32_e64 s[0:1], s91, v152
	v_cmp_lt_u32_e64 s[2:3], s91, v153
	v_cndmask_b32_e64 v56, v56, v230, s[94:95]
	v_cndmask_b32_e64 v57, v57, v230, s[86:87]
	v_cndmask_b32_e64 v58, v58, v230, s[0:1]
	v_cndmask_b32_e64 v59, v59, v230, s[2:3]
	v_sub_u32_e32 v150, 0x60, v200
	v_sub_u32_e32 v151, 0x61, v200
	v_sub_u32_e32 v152, 0x62, v200
	v_sub_u32_e32 v153, 0x63, v200
	v_cmp_lt_u32_e64 s[94:95], s91, v150
	v_cmp_lt_u32_e64 s[86:87], s91, v151
	v_cmp_lt_u32_e64 s[0:1], s91, v152
	v_cmp_lt_u32_e64 s[2:3], s91, v153
	v_cndmask_b32_e64 v60, v60, v230, s[94:95]
	v_cndmask_b32_e64 v61, v61, v230, s[86:87]
	v_cndmask_b32_e64 v62, v62, v230, s[0:1]
	v_cndmask_b32_e64 v63, v63, v230, s[2:3]
	s_waitcnt lgkmcnt(0)
	s_add_i32 s93, s8, 0xfffffc00
	s_mov_b32 m0, s15
	v_add_u32_e32 v164, s93, v231
	v_med3_i32 v164, v164, 0, s40
	v_lshl_or_b32 v164, v164, 7, v222
	global_load_lds_dwordx4 v164, s[24:25]
	s_add_i32 m0, s15, 0x400
	v_add_u32_e32 v165, s93, v232
	v_med3_i32 v165, v165, 0, s40
	v_lshl_or_b32 v165, v165, 7, v222
	global_load_lds_dwordx4 v165, s[24:25]
	s_waitcnt vmcnt(8)
	v_add_u32_e32 v154, s16, v225
	v_add_u32_e32 v155, s16, v226
	v_add_u32_e32 v156, s16, v227
	v_add_u32_e32 v157, s16, v228
	ds_read_b64_tr_b16 v[202:203], v154
	ds_read_b64_tr_b16 v[204:205], v155
	ds_read_b64_tr_b16 v[206:207], v156
	ds_read_b64_tr_b16 v[208:209], v157
	v_mfma_f32_16x16x16_bf16 v[96:99], v[88:89], v[16:17], v[96:99]
	v_mfma_f32_16x16x16_bf16 v[100:103], v[90:91], v[16:17], v[100:103]
	v_mfma_f32_16x16x16_bf16 v[104:107], v[92:93], v[16:17], v[104:107]
	v_mfma_f32_16x16x16_bf16 v[108:111], v[94:95], v[16:17], v[108:111]
	v_sub_u32_e32 v150, 0x70, v200
	v_sub_u32_e32 v151, 0x71, v200
	v_sub_u32_e32 v152, 0x72, v200
	v_sub_u32_e32 v153, 0x73, v200
	v_cmp_lt_u32_e64 s[94:95], s91, v150
	v_cmp_lt_u32_e64 s[86:87], s91, v151
	v_cmp_lt_u32_e64 s[0:1], s91, v152
	v_cmp_lt_u32_e64 s[2:3], s91, v153
	v_cndmask_b32_e64 v64, v64, v230, s[94:95]
	v_cndmask_b32_e64 v65, v65, v230, s[86:87]
	v_cndmask_b32_e64 v66, v66, v230, s[0:1]
	v_cndmask_b32_e64 v67, v67, v230, s[2:3]
	v_sub_u32_e32 v150, 0x80, v200
	v_sub_u32_e32 v151, 0x81, v200
	v_sub_u32_e32 v152, 0x82, v200
	v_sub_u32_e32 v153, 0x83, v200
	v_cmp_lt_u32_e64 s[94:95], s91, v150
	v_cmp_lt_u32_e64 s[86:87], s91, v151
	v_cmp_lt_u32_e64 s[0:1], s91, v152
	v_cmp_lt_u32_e64 s[2:3], s91, v153
	v_cndmask_b32_e64 v68, v68, v230, s[94:95]
	v_cndmask_b32_e64 v69, v69, v230, s[86:87]
	v_cndmask_b32_e64 v70, v70, v230, s[0:1]
	v_cndmask_b32_e64 v71, v71, v230, s[2:3]
	v_max3_f32 v186, v36, v37, v38
	v_max3_f32 v186, v186, v39, v40
	v_max3_f32 v186, v186, v41, v42
	v_max3_f32 v186, v186, v43, v44
	v_max3_f32 v186, v186, v45, v46
	v_max3_f32 v186, v186, v47, v48
	v_max3_f32 v186, v186, v49, v50
	s_waitcnt lgkmcnt(0)
	s_add_i32 s93, s8, 0xfffffd00
	s_mov_b32 m0, s16
	v_add_u32_e32 v164, s93, v231
	v_med3_i32 v164, v164, 0, s40
	v_lshl_or_b32 v164, v164, 7, v222
	global_load_lds_dwordx4 v164, s[24:25]
	s_add_i32 m0, s16, 0x400
	v_add_u32_e32 v165, s93, v232
	v_med3_i32 v165, v165, 0, s40
	v_lshl_or_b32 v165, v165, 7, v222
	global_load_lds_dwordx4 v165, s[24:25]
	s_waitcnt vmcnt(8)
	v_add_u32_e32 v154, s12, v225
	v_add_u32_e32 v155, s12, v226
	v_add_u32_e32 v156, s12, v227
	v_add_u32_e32 v157, s12, v228
	ds_read_b64_tr_b16 v[88:89], v154
	ds_read_b64_tr_b16 v[90:91], v155
	ds_read_b64_tr_b16 v[92:93], v156
	ds_read_b64_tr_b16 v[94:95], v157
	v_mfma_f32_16x16x16_bf16 v[96:99], v[202:203], v[20:21], v[96:99]
	v_mfma_f32_16x16x16_bf16 v[100:103], v[204:205], v[20:21], v[100:103]
	v_mfma_f32_16x16x16_bf16 v[104:107], v[206:207], v[20:21], v[104:107]
	v_mfma_f32_16x16x16_bf16 v[108:111], v[208:209], v[20:21], v[108:111]
	v_max3_f32 v186, v186, v51, v52
	v_max3_f32 v186, v186, v53, v54
	v_max3_f32 v186, v186, v55, v56
	v_max3_f32 v186, v186, v57, v58
	v_max3_f32 v186, v186, v59, v60
	v_max3_f32 v186, v186, v61, v62
	v_max3_f32 v186, v186, v63, v64
	v_max3_f32 v186, v186, v65, v66
	v_max3_f32 v186, v186, v67, v68
	v_max3_f32 v186, v186, v69, v70
	v_max_f32_e32 v186, v186, v71
	v_mov_b32_e32 v146, v186
	s_nop 1
	v_permlane16_swap_b32_e32 v186, v146
	v_max_f32_e32 v186, v186, v146
	v_mov_b32_e32 v146, v186
	s_nop 1
	v_permlane32_swap_b32_e32 v186, v146
	v_max_f32_e32 v186, v186, v146
	v_pk_add_f32 v[36:37], v[36:37], v[186:187] op_sel_hi:[1,0] neg_lo:[0,1] neg_hi:[0,1]
	v_pk_add_f32 v[38:39], v[38:39], v[186:187] op_sel_hi:[1,0] neg_lo:[0,1] neg_hi:[0,1]
	v_pk_add_f32 v[40:41], v[40:41], v[186:187] op_sel_hi:[1,0] neg_lo:[0,1] neg_hi:[0,1]
	v_pk_add_f32 v[42:43], v[42:43], v[186:187] op_sel_hi:[1,0] neg_lo:[0,1] neg_hi:[0,1]
	v_exp_f32_e32 v36, v36
	v_exp_f32_e32 v37, v37
	v_exp_f32_e32 v38, v38
	v_exp_f32_e32 v39, v39
	v_pk_add_f32 v[44:45], v[44:45], v[186:187] op_sel_hi:[1,0] neg_lo:[0,1] neg_hi:[0,1]
	v_pk_add_f32 v[46:47], v[46:47], v[186:187] op_sel_hi:[1,0] neg_lo:[0,1] neg_hi:[0,1]
	v_exp_f32_e32 v40, v40
	v_exp_f32_e32 v41, v41
	v_exp_f32_e32 v42, v42
	v_exp_f32_e32 v43, v43
	s_waitcnt lgkmcnt(0)
	s_add_i32 s93, s8, 0xfffffe00
	s_mov_b32 m0, s12
	v_add_u32_e32 v164, s93, v231
	v_med3_i32 v164, v164, 0, s40
	v_lshl_or_b32 v164, v164, 7, v222
	global_load_lds_dwordx4 v164, s[24:25]
	s_add_i32 m0, s12, 0x400
	v_add_u32_e32 v165, s93, v232
	v_med3_i32 v165, v165, 0, s40
	v_lshl_or_b32 v165, v165, 7, v222
	global_load_lds_dwordx4 v165, s[24:25]
	s_waitcnt vmcnt(8)
	v_add_u32_e32 v154, s13, v225
	v_add_u32_e32 v155, s13, v226
	v_add_u32_e32 v156, s13, v227
	v_add_u32_e32 v157, s13, v228
	ds_read_b64_tr_b16 v[202:203], v154
	ds_read_b64_tr_b16 v[204:205], v155
	ds_read_b64_tr_b16 v[206:207], v156
	ds_read_b64_tr_b16 v[208:209], v157
	v_mfma_f32_16x16x16_bf16 v[96:99], v[88:89], v[24:25], v[96:99]
	v_mfma_f32_16x16x16_bf16 v[100:103], v[90:91], v[24:25], v[100:103]
	v_mfma_f32_16x16x16_bf16 v[104:107], v[92:93], v[24:25], v[104:107]
	v_mfma_f32_16x16x16_bf16 v[108:111], v[94:95], v[24:25], v[108:111]
	v_pk_add_f32 v[48:49], v[48:49], v[186:187] op_sel_hi:[1,0] neg_lo:[0,1] neg_hi:[0,1]
	v_pk_add_f32 v[50:51], v[50:51], v[186:187] op_sel_hi:[1,0] neg_lo:[0,1] neg_hi:[0,1]
	v_exp_f32_e32 v44, v44
	v_exp_f32_e32 v45, v45
	v_exp_f32_e32 v46, v46
	v_exp_f32_e32 v47, v47
	v_pk_add_f32 v[52:53], v[52:53], v[186:187] op_sel_hi:[1,0] neg_lo:[0,1] neg_hi:[0,1]
	v_pk_add_f32 v[54:55], v[54:55], v[186:187] op_sel_hi:[1,0] neg_lo:[0,1] neg_hi:[0,1]
	v_exp_f32_e32 v48, v48
	v_exp_f32_e32 v49, v49
	v_exp_f32_e32 v50, v50
	v_exp_f32_e32 v51, v51
	v_pk_add_f32 v[56:57], v[56:57], v[186:187] op_sel_hi:[1,0] neg_lo:[0,1] neg_hi:[0,1]
	v_pk_add_f32 v[58:59], v[58:59], v[186:187] op_sel_hi:[1,0] neg_lo:[0,1] neg_hi:[0,1]
	v_exp_f32_e32 v52, v52
	v_exp_f32_e32 v53, v53
	v_exp_f32_e32 v54, v54
	v_exp_f32_e32 v55, v55
	v_pk_add_f32 v[60:61], v[60:61], v[186:187] op_sel_hi:[1,0] neg_lo:[0,1] neg_hi:[0,1]
	v_pk_add_f32 v[62:63], v[62:63], v[186:187] op_sel_hi:[1,0] neg_lo:[0,1] neg_hi:[0,1]
	v_exp_f32_e32 v56, v56
	v_exp_f32_e32 v57, v57
	v_exp_f32_e32 v58, v58
	v_exp_f32_e32 v59, v59
	v_pk_add_f32 v[64:65], v[64:65], v[186:187] op_sel_hi:[1,0] neg_lo:[0,1] neg_hi:[0,1]
	v_pk_add_f32 v[66:67], v[66:67], v[186:187] op_sel_hi:[1,0] neg_lo:[0,1] neg_hi:[0,1]
	v_exp_f32_e32 v60, v60
	v_exp_f32_e32 v61, v61
	v_exp_f32_e32 v62, v62
	v_exp_f32_e32 v63, v63
	v_pk_add_f32 v[68:69], v[68:69], v[186:187] op_sel_hi:[1,0] neg_lo:[0,1] neg_hi:[0,1]
	s_waitcnt lgkmcnt(0)
	s_add_i32 s93, s8, 0xffffff00
	s_mov_b32 m0, s13
	v_add_u32_e32 v164, s93, v231
	v_med3_i32 v164, v164, 0, s40
	v_lshl_or_b32 v164, v164, 7, v222
	global_load_lds_dwordx4 v164, s[24:25]
	s_add_i32 m0, s13, 0x400
	v_add_u32_e32 v165, s93, v232
	v_med3_i32 v165, v165, 0, s40
	v_lshl_or_b32 v165, v165, 7, v222
	global_load_lds_dwordx4 v165, s[24:25]
	s_waitcnt vmcnt(8)
	v_add_u32_e32 v154, s14, v225
	v_add_u32_e32 v155, s14, v226
	v_add_u32_e32 v156, s14, v227
	v_add_u32_e32 v157, s14, v228
	ds_read_b64_tr_b16 v[88:89], v154
	ds_read_b64_tr_b16 v[90:91], v155
	ds_read_b64_tr_b16 v[92:93], v156
	ds_read_b64_tr_b16 v[94:95], v157
	v_mfma_f32_16x16x16_bf16 v[96:99], v[202:203], v[28:29], v[96:99]
	v_mfma_f32_16x16x16_bf16 v[100:103], v[204:205], v[28:29], v[100:103]
	v_mfma_f32_16x16x16_bf16 v[104:107], v[206:207], v[28:29], v[104:107]
	v_mfma_f32_16x16x16_bf16 v[108:111], v[208:209], v[28:29], v[108:111]
	v_pk_add_f32 v[70:71], v[70:71], v[186:187] op_sel_hi:[1,0] neg_lo:[0,1] neg_hi:[0,1]
	v_exp_f32_e32 v64, v64
	v_exp_f32_e32 v65, v65
	v_exp_f32_e32 v66, v66
	v_exp_f32_e32 v67, v67
	v_exp_f32_e32 v68, v68
	v_exp_f32_e32 v69, v69
	v_exp_f32_e32 v70, v70
	v_exp_f32_e32 v71, v71
	s_nop 0
	v_pk_add_f32 v[146:147], v[36:37], v[38:39]
	v_pk_add_f32 v[148:149], v[40:41], v[42:43]
	v_pk_add_f32 v[146:147], v[146:147], v[44:45]
	v_pk_add_f32 v[148:149], v[148:149], v[46:47]
	v_pk_add_f32 v[146:147], v[146:147], v[48:49]
	v_pk_add_f32 v[148:149], v[148:149], v[50:51]
	v_pk_add_f32 v[146:147], v[146:147], v[52:53]
	v_pk_add_f32 v[148:149], v[148:149], v[54:55]
	v_pk_add_f32 v[146:147], v[146:147], v[56:57]
	v_pk_add_f32 v[148:149], v[148:149], v[58:59]
	v_pk_add_f32 v[146:147], v[146:147], v[60:61]
	v_pk_add_f32 v[148:149], v[148:149], v[62:63]
	v_pk_add_f32 v[146:147], v[146:147], v[64:65]
	v_pk_add_f32 v[148:149], v[148:149], v[66:67]
	v_pk_add_f32 v[146:147], v[146:147], v[68:69]
	v_pk_add_f32 v[148:149], v[148:149], v[70:71]
	s_nop 0
	v_pk_add_f32 v[146:147], v[146:147], v[148:149]
	s_nop 0
	v_add_f32_e32 v187, v146, v147
	v_cvt_pk_bf16_f32 v36, v36, v37
	s_waitcnt lgkmcnt(0)
	s_add_i32 s93, s8, 0
	s_mov_b32 m0, s14
	v_add_u32_e32 v164, s93, v231
	v_med3_i32 v164, v164, 0, s40
	v_lshl_or_b32 v164, v164, 7, v222
	global_load_lds_dwordx4 v164, s[24:25]
	s_add_i32 m0, s14, 0x400
	v_add_u32_e32 v165, s93, v232
	v_med3_i32 v165, v165, 0, s40
	v_lshl_or_b32 v165, v165, 7, v222
	global_load_lds_dwordx4 v165, s[24:25]
	s_waitcnt vmcnt(8)
	v_add_u32_e32 v72, s15, v225
	v_add_u32_e32 v73, s15, v226
	v_add_u32_e32 v74, s15, v227
	v_add_u32_e32 v75, s15, v228
	ds_read_b64_tr_b16 v[202:203], v72
	ds_read_b64_tr_b16 v[204:205], v73
	ds_read_b64_tr_b16 v[206:207], v74
	ds_read_b64_tr_b16 v[208:209], v75
	v_mfma_f32_16x16x16_bf16 v[96:99], v[88:89], v[32:33], v[96:99]
	v_mfma_f32_16x16x16_bf16 v[100:103], v[90:91], v[32:33], v[100:103]
	v_mfma_f32_16x16x16_bf16 v[104:107], v[92:93], v[32:33], v[104:107]
	v_mfma_f32_16x16x16_bf16 v[108:111], v[94:95], v[32:33], v[108:111]
	v_cvt_pk_bf16_f32 v37, v38, v39
	v_cvt_pk_bf16_f32 v40, v40, v41
	v_cvt_pk_bf16_f32 v41, v42, v43
	v_cvt_pk_bf16_f32 v44, v44, v45
	v_cvt_pk_bf16_f32 v45, v46, v47
	v_cvt_pk_bf16_f32 v48, v48, v49
	v_cvt_pk_bf16_f32 v49, v50, v51
	v_cvt_pk_bf16_f32 v52, v52, v53
	v_cvt_pk_bf16_f32 v53, v54, v55
	v_cvt_pk_bf16_f32 v56, v56, v57
	v_cvt_pk_bf16_f32 v57, v58, v59
	v_cvt_pk_bf16_f32 v60, v60, v61
	v_cvt_pk_bf16_f32 v61, v62, v63
	v_cvt_pk_bf16_f32 v64, v64, v65
	v_cvt_pk_bf16_f32 v65, v66, v67
	v_cvt_pk_bf16_f32 v68, v68, v69
	v_cvt_pk_bf16_f32 v69, v70, v71
	v_mov_b32_e32 v146, v187
	s_nop 1
	v_permlane16_swap_b32_e32 v187, v146
	v_add_f32_e32 v187, v187, v146
	v_mov_b32_e32 v146, v187
	s_nop 1
	v_permlane32_swap_b32_e32 v187, v146
	v_add_f32_e32 v187, v187, v146
	s_waitcnt lgkmcnt(0)
	s_add_i32 s93, s8, 0x100
	s_mov_b32 m0, s15
	v_add_u32_e32 v164, s93, v231
	v_med3_i32 v164, v164, 0, s40
	v_lshl_or_b32 v164, v164, 7, v222
	global_load_lds_dwordx4 v164, s[24:25]
	s_add_i32 m0, s15, 0x400
	v_add_u32_e32 v165, s93, v232
	v_med3_i32 v165, v165, 0, s40
	v_lshl_or_b32 v165, v165, 7, v222
	global_load_lds_dwordx4 v165, s[24:25]
	s_waitcnt vmcnt(8)
	v_add_u32_e32 v72, s16, v225
	v_add_u32_e32 v73, s16, v226
	v_add_u32_e32 v74, s16, v227
	v_add_u32_e32 v75, s16, v228
	ds_read_b64_tr_b16 v[88:89], v72
	ds_read_b64_tr_b16 v[90:91], v73
	ds_read_b64_tr_b16 v[92:93], v74
	ds_read_b64_tr_b16 v[94:95], v75
	v_mfma_f32_16x16x16_bf16 v[112:115], v[202:203], v[36:37], 0
	v_mfma_f32_16x16x16_bf16 v[116:119], v[204:205], v[36:37], 0
	v_mfma_f32_16x16x16_bf16 v[120:123], v[206:207], v[36:37], 0
	v_mfma_f32_16x16x16_bf16 v[124:127], v[208:209], v[36:37], 0
	s_waitcnt lgkmcnt(0)
	v_max_f32_e32 v146, v144, v184
	v_sub_f32_e32 v148, v144, v146
	v_sub_f32_e32 v150, v184, v146
	v_exp_f32_e32 v148, v148
	v_exp_f32_e32 v150, v150
	v_mov_b32_e32 v184, v146
	v_mul_f32_e32 v185, v185, v150
	v_fmac_f32_e32 v185, v145, v148
	v_pk_mul_f32 v[96:97], v[150:151], v[96:97] op_sel_hi:[0,1]
	v_pk_mul_f32 v[98:99], v[150:151], v[98:99] op_sel_hi:[0,1]
	v_pk_mul_f32 v[100:101], v[150:151], v[100:101] op_sel_hi:[0,1]
	s_waitcnt lgkmcnt(0)
	s_add_i32 s93, s8, 0x200
	s_mov_b32 m0, s16
	v_add_u32_e32 v164, s93, v231
	v_med3_i32 v164, v164, 0, s40
	v_lshl_or_b32 v164, v164, 7, v222
	global_load_lds_dwordx4 v164, s[24:25]
	s_add_i32 m0, s16, 0x400
	v_add_u32_e32 v165, s93, v232
	v_med3_i32 v165, v165, 0, s40
	v_lshl_or_b32 v165, v165, 7, v222
	global_load_lds_dwordx4 v165, s[24:25]
	s_waitcnt vmcnt(8)
	v_add_u32_e32 v72, s12, v225
	v_add_u32_e32 v73, s12, v226
	v_add_u32_e32 v74, s12, v227
	v_add_u32_e32 v75, s12, v228
	ds_read_b64_tr_b16 v[202:203], v72
	ds_read_b64_tr_b16 v[204:205], v73
	ds_read_b64_tr_b16 v[206:207], v74
	ds_read_b64_tr_b16 v[208:209], v75
	v_mfma_f32_16x16x16_bf16 v[112:115], v[88:89], v[40:41], v[112:115]
	v_mfma_f32_16x16x16_bf16 v[116:119], v[90:91], v[40:41], v[116:119]
	v_mfma_f32_16x16x16_bf16 v[120:123], v[92:93], v[40:41], v[120:123]
	v_mfma_f32_16x16x16_bf16 v[124:127], v[94:95], v[40:41], v[124:127]
	v_pk_mul_f32 v[102:103], v[150:151], v[102:103] op_sel_hi:[0,1]
	v_pk_mul_f32 v[104:105], v[150:151], v[104:105] op_sel_hi:[0,1]
	v_pk_mul_f32 v[106:107], v[150:151], v[106:107] op_sel_hi:[0,1]
	v_pk_mul_f32 v[108:109], v[150:151], v[108:109] op_sel_hi:[0,1]
	v_pk_mul_f32 v[110:111], v[150:151], v[110:111] op_sel_hi:[0,1]
	v_pk_fma_f32 v[96:97], v[148:149], v[128:129], v[96:97] op_sel_hi:[0,1,1]
	v_pk_fma_f32 v[98:99], v[148:149], v[130:131], v[98:99] op_sel_hi:[0,1,1]
	v_pk_fma_f32 v[100:101], v[148:149], v[132:133], v[100:101] op_sel_hi:[0,1,1]
	v_pk_fma_f32 v[102:103], v[148:149], v[134:135], v[102:103] op_sel_hi:[0,1,1]
	v_pk_fma_f32 v[104:105], v[148:149], v[136:137], v[104:105] op_sel_hi:[0,1,1]
	v_pk_fma_f32 v[106:107], v[148:149], v[138:139], v[106:107] op_sel_hi:[0,1,1]
	v_pk_fma_f32 v[108:109], v[148:149], v[140:141], v[108:109] op_sel_hi:[0,1,1]
	s_waitcnt lgkmcnt(0)
	s_add_i32 s93, s8, 0x300
	s_mov_b32 m0, s12
	v_add_u32_e32 v164, s93, v231
	v_med3_i32 v164, v164, 0, s40
	v_lshl_or_b32 v164, v164, 7, v222
	global_load_lds_dwordx4 v164, s[24:25]
	s_add_i32 m0, s12, 0x400
	v_add_u32_e32 v165, s93, v232
	v_med3_i32 v165, v165, 0, s40
	v_lshl_or_b32 v165, v165, 7, v222
	global_load_lds_dwordx4 v165, s[24:25]
	s_waitcnt vmcnt(8)
	v_add_u32_e32 v72, s13, v225
	v_add_u32_e32 v73, s13, v226
	v_add_u32_e32 v74, s13, v227
	v_add_u32_e32 v75, s13, v228
	ds_read_b64_tr_b16 v[88:89], v72
	ds_read_b64_tr_b16 v[90:91], v73
	ds_read_b64_tr_b16 v[92:93], v74
	ds_read_b64_tr_b16 v[94:95], v75
	v_mfma_f32_16x16x16_bf16 v[112:115], v[202:203], v[44:45], v[112:115]
	v_mfma_f32_16x16x16_bf16 v[116:119], v[204:205], v[44:45], v[116:119]
	v_mfma_f32_16x16x16_bf16 v[120:123], v[206:207], v[44:45], v[120:123]
	v_mfma_f32_16x16x16_bf16 v[124:127], v[208:209], v[44:45], v[124:127]
	v_pk_fma_f32 v[110:111], v[148:149], v[142:143], v[110:111] op_sel_hi:[0,1,1]
	v_div_scale_f32 v147, s[94:95], v185, v185, 1.0
	v_rcp_f32_e32 v148, v147
	v_div_scale_f32 v149, vcc, 1.0, v185, 1.0
	v_fma_f32 v150, -v147, v148, 1.0
	v_fmac_f32_e32 v148, v150, v148
	v_mul_f32_e32 v150, v149, v148
	v_fma_f32 v151, -v147, v150, v149
	v_fmac_f32_e32 v150, v151, v148
	v_fma_f32 v147, -v147, v150, v149
	s_nop 1
	v_div_fmas_f32 v147, v147, v148, v150
	s_waitcnt lgkmcnt(0)
	s_add_i32 s93, s8, 0x400
	s_mov_b32 m0, s13
	v_add_u32_e32 v164, s93, v231
	v_med3_i32 v164, v164, 0, s40
	v_lshl_or_b32 v164, v164, 7, v222
	global_load_lds_dwordx4 v164, s[24:25]
	s_add_i32 m0, s13, 0x400
	v_add_u32_e32 v165, s93, v232
	v_med3_i32 v165, v165, 0, s40
	v_lshl_or_b32 v165, v165, 7, v222
	global_load_lds_dwordx4 v165, s[24:25]
	s_waitcnt vmcnt(8)
	v_add_u32_e32 v72, s14, v225
	v_add_u32_e32 v73, s14, v226
	v_add_u32_e32 v74, s14, v227
	v_add_u32_e32 v75, s14, v228
	ds_read_b64_tr_b16 v[202:203], v72
	ds_read_b64_tr_b16 v[204:205], v73
	ds_read_b64_tr_b16 v[206:207], v74
	ds_read_b64_tr_b16 v[208:209], v75
	v_mfma_f32_16x16x16_bf16 v[112:115], v[88:89], v[48:49], v[112:115]
	v_mfma_f32_16x16x16_bf16 v[116:119], v[90:91], v[48:49], v[116:119]
	v_mfma_f32_16x16x16_bf16 v[120:123], v[92:93], v[48:49], v[120:123]
	v_mfma_f32_16x16x16_bf16 v[124:127], v[94:95], v[48:49], v[124:127]
	v_div_fixup_f32 v152, v147, v185, 1.0
	v_pk_mul_f32 v[96:97], v[152:153], v[96:97] op_sel_hi:[0,1]
	v_pk_mul_f32 v[98:99], v[152:153], v[98:99] op_sel_hi:[0,1]
	v_pk_mul_f32 v[100:101], v[152:153], v[100:101] op_sel_hi:[0,1]
	v_pk_mul_f32 v[102:103], v[152:153], v[102:103] op_sel_hi:[0,1]
	v_pk_mul_f32 v[104:105], v[152:153], v[104:105] op_sel_hi:[0,1]
	v_pk_mul_f32 v[106:107], v[152:153], v[106:107] op_sel_hi:[0,1]
	v_pk_mul_f32 v[108:109], v[152:153], v[108:109] op_sel_hi:[0,1]
	v_pk_mul_f32 v[110:111], v[152:153], v[110:111] op_sel_hi:[0,1]
	v_mul_f32_e32 v155, v97, v97
	v_mul_f32_e32 v156, v99, v99
	v_fmac_f32_e32 v155, v96, v96
	s_waitcnt lgkmcnt(0)
	s_add_i32 s93, s79, 0
	s_mov_b32 m0, s14
	v_add_u32_e32 v164, s93, v162
	v_lshl_or_b32 v164, v164, 7, v220
	global_load_lds_dwordx4 v164, s[30:31]
	s_add_i32 m0, s14, 0x400
	v_add_u32_e32 v165, s93, v163
	v_lshl_or_b32 v165, v165, 7, v221
	global_load_lds_dwordx4 v165, s[30:31]
	s_waitcnt vmcnt(8)
	v_add_u32_e32 v72, s15, v225
	v_add_u32_e32 v73, s15, v226
	v_add_u32_e32 v74, s15, v227
	v_add_u32_e32 v75, s15, v228
	ds_read_b64_tr_b16 v[88:89], v72
	ds_read_b64_tr_b16 v[90:91], v73
	ds_read_b64_tr_b16 v[92:93], v74
	ds_read_b64_tr_b16 v[94:95], v75
	v_mfma_f32_16x16x16_bf16 v[112:115], v[202:203], v[52:53], v[112:115]
	v_mfma_f32_16x16x16_bf16 v[116:119], v[204:205], v[52:53], v[116:119]
	v_mfma_f32_16x16x16_bf16 v[120:123], v[206:207], v[52:53], v[120:123]
	v_mfma_f32_16x16x16_bf16 v[124:127], v[208:209], v[52:53], v[124:127]
	v_fmac_f32_e32 v156, v98, v98
	v_add_f32_e32 v154, v155, v156
	v_mul_f32_e32 v155, v101, v101
	v_mul_f32_e32 v156, v103, v103
	v_fmac_f32_e32 v155, v100, v100
	v_fmac_f32_e32 v156, v102, v102
	v_add_f32_e32 v155, v155, v156
	v_add_f32_e32 v154, v154, v155
	v_mul_f32_e32 v155, v105, v105
	v_mul_f32_e32 v156, v107, v107
	v_fmac_f32_e32 v155, v104, v104
	v_fmac_f32_e32 v156, v106, v106
	s_waitcnt lgkmcnt(0)
	s_add_i32 s93, s79, 16
	s_mov_b32 m0, s15
	v_add_u32_e32 v164, s93, v162
	v_lshl_or_b32 v164, v164, 7, v220
	global_load_lds_dwordx4 v164, s[30:31]
	s_add_i32 m0, s15, 0x400
	v_add_u32_e32 v165, s93, v163
	v_lshl_or_b32 v165, v165, 7, v221
	global_load_lds_dwordx4 v165, s[30:31]
	s_waitcnt vmcnt(8)
	v_add_u32_e32 v72, s16, v225
	v_add_u32_e32 v73, s16, v226
	v_add_u32_e32 v74, s16, v227
	v_add_u32_e32 v75, s16, v228
	ds_read_b64_tr_b16 v[202:203], v72
	ds_read_b64_tr_b16 v[204:205], v73
	ds_read_b64_tr_b16 v[206:207], v74
	ds_read_b64_tr_b16 v[208:209], v75
	v_mfma_f32_16x16x16_bf16 v[112:115], v[88:89], v[56:57], v[112:115]
	v_mfma_f32_16x16x16_bf16 v[116:119], v[90:91], v[56:57], v[116:119]
	v_mfma_f32_16x16x16_bf16 v[120:123], v[92:93], v[56:57], v[120:123]
	v_mfma_f32_16x16x16_bf16 v[124:127], v[94:95], v[56:57], v[124:127]
	v_add_f32_e32 v155, v155, v156
	v_add_f32_e32 v154, v154, v155
	v_mul_f32_e32 v155, v109, v109
	v_mul_f32_e32 v156, v111, v111
	v_fmac_f32_e32 v155, v108, v108
	v_fmac_f32_e32 v156, v110, v110
	v_add_f32_e32 v155, v155, v156
	v_add_f32_e32 v154, v154, v155
	v_cvt_pk_bf16_f32 v96, v96, v97
	v_cvt_pk_bf16_f32 v97, v98, v99
	v_cvt_pk_bf16_f32 v100, v100, v101
	v_cvt_pk_bf16_f32 v101, v102, v103
	s_waitcnt lgkmcnt(0)
	s_add_i32 s93, s79, 0xffffffc0
	s_mov_b32 m0, s16
	v_add_u32_e32 v164, s93, v162
	v_med3_i32 v164, v164, 0, s41
	v_lshl_or_b32 v164, v164, 7, v220
	global_load_lds_dwordx4 v164, s[34:35]
	s_add_i32 m0, s16, 0x400
	v_add_u32_e32 v165, s93, v163
	v_med3_i32 v165, v165, 0, s41
	v_lshl_or_b32 v165, v165, 7, v221
	global_load_lds_dwordx4 v165, s[34:35]
	s_waitcnt vmcnt(8)
	v_add_u32_e32 v72, s12, v225
	v_add_u32_e32 v73, s12, v226
	v_add_u32_e32 v74, s12, v227
	v_add_u32_e32 v75, s12, v228
	ds_read_b64_tr_b16 v[88:89], v72
	ds_read_b64_tr_b16 v[90:91], v73
	ds_read_b64_tr_b16 v[92:93], v74
	ds_read_b64_tr_b16 v[94:95], v75
	v_mfma_f32_16x16x16_bf16 v[112:115], v[202:203], v[60:61], v[112:115]
	v_mfma_f32_16x16x16_bf16 v[116:119], v[204:205], v[60:61], v[116:119]
	v_mfma_f32_16x16x16_bf16 v[120:123], v[206:207], v[60:61], v[120:123]
	v_mfma_f32_16x16x16_bf16 v[124:127], v[208:209], v[60:61], v[124:127]
	v_cvt_pk_bf16_f32 v104, v104, v105
	v_cvt_pk_bf16_f32 v105, v106, v107
	v_cvt_pk_bf16_f32 v108, v108, v109
	v_cvt_pk_bf16_f32 v109, v110, v111
	v_add_u32_e32 v157, s42, v188
	s_lshl_b32 s90, s43, 7
	v_lshlrev_b32_e32 v158, 11, v157
	v_add3_u32 v158, v158, s90, v233
	v_mov_b32_e32 v76, v96
	v_mov_b32_e32 v77, v97
	v_mov_b32_e32 v78, v100
	v_mov_b32_e32 v79, v101
	s_waitcnt lgkmcnt(0)
	s_add_i32 s93, s79, 0xffffffd0
	s_mov_b32 m0, s12
	v_add_u32_e32 v164, s93, v162
	v_med3_i32 v164, v164, 0, s41
	v_lshl_or_b32 v164, v164, 7, v220
	global_load_lds_dwordx4 v164, s[34:35]
	s_add_i32 m0, s12, 0x400
	v_add_u32_e32 v165, s93, v163
	v_med3_i32 v165, v165, 0, s41
	v_lshl_or_b32 v165, v165, 7, v221
	global_load_lds_dwordx4 v165, s[34:35]
	s_waitcnt vmcnt(8)
	v_add_u32_e32 v72, s13, v225
	v_add_u32_e32 v73, s13, v226
	v_add_u32_e32 v74, s13, v227
	v_add_u32_e32 v75, s13, v228
	ds_read_b64_tr_b16 v[202:203], v72
	ds_read_b64_tr_b16 v[204:205], v73
	ds_read_b64_tr_b16 v[206:207], v74
	ds_read_b64_tr_b16 v[208:209], v75
	v_mfma_f32_16x16x16_bf16 v[112:115], v[88:89], v[64:65], v[112:115]
	v_mfma_f32_16x16x16_bf16 v[116:119], v[90:91], v[64:65], v[116:119]
	v_mfma_f32_16x16x16_bf16 v[120:123], v[92:93], v[64:65], v[120:123]
	v_mfma_f32_16x16x16_bf16 v[124:127], v[94:95], v[64:65], v[124:127]
	s_nop 1
	v_permlane16_swap_b32_e32 v76, v78
	v_permlane16_swap_b32_e32 v77, v79
	v_mov_b32_e32 v80, v104
	v_mov_b32_e32 v81, v105
	v_mov_b32_e32 v82, v108
	v_mov_b32_e32 v83, v109
	s_nop 1
	v_permlane16_swap_b32_e32 v80, v82
	v_permlane16_swap_b32_e32 v81, v83
	v_mov_b32_e32 v155, v154
	s_nop 1
	v_permlane16_swap_b32_e32 v154, v155
	s_waitcnt lgkmcnt(0)
	s_add_i32 s93, s79, 0xffffffe0
	s_mov_b32 m0, s13
	v_add_u32_e32 v164, s93, v162
	v_med3_i32 v164, v164, 0, s41
	v_lshl_or_b32 v164, v164, 7, v220
	global_load_lds_dwordx4 v164, s[34:35]
	s_add_i32 m0, s13, 0x400
	v_add_u32_e32 v165, s93, v163
	v_med3_i32 v165, v165, 0, s41
	v_lshl_or_b32 v165, v165, 7, v221
	global_load_lds_dwordx4 v165, s[34:35]
	v_mfma_f32_16x16x16_bf16 v[112:115], v[202:203], v[68:69], v[112:115]
	v_mfma_f32_16x16x16_bf16 v[116:119], v[204:205], v[68:69], v[116:119]
	v_mfma_f32_16x16x16_bf16 v[120:123], v[206:207], v[68:69], v[120:123]
	v_mfma_f32_16x16x16_bf16 v[124:127], v[208:209], v[68:69], v[124:127]
	v_add_f32_e32 v154, v154, v155
	v_mov_b32_e32 v155, v154
	s_nop 1
	v_permlane32_swap_b32_e32 v154, v155
	v_add_f32_e32 v154, v154, v155
	v_mul_u32_u24_e32 v157, 48, v157
	s_lshl_b32 s90, s43, 2
	v_add_u32_e32 v157, s90, v157
	s_nop 1
	global_store_dwordx4 v158, v[76:79], s[48:49] offset:0
	global_store_dwordx4 v158, v[80:83], s[48:49] offset:64
	s_and_saveexec_b64 s[80:81], s[74:75]
	global_store_dword v157, v154, s[50:51]
	s_mov_b64 exec, s[80:81]
	s_waitcnt lgkmcnt(0)
	v_max_f32_e32 v146, v182, v186
	v_sub_f32_e32 v148, v182, v146
	v_sub_f32_e32 v150, v186, v146
	v_exp_f32_e32 v148, v148
	v_exp_f32_e32 v150, v150
	v_mov_b32_e32 v186, v146
	v_mul_f32_e32 v187, v187, v150
	v_fmac_f32_e32 v187, v183, v148
	v_pk_mul_f32 v[112:113], v[150:151], v[112:113] op_sel_hi:[0,1]
	v_pk_mul_f32 v[114:115], v[150:151], v[114:115] op_sel_hi:[0,1]
	v_pk_mul_f32 v[116:117], v[150:151], v[116:117] op_sel_hi:[0,1]
	v_pk_mul_f32 v[118:119], v[150:151], v[118:119] op_sel_hi:[0,1]
	v_pk_mul_f32 v[120:121], v[150:151], v[120:121] op_sel_hi:[0,1]
	v_pk_mul_f32 v[122:123], v[150:151], v[122:123] op_sel_hi:[0,1]
	v_pk_mul_f32 v[124:125], v[150:151], v[124:125] op_sel_hi:[0,1]
	v_pk_mul_f32 v[126:127], v[150:151], v[126:127] op_sel_hi:[0,1]
	v_pk_fma_f32 v[112:113], v[148:149], v[166:167], v[112:113] op_sel_hi:[0,1,1]
	v_pk_fma_f32 v[114:115], v[148:149], v[168:169], v[114:115] op_sel_hi:[0,1,1]
	v_pk_fma_f32 v[116:117], v[148:149], v[170:171], v[116:117] op_sel_hi:[0,1,1]
	v_pk_fma_f32 v[118:119], v[148:149], v[172:173], v[118:119] op_sel_hi:[0,1,1]
	v_pk_fma_f32 v[120:121], v[148:149], v[174:175], v[120:121] op_sel_hi:[0,1,1]
	v_pk_fma_f32 v[122:123], v[148:149], v[176:177], v[122:123] op_sel_hi:[0,1,1]
	v_pk_fma_f32 v[124:125], v[148:149], v[178:179], v[124:125] op_sel_hi:[0,1,1]
	v_pk_fma_f32 v[126:127], v[148:149], v[180:181], v[126:127] op_sel_hi:[0,1,1]
	v_div_scale_f32 v147, s[94:95], v187, v187, 1.0
	v_rcp_f32_e32 v148, v147
	v_div_scale_f32 v149, vcc, 1.0, v187, 1.0
	v_fma_f32 v150, -v147, v148, 1.0
	v_fmac_f32_e32 v148, v150, v148
	v_mul_f32_e32 v150, v149, v148
	v_fma_f32 v151, -v147, v150, v149
	v_fmac_f32_e32 v150, v151, v148
	v_fma_f32 v147, -v147, v150, v149
	s_nop 1
	v_div_fmas_f32 v147, v147, v148, v150
	v_div_fixup_f32 v152, v147, v187, 1.0
	v_pk_mul_f32 v[112:113], v[152:153], v[112:113] op_sel_hi:[0,1]
	v_pk_mul_f32 v[114:115], v[152:153], v[114:115] op_sel_hi:[0,1]
	v_pk_mul_f32 v[116:117], v[152:153], v[116:117] op_sel_hi:[0,1]
	v_pk_mul_f32 v[118:119], v[152:153], v[118:119] op_sel_hi:[0,1]
	v_pk_mul_f32 v[120:121], v[152:153], v[120:121] op_sel_hi:[0,1]
	v_pk_mul_f32 v[122:123], v[152:153], v[122:123] op_sel_hi:[0,1]
	v_pk_mul_f32 v[124:125], v[152:153], v[124:125] op_sel_hi:[0,1]
	v_pk_mul_f32 v[126:127], v[152:153], v[126:127] op_sel_hi:[0,1]
	v_mul_f32_e32 v155, v113, v113
	v_mul_f32_e32 v156, v115, v115
	v_fmac_f32_e32 v155, v112, v112
	v_fmac_f32_e32 v156, v114, v114
	v_add_f32_e32 v154, v155, v156
	v_mul_f32_e32 v155, v117, v117
	v_mul_f32_e32 v156, v119, v119
	v_fmac_f32_e32 v155, v116, v116
	v_fmac_f32_e32 v156, v118, v118
	v_add_f32_e32 v155, v155, v156
	v_add_f32_e32 v154, v154, v155
	v_mul_f32_e32 v155, v121, v121
	v_mul_f32_e32 v156, v123, v123
	v_fmac_f32_e32 v155, v120, v120
	v_fmac_f32_e32 v156, v122, v122
	v_add_f32_e32 v155, v155, v156
	v_add_f32_e32 v154, v154, v155
	v_mul_f32_e32 v155, v125, v125
	v_mul_f32_e32 v156, v127, v127
	v_fmac_f32_e32 v155, v124, v124
	v_fmac_f32_e32 v156, v126, v126
	v_add_f32_e32 v155, v155, v156
	v_add_f32_e32 v154, v154, v155
	v_cvt_pk_bf16_f32 v112, v112, v113
	v_cvt_pk_bf16_f32 v113, v114, v115
	v_cvt_pk_bf16_f32 v116, v116, v117
	v_cvt_pk_bf16_f32 v117, v118, v119
	v_cvt_pk_bf16_f32 v120, v120, v121
	v_cvt_pk_bf16_f32 v121, v122, v123
	v_cvt_pk_bf16_f32 v124, v124, v125
	v_cvt_pk_bf16_f32 v125, v126, v127
	v_add_u32_e32 v157, s42, v189
	s_lshl_b32 s90, s43, 7
	v_lshlrev_b32_e32 v158, 11, v157
	v_add3_u32 v158, v158, s90, v233
	v_mov_b32_e32 v160, v112
	v_mov_b32_e32 v161, v113
	v_mov_b32_e32 v162, v116
	v_mov_b32_e32 v163, v117
	s_nop 1
	v_permlane16_swap_b32_e32 v160, v162
	v_permlane16_swap_b32_e32 v161, v163
	s_nop 1
	global_store_dwordx4 v158, v[160:163], s[48:49] offset:0
	s_nop 1
	v_mov_b32_e32 v160, v120
	v_mov_b32_e32 v161, v121
	v_mov_b32_e32 v162, v124
	v_mov_b32_e32 v163, v125
	s_nop 1
	v_permlane16_swap_b32_e32 v160, v162
	v_permlane16_swap_b32_e32 v161, v163
	s_nop 1
	global_store_dwordx4 v158, v[160:163], s[48:49] offset:64
	s_nop 1
	v_mov_b32_e32 v155, v154
	s_nop 1
	v_permlane16_swap_b32_e32 v154, v155
	v_add_f32_e32 v154, v154, v155
	v_mov_b32_e32 v155, v154
	s_nop 1
	v_permlane32_swap_b32_e32 v154, v155
	v_add_f32_e32 v154, v154, v155
	v_mul_u32_u24_e32 v157, 48, v157
	s_lshl_b32 s90, s43, 2
	v_add_u32_e32 v157, s90, v157
	s_and_saveexec_b64 s[80:81], s[74:75]
	global_store_dword v157, v154, s[50:51]
	s_mov_b64 exec, s[80:81]
	s_waitcnt lgkmcnt(0)
	s_barrier
	s_mov_b32 s90, s14
	s_mov_b32 s91, s15
	s_mov_b32 s92, s16
	s_mov_b32 s93, s12
	s_mov_b32 s97, s13
	s_mov_b32 s12, s90
	s_mov_b32 s13, s91
	s_mov_b32 s14, s92
	s_mov_b32 s15, s93
	s_mov_b32 s16, s97
	s_mov_b64 s[18:19], s[30:31]
	s_mov_b64 s[20:21], s[34:35]
	s_mov_b64 s[24:25], s[36:37]
	s_mov_b32 s38, s39
	s_mov_b32 s40, s41
	s_mov_b32 s42, s44
	s_mov_b32 s43, s45
	s_add_i32 s11, s11, s66
	s_cmpk_lt_u32 s11, 0x900
	s_cbranch_scc1 .Latt_unit
	v_readlane_b32 s0, v244, 20
	s_bfe_u32 s3, s0, 0x20006
